# SSD output unit (s3_unit) rewritten by hand: batched staging loads, z tile in LDS, 2-slot B-row prefetch, 5-slot state-fragment ring, identical arithmetic order
# speedup vs baseline: 1.0420x; 1.0298x over previous
.LBB0_104:
	s_or_b64 exec, exec, s[0:1]
	s_branch .LBB0_107
.LBB0_106:
	s_andn2_b64 vcc, exec, s[64:65]
	s_cbranch_vccz .LBB0_192

.LBB0_118:
	v_readfirstlane_b32 s56, v203
	v_readlane_b32 s40, v251, 43
	v_readlane_b32 s41, v251, 44
	v_readlane_b32 s42, v251, 49
	v_readlane_b32 s43, v251, 50
	v_readlane_b32 s46, v251, 59
	v_readlane_b32 s47, v251, 60
	v_readlane_b32 s54, v251, 45
	v_readlane_b32 s55, v251, 46
	v_readlane_b32 s58, v251, 47
	v_readlane_b32 s59, v251, 48
	v_readlane_b32 s48, v254, 44
	v_readlane_b32 s49, v254, 45
	v_readlane_b32 s50, v254, 46
	v_readlane_b32 s51, v254, 47
	s_lshr_b32 s56, s56, 6
	s_mul_i32 s0, s24, 0x600
	s_add_u32 s40, s40, s0
	s_addc_u32 s41, s41, 0
	s_mul_i32 s0, s2, 34
	s_add_i32 s0, s0, s3
	s_lshl_b32 s0, s0, 17
	s_add_u32 s42, s42, s0
	s_addc_u32 s43, s43, 0
	s_mul_i32 s0, s24, 0x1c00
	s_add_u32 s44, s70, s0
	s_addc_u32 s45, s71, 0
	s_add_u32 s44, s44, 0x1a00
	s_addc_u32 s45, s45, 0
	s_lshl_b32 s0, s24, 11
	s_add_u32 s46, s46, s0
	s_addc_u32 s47, s47, 0
	s_add_u32 s46, s46, 0x600
	s_addc_u32 s47, s47, 0
	s_lshl_b32 s0, s24, 5
	s_add_u32 s54, s54, s0
	s_addc_u32 s55, s55, 0
	s_add_u32 s58, s58, s0
	s_addc_u32 s59, s59, 0
	s_load_dword s60, s[48:49], 0x0
	s_load_dword s61, s[48:49], 0x4
	s_load_dword s62, s[48:49], 0x8
	s_load_dword s63, s[48:49], 0xc
	s_mov_b32 s25, 0x3b800000
	v_lshrrev_b32_e32 v0, 5, v203
	v_and_b32_e32 v1, 31, v203
	v_lshlrev_b32_e32 v1, 4, v1
	v_mul_u32_u24_e32 v2, 0x600, v0
	v_add_u32_e32 v2, v2, v1
	v_mul_u32_u24_e32 v3, 0x220, v0
	v_add_u32_e32 v3, v3, v1
	v_mul_u32_u24_e32 v4, 0x1c00, v0
	v_add_u32_e32 v4, v4, v1
	v_add_u32_e32 v5, 0x13000, v3
	v_lshlrev_b32_e32 v6, 2, v203
	v_and_b32_e32 v7, 7, v203
	v_lshlrev_b32_e32 v7, 9, v7
	v_lshrrev_b32_e32 v8, 3, v203
	v_lshl_add_u32 v7, v8, 2, v7
	v_add_u32_e32 v7, 0x11000, v7
	s_mov_b32 s52, s40
	s_mov_b32 s53, s41
	global_load_dwordx4 v[104:107], v2, s[52:53]
	s_add_u32 s52, s40, 0x6000
	s_addc_u32 s53, s41, 0
	global_load_dwordx4 v[108:111], v2, s[52:53]
	s_add_u32 s52, s40, 0xc000
	s_addc_u32 s53, s41, 0
	global_load_dwordx4 v[112:115], v2, s[52:53]
	s_add_u32 s52, s40, 0x12000
	s_addc_u32 s53, s41, 0
	global_load_dwordx4 v[116:119], v2, s[52:53]
	s_add_u32 s52, s40, 0x18000
	s_addc_u32 s53, s41, 0
	global_load_dwordx4 v[120:123], v2, s[52:53]
	s_add_u32 s52, s40, 0x1e000
	s_addc_u32 s53, s41, 0
	global_load_dwordx4 v[124:127], v2, s[52:53]
	s_add_u32 s52, s40, 0x24000
	s_addc_u32 s53, s41, 0
	global_load_dwordx4 v[128:131], v2, s[52:53]
	s_add_u32 s52, s40, 0x2a000
	s_addc_u32 s53, s41, 0
	global_load_dwordx4 v[132:135], v2, s[52:53]
	s_mov_b32 s52, s44
	s_mov_b32 s53, s45
	global_load_dwordx4 v[16:19], v4, s[52:53]
	s_add_u32 s52, s44, 0x1c000
	s_addc_u32 s53, s45, 0
	global_load_dwordx4 v[20:23], v4, s[52:53]
	s_add_u32 s52, s44, 0x38000
	s_addc_u32 s53, s45, 0
	global_load_dwordx4 v[24:27], v4, s[52:53]
	s_add_u32 s52, s44, 0x54000
	s_addc_u32 s53, s45, 0
	global_load_dwordx4 v[28:31], v4, s[52:53]
	s_add_u32 s52, s44, 0x70000
	s_addc_u32 s53, s45, 0
	global_load_dwordx4 v[32:35], v4, s[52:53]
	s_add_u32 s52, s44, 0x8c000
	s_addc_u32 s53, s45, 0
	global_load_dwordx4 v[36:39], v4, s[52:53]
	s_add_u32 s52, s44, 0xa8000
	s_addc_u32 s53, s45, 0
	global_load_dwordx4 v[40:43], v4, s[52:53]
	s_add_u32 s52, s44, 0xc4000
	s_addc_u32 s53, s45, 0
	global_load_dwordx4 v[44:47], v4, s[52:53]
	global_load_dword v236, v6, s[54:55]
	global_load_dword v237, v6, s[54:55] offset:2048
	global_load_dword v238, v6, s[58:59]
	global_load_dword v239, v6, s[58:59] offset:2048
	v_and_b32_e32 v10, 15, v220
	v_lshrrev_b32_e32 v11, 4, v220
	v_lshlrev_b32_e32 v165, 4, v11
	v_lshrrev_b32_e32 v12, 2, v10
	v_lshl_add_u32 v12, v11, 2, v12
	v_mul_u32_u24_e32 v166, 0x220, v12
	v_and_b32_e32 v13, 3, v10
	v_lshl_add_u32 v166, v13, 3, v166
	s_lshl_b32 s0, s56, 4
	v_add_u32_e32 v14, s0, v10
	v_lshl_add_u32 v167, v14, 2, 0
	v_add_u32_e32 v167, 0x11000, v167
	v_add_u32_e32 v168, 0x11000, v165
	v_mul_u32_u24_e32 v169, 0x600, v10
	v_add_u32_e32 v169, v169, v165
	v_add_u32_e32 v169, 0x200, v169
	v_lshlrev_b32_e32 v170, 8, v10
	v_add_u32_e32 v170, v170, v165
	v_add_u32_e32 v171, 0x1000, v170
	v_add_u32_e32 v172, 0x2000, v170
	v_add_u32_e32 v173, 0x3000, v170
	s_mul_i32 s1, s56, 0x2200
	v_add_u32_e32 v174, s1, v166
	v_lshlrev_b32_e32 v15, 2, v11
	v_sub_u32_e32 v175, v14, v15
	v_mul_u32_u24_e32 v177, 0x600, v14
	v_add_u32_e32 v177, v177, v165
	v_add_u32_e32 v177, 0x400, v177
	v_add_u32_e32 v227, 0x13000, v174
	v_add_u32_e32 v15, s0, v15
	v_lshlrev_b32_e32 v232, 11, v15
	v_lshl_add_u32 v232, v10, 1, v232
	v_add_u32_e32 v233, 0x1000, v232
	v_lshlrev_b32_e32 v234, 2, v10
	v_mov_b32_e32 v228, 0
	v_mov_b32_e32 v229, 0
	v_mov_b32_e32 v230, 0
	v_mov_b32_e32 v231, 0
	global_load_dwordx4 v[48:51], v177, s[40:41] offset:0
	global_load_dwordx4 v[52:55], v177, s[40:41] offset:64
	global_load_dwordx4 v[56:59], v177, s[40:41] offset:128
	global_load_dwordx4 v[60:63], v177, s[40:41] offset:192
	s_mov_b32 s52, s40
	s_mov_b32 s53, s41
	global_load_dwordx4 v[64:67], v169, s[52:53] offset:0
	global_load_dwordx4 v[68:71], v169, s[52:53] offset:64
	global_load_dwordx4 v[72:75], v169, s[52:53] offset:128
	global_load_dwordx4 v[76:79], v169, s[52:53] offset:192
	s_add_u32 s52, s40, 0x6000
	s_addc_u32 s53, s41, 0
	global_load_dwordx4 v[80:83], v169, s[52:53] offset:0
	global_load_dwordx4 v[84:87], v169, s[52:53] offset:64
	global_load_dwordx4 v[88:91], v169, s[52:53] offset:128
	global_load_dwordx4 v[92:95], v169, s[52:53] offset:192
	s_waitcnt vmcnt(12)
	ds_write_b128 v3, v[104:107]
	ds_write_b128 v3, v[108:111] offset:8704
	ds_write_b128 v3, v[112:115] offset:17408
	ds_write_b128 v3, v[116:119] offset:26112
	ds_write_b128 v3, v[120:123] offset:34816
	ds_write_b128 v3, v[124:127] offset:43520
	ds_write_b128 v3, v[128:131] offset:52224
	ds_write_b128 v3, v[132:135] offset:60928
	ds_write_b128 v5, v[16:19]
	ds_write_b128 v5, v[20:23] offset:8704
	ds_write_b128 v5, v[24:27] offset:17408
	ds_write_b128 v5, v[28:31] offset:26112
	ds_write_b128 v5, v[32:35] offset:34816
	ds_write_b128 v5, v[36:39] offset:43520
	ds_write_b128 v5, v[40:43] offset:52224
	ds_write_b128 v5, v[44:47] offset:60928
	ds_write_b32 v7, v236
	ds_write_b32 v7, v237 offset:256
	ds_write_b32 v7, v238 offset:4096
	ds_write_b32 v7, v239 offset:4352
	s_waitcnt lgkmcnt(0)
	s_barrier
	ds_read_b32 v156, v167 offset:4096
	ds_read_b32 v157, v167 offset:6144
	ds_read_b32 v158, v167 offset:4608
	ds_read_b32 v159, v167 offset:6656
	s_waitcnt vmcnt(0)
	v_mfma_f32_16x16x32_bf16 v[96:99], v[64:67], v[48:51], 0
	v_mfma_f32_16x16x32_bf16 v[96:99], v[68:71], v[52:55], v[96:99]
	v_mfma_f32_16x16x32_bf16 v[96:99], v[72:75], v[56:59], v[96:99]
	v_mfma_f32_16x16x32_bf16 v[96:99], v[76:79], v[60:63], v[96:99]
	v_mfma_f32_16x16x32_bf16 v[100:103], v[80:83], v[48:51], 0
	v_mfma_f32_16x16x32_bf16 v[100:103], v[84:87], v[52:55], v[100:103]
	v_mfma_f32_16x16x32_bf16 v[100:103], v[88:91], v[56:59], v[100:103]
	v_mfma_f32_16x16x32_bf16 v[100:103], v[92:95], v[60:63], v[100:103]
	s_add_u32 s52, s40, 0xc000
	s_addc_u32 s53, s41, 0
	global_load_dwordx4 v[64:67], v169, s[52:53] offset:0
	global_load_dwordx4 v[68:71], v169, s[52:53] offset:64
	global_load_dwordx4 v[72:75], v169, s[52:53] offset:128
	global_load_dwordx4 v[76:79], v169, s[52:53] offset:192
	s_add_u32 s52, s40, 0x12000
	s_addc_u32 s53, s41, 0
	global_load_dwordx4 v[80:83], v169, s[52:53] offset:0
	global_load_dwordx4 v[84:87], v169, s[52:53] offset:64
	global_load_dwordx4 v[88:91], v169, s[52:53] offset:128
	global_load_dwordx4 v[92:95], v169, s[52:53] offset:192
	ds_read_b128 v[104:107], v168 offset:0
	ds_read_b128 v[108:111], v168 offset:2048
	ds_read_b128 v[112:115], v168 offset:4096
	ds_read_b128 v[116:119], v168 offset:6144
	ds_read_b128 v[120:123], v168 offset:64
	ds_read_b128 v[124:127], v168 offset:2112
	ds_read_b128 v[128:131], v168 offset:4160
	ds_read_b128 v[132:135], v168 offset:6208
	ds_read_b64_tr_b16 v[140:141], v166 offset:0
	ds_read_b64_tr_b16 v[142:143], v166 offset:8704
	ds_read_b64_tr_b16 v[144:145], v166 offset:32
	ds_read_b64_tr_b16 v[146:147], v166 offset:8736
	s_waitcnt lgkmcnt(4)
	v_subrev_u32_e32 v236, 0, v175
	v_cmp_gt_i32_e64 s[78:79], v236, 0
	v_cmp_gt_i32_e64 s[80:81], v236, 1
	v_cmp_gt_i32_e64 s[82:83], v236, 2
	v_cmp_gt_i32_e64 s[84:85], v236, 3
	v_cmp_eq_u32_e64 s[86:87], v236, 0
	v_cmp_eq_u32_e64 s[88:89], v236, 1
	v_cmp_eq_u32_e64 s[90:91], v236, 2
	v_cmp_eq_u32_e64 s[92:93], v236, 3
	v_cndmask_b32_e64 v237, v116, v112, s[78:79]
	v_cndmask_b32_e64 v238, v157, v156, s[78:79]
	v_sub_f32_e32 v237, v238, v237
	v_min_f32_e32 v237, 0, v237
	v_mul_f32_e32 v237, 0x3fb8aa3b, v237
	v_exp_f32_e32 v237, v237
	v_cndmask_b32_e64 v239, v108, v104, s[78:79]
	v_add_f32_e32 v240, v104, v108
	v_mul_f32_e32 v237, v239, v237
	v_cndmask_b32_e64 v237, v237, v240, s[86:87]
	v_mul_f32_e32 v241, v96, v237
	v_cndmask_b32_e64 v237, v117, v113, s[80:81]
	v_cndmask_b32_e64 v238, v157, v156, s[80:81]
	v_sub_f32_e32 v237, v238, v237
	v_min_f32_e32 v237, 0, v237
	v_mul_f32_e32 v237, 0x3fb8aa3b, v237
	v_exp_f32_e32 v237, v237
	v_cndmask_b32_e64 v239, v109, v105, s[80:81]
	v_add_f32_e32 v240, v105, v109
	v_mul_f32_e32 v237, v239, v237
	v_cndmask_b32_e64 v237, v237, v240, s[88:89]
	v_mul_f32_e32 v242, v97, v237
	v_cndmask_b32_e64 v237, v118, v114, s[82:83]
	v_cndmask_b32_e64 v238, v157, v156, s[82:83]
	v_sub_f32_e32 v237, v238, v237
	v_min_f32_e32 v237, 0, v237
	v_mul_f32_e32 v237, 0x3fb8aa3b, v237
	v_exp_f32_e32 v237, v237
	v_cndmask_b32_e64 v239, v110, v106, s[82:83]
	v_add_f32_e32 v240, v106, v110
	v_mul_f32_e32 v237, v239, v237
	v_cndmask_b32_e64 v237, v237, v240, s[90:91]
	v_mul_f32_e32 v243, v98, v237
	v_cndmask_b32_e64 v237, v119, v115, s[84:85]
	v_cndmask_b32_e64 v238, v157, v156, s[84:85]
	v_sub_f32_e32 v237, v238, v237
	v_min_f32_e32 v237, 0, v237
	v_mul_f32_e32 v237, 0x3fb8aa3b, v237
	v_exp_f32_e32 v237, v237
	v_cndmask_b32_e64 v239, v111, v107, s[84:85]
	v_add_f32_e32 v240, v107, v111
	v_mul_f32_e32 v237, v239, v237
	v_cndmask_b32_e64 v237, v237, v240, s[92:93]
	v_mul_f32_e32 v244, v99, v237
	ds_read_b64_tr_b16 v[148:149], v166 offset:64
	ds_read_b64_tr_b16 v[150:151], v166 offset:8768
	ds_read_b64_tr_b16 v[152:153], v166 offset:96
	ds_read_b64_tr_b16 v[154:155], v166 offset:8800
	v_subrev_u32_e32 v236, 16, v175
	v_cmp_gt_i32_e64 s[78:79], v236, 0
	v_cmp_gt_i32_e64 s[80:81], v236, 1
	v_cmp_gt_i32_e64 s[82:83], v236, 2
	v_cmp_gt_i32_e64 s[84:85], v236, 3
	v_cmp_eq_u32_e64 s[86:87], v236, 0
	v_cmp_eq_u32_e64 s[88:89], v236, 1
	v_cmp_eq_u32_e64 s[90:91], v236, 2
	v_cmp_eq_u32_e64 s[92:93], v236, 3
	v_cndmask_b32_e64 v237, v132, v128, s[78:79]
	v_cndmask_b32_e64 v238, v157, v156, s[78:79]
	v_sub_f32_e32 v237, v238, v237
	v_min_f32_e32 v237, 0, v237
	v_mul_f32_e32 v237, 0x3fb8aa3b, v237
	v_exp_f32_e32 v237, v237
	v_cndmask_b32_e64 v239, v124, v120, s[78:79]
	v_add_f32_e32 v240, v120, v124
	v_mul_f32_e32 v237, v239, v237
	v_cndmask_b32_e64 v237, v237, v240, s[86:87]
	v_mul_f32_e32 v245, v100, v237
	v_cndmask_b32_e64 v237, v133, v129, s[80:81]
	v_cndmask_b32_e64 v238, v157, v156, s[80:81]
	v_sub_f32_e32 v237, v238, v237
	v_min_f32_e32 v237, 0, v237
	v_mul_f32_e32 v237, 0x3fb8aa3b, v237
	v_exp_f32_e32 v237, v237
	v_cndmask_b32_e64 v239, v125, v121, s[80:81]
	v_add_f32_e32 v240, v121, v125
	v_mul_f32_e32 v237, v239, v237
	v_cndmask_b32_e64 v237, v237, v240, s[88:89]
	v_mul_f32_e32 v246, v101, v237
	v_cndmask_b32_e64 v237, v134, v130, s[82:83]
	v_cndmask_b32_e64 v238, v157, v156, s[82:83]
	v_sub_f32_e32 v237, v238, v237
	v_min_f32_e32 v237, 0, v237
	v_mul_f32_e32 v237, 0x3fb8aa3b, v237
	v_exp_f32_e32 v237, v237
	v_cndmask_b32_e64 v239, v126, v122, s[82:83]
	v_add_f32_e32 v240, v122, v126
	v_mul_f32_e32 v237, v239, v237
	v_cndmask_b32_e64 v237, v237, v240, s[90:91]
	v_mul_f32_e32 v247, v102, v237
	v_cndmask_b32_e64 v237, v135, v131, s[84:85]
	v_cndmask_b32_e64 v238, v157, v156, s[84:85]
	v_sub_f32_e32 v237, v238, v237
	v_min_f32_e32 v237, 0, v237
	v_mul_f32_e32 v237, 0x3fb8aa3b, v237
	v_exp_f32_e32 v237, v237
	v_cndmask_b32_e64 v239, v127, v123, s[84:85]
	v_add_f32_e32 v240, v123, v127
	v_mul_f32_e32 v237, v239, v237
	v_cndmask_b32_e64 v237, v237, v240, s[92:93]
	v_mul_f32_e32 v248, v103, v237
	v_cvt_pk_bf16_f32 v136, v241, v242
	v_cvt_pk_bf16_f32 v137, v243, v244
	v_cvt_pk_bf16_f32 v138, v245, v246
	v_cvt_pk_bf16_f32 v139, v247, v248
	s_waitcnt lgkmcnt(0)
	s_nop 1
	v_mfma_f32_16x16x32_bf16 v[16:19], v[136:139], v[140:143], 0
	v_mfma_f32_16x16x32_bf16 v[20:23], v[136:139], v[144:147], 0
	v_mfma_f32_16x16x32_bf16 v[24:27], v[136:139], v[148:151], 0
	v_mfma_f32_16x16x32_bf16 v[28:31], v[136:139], v[152:155], 0
	ds_read_b128 v[104:107], v168 offset:512
	ds_read_b128 v[108:111], v168 offset:2560
	ds_read_b128 v[112:115], v168 offset:4608
	ds_read_b128 v[116:119], v168 offset:6656
	ds_read_b128 v[120:123], v168 offset:576
	ds_read_b128 v[124:127], v168 offset:2624
	ds_read_b128 v[128:131], v168 offset:4672
	ds_read_b128 v[132:135], v168 offset:6720
	ds_read_b64_tr_b16 v[140:141], v166 offset:128
	ds_read_b64_tr_b16 v[142:143], v166 offset:8832
	ds_read_b64_tr_b16 v[144:145], v166 offset:160
	ds_read_b64_tr_b16 v[146:147], v166 offset:8864
	s_waitcnt lgkmcnt(4)
	v_subrev_u32_e32 v236, 0, v175
	v_cmp_gt_i32_e64 s[78:79], v236, 0
	v_cmp_gt_i32_e64 s[80:81], v236, 1
	v_cmp_gt_i32_e64 s[82:83], v236, 2
	v_cmp_gt_i32_e64 s[84:85], v236, 3
	v_cmp_eq_u32_e64 s[86:87], v236, 0
	v_cmp_eq_u32_e64 s[88:89], v236, 1
	v_cmp_eq_u32_e64 s[90:91], v236, 2
	v_cmp_eq_u32_e64 s[92:93], v236, 3
	v_cndmask_b32_e64 v237, v116, v112, s[78:79]
	v_cndmask_b32_e64 v238, v159, v158, s[78:79]
	v_sub_f32_e32 v237, v238, v237
	v_min_f32_e32 v237, 0, v237
	v_mul_f32_e32 v237, 0x3fb8aa3b, v237
	v_exp_f32_e32 v237, v237
	v_cndmask_b32_e64 v239, v108, v104, s[78:79]
	v_add_f32_e32 v240, v104, v108
	v_mul_f32_e32 v237, v239, v237
	v_cndmask_b32_e64 v237, v237, v240, s[86:87]
	v_mul_f32_e32 v241, v96, v237
	v_cndmask_b32_e64 v237, v117, v113, s[80:81]
	v_cndmask_b32_e64 v238, v159, v158, s[80:81]
	v_sub_f32_e32 v237, v238, v237
	v_min_f32_e32 v237, 0, v237
	v_mul_f32_e32 v237, 0x3fb8aa3b, v237
	v_exp_f32_e32 v237, v237
	v_cndmask_b32_e64 v239, v109, v105, s[80:81]
	v_add_f32_e32 v240, v105, v109
	v_mul_f32_e32 v237, v239, v237
	v_cndmask_b32_e64 v237, v237, v240, s[88:89]
	v_mul_f32_e32 v242, v97, v237
	v_cndmask_b32_e64 v237, v118, v114, s[82:83]
	v_cndmask_b32_e64 v238, v159, v158, s[82:83]
	v_sub_f32_e32 v237, v238, v237
	v_min_f32_e32 v237, 0, v237
	v_mul_f32_e32 v237, 0x3fb8aa3b, v237
	v_exp_f32_e32 v237, v237
	v_cndmask_b32_e64 v239, v110, v106, s[82:83]
	v_add_f32_e32 v240, v106, v110
	v_mul_f32_e32 v237, v239, v237
	v_cndmask_b32_e64 v237, v237, v240, s[90:91]
	v_mul_f32_e32 v243, v98, v237
	v_cndmask_b32_e64 v237, v119, v115, s[84:85]
	v_cndmask_b32_e64 v238, v159, v158, s[84:85]
	v_sub_f32_e32 v237, v238, v237
	v_min_f32_e32 v237, 0, v237
	v_mul_f32_e32 v237, 0x3fb8aa3b, v237
	v_exp_f32_e32 v237, v237
	v_cndmask_b32_e64 v239, v111, v107, s[84:85]
	v_add_f32_e32 v240, v107, v111
	v_mul_f32_e32 v237, v239, v237
	v_cndmask_b32_e64 v237, v237, v240, s[92:93]
	v_mul_f32_e32 v244, v99, v237
	ds_read_b64_tr_b16 v[148:149], v166 offset:192
	ds_read_b64_tr_b16 v[150:151], v166 offset:8896
	ds_read_b64_tr_b16 v[152:153], v166 offset:224
	ds_read_b64_tr_b16 v[154:155], v166 offset:8928
	v_subrev_u32_e32 v236, 16, v175
	v_cmp_gt_i32_e64 s[78:79], v236, 0
	v_cmp_gt_i32_e64 s[80:81], v236, 1
	v_cmp_gt_i32_e64 s[82:83], v236, 2
	v_cmp_gt_i32_e64 s[84:85], v236, 3
	v_cmp_eq_u32_e64 s[86:87], v236, 0
	v_cmp_eq_u32_e64 s[88:89], v236, 1
	v_cmp_eq_u32_e64 s[90:91], v236, 2
	v_cmp_eq_u32_e64 s[92:93], v236, 3
	v_cndmask_b32_e64 v237, v132, v128, s[78:79]
	v_cndmask_b32_e64 v238, v159, v158, s[78:79]
	v_sub_f32_e32 v237, v238, v237
	v_min_f32_e32 v237, 0, v237
	v_mul_f32_e32 v237, 0x3fb8aa3b, v237
	v_exp_f32_e32 v237, v237
	v_cndmask_b32_e64 v239, v124, v120, s[78:79]
	v_add_f32_e32 v240, v120, v124
	v_mul_f32_e32 v237, v239, v237
	v_cndmask_b32_e64 v237, v237, v240, s[86:87]
	v_mul_f32_e32 v245, v100, v237
	v_cndmask_b32_e64 v237, v133, v129, s[80:81]
	v_cndmask_b32_e64 v238, v159, v158, s[80:81]
	v_sub_f32_e32 v237, v238, v237
	v_min_f32_e32 v237, 0, v237
	v_mul_f32_e32 v237, 0x3fb8aa3b, v237
	v_exp_f32_e32 v237, v237
	v_cndmask_b32_e64 v239, v125, v121, s[80:81]
	v_add_f32_e32 v240, v121, v125
	v_mul_f32_e32 v237, v239, v237
	v_cndmask_b32_e64 v237, v237, v240, s[88:89]
	v_mul_f32_e32 v246, v101, v237
	v_cndmask_b32_e64 v237, v134, v130, s[82:83]
	v_cndmask_b32_e64 v238, v159, v158, s[82:83]
	v_sub_f32_e32 v237, v238, v237
	v_min_f32_e32 v237, 0, v237
	v_mul_f32_e32 v237, 0x3fb8aa3b, v237
	v_exp_f32_e32 v237, v237
	v_cndmask_b32_e64 v239, v126, v122, s[82:83]
	v_add_f32_e32 v240, v122, v126
	v_mul_f32_e32 v237, v239, v237
	v_cndmask_b32_e64 v237, v237, v240, s[90:91]
	v_mul_f32_e32 v247, v102, v237
	v_cndmask_b32_e64 v237, v135, v131, s[84:85]
	v_cndmask_b32_e64 v238, v159, v158, s[84:85]
	v_sub_f32_e32 v237, v238, v237
	v_min_f32_e32 v237, 0, v237
	v_mul_f32_e32 v237, 0x3fb8aa3b, v237
	v_exp_f32_e32 v237, v237
	v_cndmask_b32_e64 v239, v127, v123, s[84:85]
	v_add_f32_e32 v240, v123, v127
	v_mul_f32_e32 v237, v239, v237
	v_cndmask_b32_e64 v237, v237, v240, s[92:93]
	v_mul_f32_e32 v248, v103, v237
	v_cvt_pk_bf16_f32 v136, v241, v242
	v_cvt_pk_bf16_f32 v137, v243, v244
	v_cvt_pk_bf16_f32 v138, v245, v246
	v_cvt_pk_bf16_f32 v139, v247, v248
	s_waitcnt lgkmcnt(0)
	s_nop 1
	v_mfma_f32_16x16x32_bf16 v[32:35], v[136:139], v[140:143], 0
	v_mfma_f32_16x16x32_bf16 v[36:39], v[136:139], v[144:147], 0
	v_mfma_f32_16x16x32_bf16 v[40:43], v[136:139], v[148:151], 0
	v_mfma_f32_16x16x32_bf16 v[44:47], v[136:139], v[152:155], 0
	s_waitcnt vmcnt(0)
	v_mfma_f32_16x16x32_bf16 v[96:99], v[64:67], v[48:51], 0
	v_mfma_f32_16x16x32_bf16 v[96:99], v[68:71], v[52:55], v[96:99]
	v_mfma_f32_16x16x32_bf16 v[96:99], v[72:75], v[56:59], v[96:99]
	v_mfma_f32_16x16x32_bf16 v[96:99], v[76:79], v[60:63], v[96:99]
	v_mfma_f32_16x16x32_bf16 v[100:103], v[80:83], v[48:51], 0
	v_mfma_f32_16x16x32_bf16 v[100:103], v[84:87], v[52:55], v[100:103]
	v_mfma_f32_16x16x32_bf16 v[100:103], v[88:91], v[56:59], v[100:103]
	v_mfma_f32_16x16x32_bf16 v[100:103], v[92:95], v[60:63], v[100:103]
	s_add_u32 s52, s40, 0x18000
	s_addc_u32 s53, s41, 0
	global_load_dwordx4 v[64:67], v169, s[52:53] offset:0
	global_load_dwordx4 v[68:71], v169, s[52:53] offset:64
	global_load_dwordx4 v[72:75], v169, s[52:53] offset:128
	global_load_dwordx4 v[76:79], v169, s[52:53] offset:192
	s_add_u32 s52, s40, 0x1e000
	s_addc_u32 s53, s41, 0
	global_load_dwordx4 v[80:83], v169, s[52:53] offset:0
	global_load_dwordx4 v[84:87], v169, s[52:53] offset:64
	global_load_dwordx4 v[88:91], v169, s[52:53] offset:128
	global_load_dwordx4 v[92:95], v169, s[52:53] offset:192
	ds_read_b128 v[104:107], v168 offset:128
	ds_read_b128 v[108:111], v168 offset:2176
	ds_read_b128 v[112:115], v168 offset:4224
	ds_read_b128 v[116:119], v168 offset:6272
	ds_read_b128 v[120:123], v168 offset:192
	ds_read_b128 v[124:127], v168 offset:2240
	ds_read_b128 v[128:131], v168 offset:4288
	ds_read_b128 v[132:135], v168 offset:6336
	ds_read_b64_tr_b16 v[140:141], v166 offset:17408
	ds_read_b64_tr_b16 v[142:143], v166 offset:26112
	ds_read_b64_tr_b16 v[144:145], v166 offset:17440
	ds_read_b64_tr_b16 v[146:147], v166 offset:26144
	s_waitcnt lgkmcnt(4)
	v_subrev_u32_e32 v236, 32, v175
	v_cmp_gt_i32_e64 s[78:79], v236, 0
	v_cmp_gt_i32_e64 s[80:81], v236, 1
	v_cmp_gt_i32_e64 s[82:83], v236, 2
	v_cmp_gt_i32_e64 s[84:85], v236, 3
	v_cmp_eq_u32_e64 s[86:87], v236, 0
	v_cmp_eq_u32_e64 s[88:89], v236, 1
	v_cmp_eq_u32_e64 s[90:91], v236, 2
	v_cmp_eq_u32_e64 s[92:93], v236, 3
	v_cndmask_b32_e64 v237, v116, v112, s[78:79]
	v_cndmask_b32_e64 v238, v157, v156, s[78:79]
	v_sub_f32_e32 v237, v238, v237
	v_min_f32_e32 v237, 0, v237
	v_mul_f32_e32 v237, 0x3fb8aa3b, v237
	v_exp_f32_e32 v237, v237
	v_cndmask_b32_e64 v239, v108, v104, s[78:79]
	v_add_f32_e32 v240, v104, v108
	v_mul_f32_e32 v237, v239, v237
	v_cndmask_b32_e64 v237, v237, v240, s[86:87]
	v_mul_f32_e32 v241, v96, v237
	v_cndmask_b32_e64 v237, v117, v113, s[80:81]
	v_cndmask_b32_e64 v238, v157, v156, s[80:81]
	v_sub_f32_e32 v237, v238, v237
	v_min_f32_e32 v237, 0, v237
	v_mul_f32_e32 v237, 0x3fb8aa3b, v237
	v_exp_f32_e32 v237, v237
	v_cndmask_b32_e64 v239, v109, v105, s[80:81]
	v_add_f32_e32 v240, v105, v109
	v_mul_f32_e32 v237, v239, v237
	v_cndmask_b32_e64 v237, v237, v240, s[88:89]
	v_mul_f32_e32 v242, v97, v237
	v_cndmask_b32_e64 v237, v118, v114, s[82:83]
	v_cndmask_b32_e64 v238, v157, v156, s[82:83]
	v_sub_f32_e32 v237, v238, v237
	v_min_f32_e32 v237, 0, v237
	v_mul_f32_e32 v237, 0x3fb8aa3b, v237
	v_exp_f32_e32 v237, v237
	v_cndmask_b32_e64 v239, v110, v106, s[82:83]
	v_add_f32_e32 v240, v106, v110
	v_mul_f32_e32 v237, v239, v237
	v_cndmask_b32_e64 v237, v237, v240, s[90:91]
	v_mul_f32_e32 v243, v98, v237
	v_cndmask_b32_e64 v237, v119, v115, s[84:85]
	v_cndmask_b32_e64 v238, v157, v156, s[84:85]
	v_sub_f32_e32 v237, v238, v237
	v_min_f32_e32 v237, 0, v237
	v_mul_f32_e32 v237, 0x3fb8aa3b, v237
	v_exp_f32_e32 v237, v237
	v_cndmask_b32_e64 v239, v111, v107, s[84:85]
	v_add_f32_e32 v240, v107, v111
	v_mul_f32_e32 v237, v239, v237
	v_cndmask_b32_e64 v237, v237, v240, s[92:93]
	v_mul_f32_e32 v244, v99, v237
	ds_read_b64_tr_b16 v[148:149], v166 offset:17472
	ds_read_b64_tr_b16 v[150:151], v166 offset:26176
	ds_read_b64_tr_b16 v[152:153], v166 offset:17504
	ds_read_b64_tr_b16 v[154:155], v166 offset:26208
	v_subrev_u32_e32 v236, 48, v175
	v_cmp_gt_i32_e64 s[78:79], v236, 0
	v_cmp_gt_i32_e64 s[80:81], v236, 1
	v_cmp_gt_i32_e64 s[82:83], v236, 2
	v_cmp_gt_i32_e64 s[84:85], v236, 3
	v_cmp_eq_u32_e64 s[86:87], v236, 0
	v_cmp_eq_u32_e64 s[88:89], v236, 1
	v_cmp_eq_u32_e64 s[90:91], v236, 2
	v_cmp_eq_u32_e64 s[92:93], v236, 3
	v_cndmask_b32_e64 v237, v132, v128, s[78:79]
	v_cndmask_b32_e64 v238, v157, v156, s[78:79]
	v_sub_f32_e32 v237, v238, v237
	v_min_f32_e32 v237, 0, v237
	v_mul_f32_e32 v237, 0x3fb8aa3b, v237
	v_exp_f32_e32 v237, v237
	v_cndmask_b32_e64 v239, v124, v120, s[78:79]
	v_add_f32_e32 v240, v120, v124
	v_mul_f32_e32 v237, v239, v237
	v_cndmask_b32_e64 v237, v237, v240, s[86:87]
	v_mul_f32_e32 v245, v100, v237
	v_cndmask_b32_e64 v237, v133, v129, s[80:81]
	v_cndmask_b32_e64 v238, v157, v156, s[80:81]
	v_sub_f32_e32 v237, v238, v237
	v_min_f32_e32 v237, 0, v237
	v_mul_f32_e32 v237, 0x3fb8aa3b, v237
	v_exp_f32_e32 v237, v237
	v_cndmask_b32_e64 v239, v125, v121, s[80:81]
	v_add_f32_e32 v240, v121, v125
	v_mul_f32_e32 v237, v239, v237
	v_cndmask_b32_e64 v237, v237, v240, s[88:89]
	v_mul_f32_e32 v246, v101, v237
	v_cndmask_b32_e64 v237, v134, v130, s[82:83]
	v_cndmask_b32_e64 v238, v157, v156, s[82:83]
	v_sub_f32_e32 v237, v238, v237
	v_min_f32_e32 v237, 0, v237
	v_mul_f32_e32 v237, 0x3fb8aa3b, v237
	v_exp_f32_e32 v237, v237
	v_cndmask_b32_e64 v239, v126, v122, s[82:83]
	v_add_f32_e32 v240, v122, v126
	v_mul_f32_e32 v237, v239, v237
	v_cndmask_b32_e64 v237, v237, v240, s[90:91]
	v_mul_f32_e32 v247, v102, v237
	v_cndmask_b32_e64 v237, v135, v131, s[84:85]
	v_cndmask_b32_e64 v238, v157, v156, s[84:85]
	v_sub_f32_e32 v237, v238, v237
	v_min_f32_e32 v237, 0, v237
	v_mul_f32_e32 v237, 0x3fb8aa3b, v237
	v_exp_f32_e32 v237, v237
	v_cndmask_b32_e64 v239, v127, v123, s[84:85]
	v_add_f32_e32 v240, v123, v127
	v_mul_f32_e32 v237, v239, v237
	v_cndmask_b32_e64 v237, v237, v240, s[92:93]
	v_mul_f32_e32 v248, v103, v237
	v_cvt_pk_bf16_f32 v136, v241, v242
	v_cvt_pk_bf16_f32 v137, v243, v244
	v_cvt_pk_bf16_f32 v138, v245, v246
	v_cvt_pk_bf16_f32 v139, v247, v248
	s_waitcnt lgkmcnt(0)
	s_nop 1
	v_mfma_f32_16x16x32_bf16 v[16:19], v[136:139], v[140:143], v[16:19]
	v_mfma_f32_16x16x32_bf16 v[20:23], v[136:139], v[144:147], v[20:23]
	v_mfma_f32_16x16x32_bf16 v[24:27], v[136:139], v[148:151], v[24:27]
	v_mfma_f32_16x16x32_bf16 v[28:31], v[136:139], v[152:155], v[28:31]
	ds_read_b128 v[104:107], v168 offset:640
	ds_read_b128 v[108:111], v168 offset:2688
	ds_read_b128 v[112:115], v168 offset:4736
	ds_read_b128 v[116:119], v168 offset:6784
	ds_read_b128 v[120:123], v168 offset:704
	ds_read_b128 v[124:127], v168 offset:2752
	ds_read_b128 v[128:131], v168 offset:4800
	ds_read_b128 v[132:135], v168 offset:6848
	ds_read_b64_tr_b16 v[140:141], v166 offset:17536
	ds_read_b64_tr_b16 v[142:143], v166 offset:26240
	ds_read_b64_tr_b16 v[144:145], v166 offset:17568
	ds_read_b64_tr_b16 v[146:147], v166 offset:26272
	s_waitcnt lgkmcnt(4)
	v_subrev_u32_e32 v236, 32, v175
	v_cmp_gt_i32_e64 s[78:79], v236, 0
	v_cmp_gt_i32_e64 s[80:81], v236, 1
	v_cmp_gt_i32_e64 s[82:83], v236, 2
	v_cmp_gt_i32_e64 s[84:85], v236, 3
	v_cmp_eq_u32_e64 s[86:87], v236, 0
	v_cmp_eq_u32_e64 s[88:89], v236, 1
	v_cmp_eq_u32_e64 s[90:91], v236, 2
	v_cmp_eq_u32_e64 s[92:93], v236, 3
	v_cndmask_b32_e64 v237, v116, v112, s[78:79]
	v_cndmask_b32_e64 v238, v159, v158, s[78:79]
	v_sub_f32_e32 v237, v238, v237
	v_min_f32_e32 v237, 0, v237
	v_mul_f32_e32 v237, 0x3fb8aa3b, v237
	v_exp_f32_e32 v237, v237
	v_cndmask_b32_e64 v239, v108, v104, s[78:79]
	v_add_f32_e32 v240, v104, v108
	v_mul_f32_e32 v237, v239, v237
	v_cndmask_b32_e64 v237, v237, v240, s[86:87]
	v_mul_f32_e32 v241, v96, v237
	v_cndmask_b32_e64 v237, v117, v113, s[80:81]
	v_cndmask_b32_e64 v238, v159, v158, s[80:81]
	v_sub_f32_e32 v237, v238, v237
	v_min_f32_e32 v237, 0, v237
	v_mul_f32_e32 v237, 0x3fb8aa3b, v237
	v_exp_f32_e32 v237, v237
	v_cndmask_b32_e64 v239, v109, v105, s[80:81]
	v_add_f32_e32 v240, v105, v109
	v_mul_f32_e32 v237, v239, v237
	v_cndmask_b32_e64 v237, v237, v240, s[88:89]
	v_mul_f32_e32 v242, v97, v237
	v_cndmask_b32_e64 v237, v118, v114, s[82:83]
	v_cndmask_b32_e64 v238, v159, v158, s[82:83]
	v_sub_f32_e32 v237, v238, v237
	v_min_f32_e32 v237, 0, v237
	v_mul_f32_e32 v237, 0x3fb8aa3b, v237
	v_exp_f32_e32 v237, v237
	v_cndmask_b32_e64 v239, v110, v106, s[82:83]
	v_add_f32_e32 v240, v106, v110
	v_mul_f32_e32 v237, v239, v237
	v_cndmask_b32_e64 v237, v237, v240, s[90:91]
	v_mul_f32_e32 v243, v98, v237
	v_cndmask_b32_e64 v237, v119, v115, s[84:85]
	v_cndmask_b32_e64 v238, v159, v158, s[84:85]
	v_sub_f32_e32 v237, v238, v237
	v_min_f32_e32 v237, 0, v237
	v_mul_f32_e32 v237, 0x3fb8aa3b, v237
	v_exp_f32_e32 v237, v237
	v_cndmask_b32_e64 v239, v111, v107, s[84:85]
	v_add_f32_e32 v240, v107, v111
	v_mul_f32_e32 v237, v239, v237
	v_cndmask_b32_e64 v237, v237, v240, s[92:93]
	v_mul_f32_e32 v244, v99, v237
	ds_read_b64_tr_b16 v[148:149], v166 offset:17600
	ds_read_b64_tr_b16 v[150:151], v166 offset:26304
	ds_read_b64_tr_b16 v[152:153], v166 offset:17632
	ds_read_b64_tr_b16 v[154:155], v166 offset:26336
	v_subrev_u32_e32 v236, 48, v175
	v_cmp_gt_i32_e64 s[78:79], v236, 0
	v_cmp_gt_i32_e64 s[80:81], v236, 1
	v_cmp_gt_i32_e64 s[82:83], v236, 2
	v_cmp_gt_i32_e64 s[84:85], v236, 3
	v_cmp_eq_u32_e64 s[86:87], v236, 0
	v_cmp_eq_u32_e64 s[88:89], v236, 1
	v_cmp_eq_u32_e64 s[90:91], v236, 2
	v_cmp_eq_u32_e64 s[92:93], v236, 3
	v_cndmask_b32_e64 v237, v132, v128, s[78:79]
	v_cndmask_b32_e64 v238, v159, v158, s[78:79]
	v_sub_f32_e32 v237, v238, v237
	v_min_f32_e32 v237, 0, v237
	v_mul_f32_e32 v237, 0x3fb8aa3b, v237
	v_exp_f32_e32 v237, v237
	v_cndmask_b32_e64 v239, v124, v120, s[78:79]
	v_add_f32_e32 v240, v120, v124
	v_mul_f32_e32 v237, v239, v237
	v_cndmask_b32_e64 v237, v237, v240, s[86:87]
	v_mul_f32_e32 v245, v100, v237
	v_cndmask_b32_e64 v237, v133, v129, s[80:81]
	v_cndmask_b32_e64 v238, v159, v158, s[80:81]
	v_sub_f32_e32 v237, v238, v237
	v_min_f32_e32 v237, 0, v237
	v_mul_f32_e32 v237, 0x3fb8aa3b, v237
	v_exp_f32_e32 v237, v237
	v_cndmask_b32_e64 v239, v125, v121, s[80:81]
	v_add_f32_e32 v240, v121, v125
	v_mul_f32_e32 v237, v239, v237
	v_cndmask_b32_e64 v237, v237, v240, s[88:89]
	v_mul_f32_e32 v246, v101, v237
	v_cndmask_b32_e64 v237, v134, v130, s[82:83]
	v_cndmask_b32_e64 v238, v159, v158, s[82:83]
	v_sub_f32_e32 v237, v238, v237
	v_min_f32_e32 v237, 0, v237
	v_mul_f32_e32 v237, 0x3fb8aa3b, v237
	v_exp_f32_e32 v237, v237
	v_cndmask_b32_e64 v239, v126, v122, s[82:83]
	v_add_f32_e32 v240, v122, v126
	v_mul_f32_e32 v237, v239, v237
	v_cndmask_b32_e64 v237, v237, v240, s[90:91]
	v_mul_f32_e32 v247, v102, v237
	v_cndmask_b32_e64 v237, v135, v131, s[84:85]
	v_cndmask_b32_e64 v238, v159, v158, s[84:85]
	v_sub_f32_e32 v237, v238, v237
	v_min_f32_e32 v237, 0, v237
	v_mul_f32_e32 v237, 0x3fb8aa3b, v237
	v_exp_f32_e32 v237, v237
	v_cndmask_b32_e64 v239, v127, v123, s[84:85]
	v_add_f32_e32 v240, v123, v127
	v_mul_f32_e32 v237, v239, v237
	v_cndmask_b32_e64 v237, v237, v240, s[92:93]
	v_mul_f32_e32 v248, v103, v237
	v_cvt_pk_bf16_f32 v136, v241, v242
	v_cvt_pk_bf16_f32 v137, v243, v244
	v_cvt_pk_bf16_f32 v138, v245, v246
	v_cvt_pk_bf16_f32 v139, v247, v248
	s_waitcnt lgkmcnt(0)
	s_nop 1
	v_mfma_f32_16x16x32_bf16 v[32:35], v[136:139], v[140:143], v[32:35]
	v_mfma_f32_16x16x32_bf16 v[36:39], v[136:139], v[144:147], v[36:39]
	v_mfma_f32_16x16x32_bf16 v[40:43], v[136:139], v[148:151], v[40:43]
	v_mfma_f32_16x16x32_bf16 v[44:47], v[136:139], v[152:155], v[44:47]
	s_waitcnt vmcnt(0)
	v_mfma_f32_16x16x32_bf16 v[96:99], v[64:67], v[48:51], 0
	v_mfma_f32_16x16x32_bf16 v[96:99], v[68:71], v[52:55], v[96:99]
	v_mfma_f32_16x16x32_bf16 v[96:99], v[72:75], v[56:59], v[96:99]
	v_mfma_f32_16x16x32_bf16 v[96:99], v[76:79], v[60:63], v[96:99]
	v_mfma_f32_16x16x32_bf16 v[100:103], v[80:83], v[48:51], 0
	v_mfma_f32_16x16x32_bf16 v[100:103], v[84:87], v[52:55], v[100:103]
	v_mfma_f32_16x16x32_bf16 v[100:103], v[88:91], v[56:59], v[100:103]
	v_mfma_f32_16x16x32_bf16 v[100:103], v[92:95], v[60:63], v[100:103]
	s_add_u32 s52, s40, 0x24000
	s_addc_u32 s53, s41, 0
	global_load_dwordx4 v[64:67], v169, s[52:53] offset:0
	global_load_dwordx4 v[68:71], v169, s[52:53] offset:64
	global_load_dwordx4 v[72:75], v169, s[52:53] offset:128
	global_load_dwordx4 v[76:79], v169, s[52:53] offset:192
	s_add_u32 s52, s40, 0x2a000
	s_addc_u32 s53, s41, 0
	global_load_dwordx4 v[80:83], v169, s[52:53] offset:0
	global_load_dwordx4 v[84:87], v169, s[52:53] offset:64
	global_load_dwordx4 v[88:91], v169, s[52:53] offset:128
	global_load_dwordx4 v[92:95], v169, s[52:53] offset:192
	ds_read_b128 v[104:107], v168 offset:256
	ds_read_b128 v[108:111], v168 offset:2304
	ds_read_b128 v[112:115], v168 offset:4352
	ds_read_b128 v[116:119], v168 offset:6400
	ds_read_b128 v[120:123], v168 offset:320
	ds_read_b128 v[124:127], v168 offset:2368
	ds_read_b128 v[128:131], v168 offset:4416
	ds_read_b128 v[132:135], v168 offset:6464
	ds_read_b64_tr_b16 v[140:141], v166 offset:34816
	ds_read_b64_tr_b16 v[142:143], v166 offset:43520
	ds_read_b64_tr_b16 v[144:145], v166 offset:34848
	ds_read_b64_tr_b16 v[146:147], v166 offset:43552
	s_waitcnt lgkmcnt(4)
	v_subrev_u32_e32 v236, 64, v175
	v_cmp_gt_i32_e64 s[78:79], v236, 0
	v_cmp_gt_i32_e64 s[80:81], v236, 1
	v_cmp_gt_i32_e64 s[82:83], v236, 2
	v_cmp_gt_i32_e64 s[84:85], v236, 3
	v_cmp_eq_u32_e64 s[86:87], v236, 0
	v_cmp_eq_u32_e64 s[88:89], v236, 1
	v_cmp_eq_u32_e64 s[90:91], v236, 2
	v_cmp_eq_u32_e64 s[92:93], v236, 3
	v_cndmask_b32_e64 v237, v116, v112, s[78:79]
	v_cndmask_b32_e64 v238, v157, v156, s[78:79]
	v_sub_f32_e32 v237, v238, v237
	v_min_f32_e32 v237, 0, v237
	v_mul_f32_e32 v237, 0x3fb8aa3b, v237
	v_exp_f32_e32 v237, v237
	v_cndmask_b32_e64 v239, v108, v104, s[78:79]
	v_add_f32_e32 v240, v104, v108
	v_mul_f32_e32 v237, v239, v237
	v_cndmask_b32_e64 v237, v237, v240, s[86:87]
	v_mul_f32_e32 v241, v96, v237
	v_cndmask_b32_e64 v237, v117, v113, s[80:81]
	v_cndmask_b32_e64 v238, v157, v156, s[80:81]
	v_sub_f32_e32 v237, v238, v237
	v_min_f32_e32 v237, 0, v237
	v_mul_f32_e32 v237, 0x3fb8aa3b, v237
	v_exp_f32_e32 v237, v237
	v_cndmask_b32_e64 v239, v109, v105, s[80:81]
	v_add_f32_e32 v240, v105, v109
	v_mul_f32_e32 v237, v239, v237
	v_cndmask_b32_e64 v237, v237, v240, s[88:89]
	v_mul_f32_e32 v242, v97, v237
	v_cndmask_b32_e64 v237, v118, v114, s[82:83]
	v_cndmask_b32_e64 v238, v157, v156, s[82:83]
	v_sub_f32_e32 v237, v238, v237
	v_min_f32_e32 v237, 0, v237
	v_mul_f32_e32 v237, 0x3fb8aa3b, v237
	v_exp_f32_e32 v237, v237
	v_cndmask_b32_e64 v239, v110, v106, s[82:83]
	v_add_f32_e32 v240, v106, v110
	v_mul_f32_e32 v237, v239, v237
	v_cndmask_b32_e64 v237, v237, v240, s[90:91]
	v_mul_f32_e32 v243, v98, v237
	v_cndmask_b32_e64 v237, v119, v115, s[84:85]
	v_cndmask_b32_e64 v238, v157, v156, s[84:85]
	v_sub_f32_e32 v237, v238, v237
	v_min_f32_e32 v237, 0, v237
	v_mul_f32_e32 v237, 0x3fb8aa3b, v237
	v_exp_f32_e32 v237, v237
	v_cndmask_b32_e64 v239, v111, v107, s[84:85]
	v_add_f32_e32 v240, v107, v111
	v_mul_f32_e32 v237, v239, v237
	v_cndmask_b32_e64 v237, v237, v240, s[92:93]
	v_mul_f32_e32 v244, v99, v237
	ds_read_b64_tr_b16 v[148:149], v166 offset:34880
	ds_read_b64_tr_b16 v[150:151], v166 offset:43584
	ds_read_b64_tr_b16 v[152:153], v166 offset:34912
	ds_read_b64_tr_b16 v[154:155], v166 offset:43616
	v_subrev_u32_e32 v236, 80, v175
	v_cmp_gt_i32_e64 s[78:79], v236, 0
	v_cmp_gt_i32_e64 s[80:81], v236, 1
	v_cmp_gt_i32_e64 s[82:83], v236, 2
	v_cmp_gt_i32_e64 s[84:85], v236, 3
	v_cmp_eq_u32_e64 s[86:87], v236, 0
	v_cmp_eq_u32_e64 s[88:89], v236, 1
	v_cmp_eq_u32_e64 s[90:91], v236, 2
	v_cmp_eq_u32_e64 s[92:93], v236, 3
	v_cndmask_b32_e64 v237, v132, v128, s[78:79]
	v_cndmask_b32_e64 v238, v157, v156, s[78:79]
	v_sub_f32_e32 v237, v238, v237
	v_min_f32_e32 v237, 0, v237
	v_mul_f32_e32 v237, 0x3fb8aa3b, v237
	v_exp_f32_e32 v237, v237
	v_cndmask_b32_e64 v239, v124, v120, s[78:79]
	v_add_f32_e32 v240, v120, v124
	v_mul_f32_e32 v237, v239, v237
	v_cndmask_b32_e64 v237, v237, v240, s[86:87]
	v_mul_f32_e32 v245, v100, v237
	v_cndmask_b32_e64 v237, v133, v129, s[80:81]
	v_cndmask_b32_e64 v238, v157, v156, s[80:81]
	v_sub_f32_e32 v237, v238, v237
	v_min_f32_e32 v237, 0, v237
	v_mul_f32_e32 v237, 0x3fb8aa3b, v237
	v_exp_f32_e32 v237, v237
	v_cndmask_b32_e64 v239, v125, v121, s[80:81]
	v_add_f32_e32 v240, v121, v125
	v_mul_f32_e32 v237, v239, v237
	v_cndmask_b32_e64 v237, v237, v240, s[88:89]
	v_mul_f32_e32 v246, v101, v237
	v_cndmask_b32_e64 v237, v134, v130, s[82:83]
	v_cndmask_b32_e64 v238, v157, v156, s[82:83]
	v_sub_f32_e32 v237, v238, v237
	v_min_f32_e32 v237, 0, v237
	v_mul_f32_e32 v237, 0x3fb8aa3b, v237
	v_exp_f32_e32 v237, v237
	v_cndmask_b32_e64 v239, v126, v122, s[82:83]
	v_add_f32_e32 v240, v122, v126
	v_mul_f32_e32 v237, v239, v237
	v_cndmask_b32_e64 v237, v237, v240, s[90:91]
	v_mul_f32_e32 v247, v102, v237
	v_cndmask_b32_e64 v237, v135, v131, s[84:85]
	v_cndmask_b32_e64 v238, v157, v156, s[84:85]
	v_sub_f32_e32 v237, v238, v237
	v_min_f32_e32 v237, 0, v237
	v_mul_f32_e32 v237, 0x3fb8aa3b, v237
	v_exp_f32_e32 v237, v237
	v_cndmask_b32_e64 v239, v127, v123, s[84:85]
	v_add_f32_e32 v240, v123, v127
	v_mul_f32_e32 v237, v239, v237
	v_cndmask_b32_e64 v237, v237, v240, s[92:93]
	v_mul_f32_e32 v248, v103, v237
	v_cvt_pk_bf16_f32 v136, v241, v242
	v_cvt_pk_bf16_f32 v137, v243, v244
	v_cvt_pk_bf16_f32 v138, v245, v246
	v_cvt_pk_bf16_f32 v139, v247, v248
	s_waitcnt lgkmcnt(0)
	s_nop 1
	v_mfma_f32_16x16x32_bf16 v[16:19], v[136:139], v[140:143], v[16:19]
	v_mfma_f32_16x16x32_bf16 v[20:23], v[136:139], v[144:147], v[20:23]
	v_mfma_f32_16x16x32_bf16 v[24:27], v[136:139], v[148:151], v[24:27]
	v_mfma_f32_16x16x32_bf16 v[28:31], v[136:139], v[152:155], v[28:31]
	ds_read_b128 v[104:107], v168 offset:768
	ds_read_b128 v[108:111], v168 offset:2816
	ds_read_b128 v[112:115], v168 offset:4864
	ds_read_b128 v[116:119], v168 offset:6912
	ds_read_b128 v[120:123], v168 offset:832
	ds_read_b128 v[124:127], v168 offset:2880
	ds_read_b128 v[128:131], v168 offset:4928
	ds_read_b128 v[132:135], v168 offset:6976
	ds_read_b64_tr_b16 v[140:141], v166 offset:34944
	ds_read_b64_tr_b16 v[142:143], v166 offset:43648
	ds_read_b64_tr_b16 v[144:145], v166 offset:34976
	ds_read_b64_tr_b16 v[146:147], v166 offset:43680
	s_waitcnt lgkmcnt(4)
	v_subrev_u32_e32 v236, 64, v175
	v_cmp_gt_i32_e64 s[78:79], v236, 0
	v_cmp_gt_i32_e64 s[80:81], v236, 1
	v_cmp_gt_i32_e64 s[82:83], v236, 2
	v_cmp_gt_i32_e64 s[84:85], v236, 3
	v_cmp_eq_u32_e64 s[86:87], v236, 0
	v_cmp_eq_u32_e64 s[88:89], v236, 1
	v_cmp_eq_u32_e64 s[90:91], v236, 2
	v_cmp_eq_u32_e64 s[92:93], v236, 3
	v_cndmask_b32_e64 v237, v116, v112, s[78:79]
	v_cndmask_b32_e64 v238, v159, v158, s[78:79]
	v_sub_f32_e32 v237, v238, v237
	v_min_f32_e32 v237, 0, v237
	v_mul_f32_e32 v237, 0x3fb8aa3b, v237
	v_exp_f32_e32 v237, v237
	v_cndmask_b32_e64 v239, v108, v104, s[78:79]
	v_add_f32_e32 v240, v104, v108
	v_mul_f32_e32 v237, v239, v237
	v_cndmask_b32_e64 v237, v237, v240, s[86:87]
	v_mul_f32_e32 v241, v96, v237
	v_cndmask_b32_e64 v237, v117, v113, s[80:81]
	v_cndmask_b32_e64 v238, v159, v158, s[80:81]
	v_sub_f32_e32 v237, v238, v237
	v_min_f32_e32 v237, 0, v237
	v_mul_f32_e32 v237, 0x3fb8aa3b, v237
	v_exp_f32_e32 v237, v237
	v_cndmask_b32_e64 v239, v109, v105, s[80:81]
	v_add_f32_e32 v240, v105, v109
	v_mul_f32_e32 v237, v239, v237
	v_cndmask_b32_e64 v237, v237, v240, s[88:89]
	v_mul_f32_e32 v242, v97, v237
	v_cndmask_b32_e64 v237, v118, v114, s[82:83]
	v_cndmask_b32_e64 v238, v159, v158, s[82:83]
	v_sub_f32_e32 v237, v238, v237
	v_min_f32_e32 v237, 0, v237
	v_mul_f32_e32 v237, 0x3fb8aa3b, v237
	v_exp_f32_e32 v237, v237
	v_cndmask_b32_e64 v239, v110, v106, s[82:83]
	v_add_f32_e32 v240, v106, v110
	v_mul_f32_e32 v237, v239, v237
	v_cndmask_b32_e64 v237, v237, v240, s[90:91]
	v_mul_f32_e32 v243, v98, v237
	v_cndmask_b32_e64 v237, v119, v115, s[84:85]
	v_cndmask_b32_e64 v238, v159, v158, s[84:85]
	v_sub_f32_e32 v237, v238, v237
	v_min_f32_e32 v237, 0, v237
	v_mul_f32_e32 v237, 0x3fb8aa3b, v237
	v_exp_f32_e32 v237, v237
	v_cndmask_b32_e64 v239, v111, v107, s[84:85]
	v_add_f32_e32 v240, v107, v111
	v_mul_f32_e32 v237, v239, v237
	v_cndmask_b32_e64 v237, v237, v240, s[92:93]
	v_mul_f32_e32 v244, v99, v237
	ds_read_b64_tr_b16 v[148:149], v166 offset:35008
	ds_read_b64_tr_b16 v[150:151], v166 offset:43712
	ds_read_b64_tr_b16 v[152:153], v166 offset:35040
	ds_read_b64_tr_b16 v[154:155], v166 offset:43744
	v_subrev_u32_e32 v236, 80, v175
	v_cmp_gt_i32_e64 s[78:79], v236, 0
	v_cmp_gt_i32_e64 s[80:81], v236, 1
	v_cmp_gt_i32_e64 s[82:83], v236, 2
	v_cmp_gt_i32_e64 s[84:85], v236, 3
	v_cmp_eq_u32_e64 s[86:87], v236, 0
	v_cmp_eq_u32_e64 s[88:89], v236, 1
	v_cmp_eq_u32_e64 s[90:91], v236, 2
	v_cmp_eq_u32_e64 s[92:93], v236, 3
	v_cndmask_b32_e64 v237, v132, v128, s[78:79]
	v_cndmask_b32_e64 v238, v159, v158, s[78:79]
	v_sub_f32_e32 v237, v238, v237
	v_min_f32_e32 v237, 0, v237
	v_mul_f32_e32 v237, 0x3fb8aa3b, v237
	v_exp_f32_e32 v237, v237
	v_cndmask_b32_e64 v239, v124, v120, s[78:79]
	v_add_f32_e32 v240, v120, v124
	v_mul_f32_e32 v237, v239, v237
	v_cndmask_b32_e64 v237, v237, v240, s[86:87]
	v_mul_f32_e32 v245, v100, v237
	v_cndmask_b32_e64 v237, v133, v129, s[80:81]
	v_cndmask_b32_e64 v238, v159, v158, s[80:81]
	v_sub_f32_e32 v237, v238, v237
	v_min_f32_e32 v237, 0, v237
	v_mul_f32_e32 v237, 0x3fb8aa3b, v237
	v_exp_f32_e32 v237, v237
	v_cndmask_b32_e64 v239, v125, v121, s[80:81]
	v_add_f32_e32 v240, v121, v125
	v_mul_f32_e32 v237, v239, v237
	v_cndmask_b32_e64 v237, v237, v240, s[88:89]
	v_mul_f32_e32 v246, v101, v237
	v_cndmask_b32_e64 v237, v134, v130, s[82:83]
	v_cndmask_b32_e64 v238, v159, v158, s[82:83]
	v_sub_f32_e32 v237, v238, v237
	v_min_f32_e32 v237, 0, v237
	v_mul_f32_e32 v237, 0x3fb8aa3b, v237
	v_exp_f32_e32 v237, v237
	v_cndmask_b32_e64 v239, v126, v122, s[82:83]
	v_add_f32_e32 v240, v122, v126
	v_mul_f32_e32 v237, v239, v237
	v_cndmask_b32_e64 v237, v237, v240, s[90:91]
	v_mul_f32_e32 v247, v102, v237
	v_cndmask_b32_e64 v237, v135, v131, s[84:85]
	v_cndmask_b32_e64 v238, v159, v158, s[84:85]
	v_sub_f32_e32 v237, v238, v237
	v_min_f32_e32 v237, 0, v237
	v_mul_f32_e32 v237, 0x3fb8aa3b, v237
	v_exp_f32_e32 v237, v237
	v_cndmask_b32_e64 v239, v127, v123, s[84:85]
	v_add_f32_e32 v240, v123, v127
	v_mul_f32_e32 v237, v239, v237
	v_cndmask_b32_e64 v237, v237, v240, s[92:93]
	v_mul_f32_e32 v248, v103, v237
	v_cvt_pk_bf16_f32 v136, v241, v242
	v_cvt_pk_bf16_f32 v137, v243, v244
	v_cvt_pk_bf16_f32 v138, v245, v246
	v_cvt_pk_bf16_f32 v139, v247, v248
	s_waitcnt lgkmcnt(0)
	s_nop 1
	v_mfma_f32_16x16x32_bf16 v[32:35], v[136:139], v[140:143], v[32:35]
	v_mfma_f32_16x16x32_bf16 v[36:39], v[136:139], v[144:147], v[36:39]
	v_mfma_f32_16x16x32_bf16 v[40:43], v[136:139], v[148:151], v[40:43]
	v_mfma_f32_16x16x32_bf16 v[44:47], v[136:139], v[152:155], v[44:47]
	s_waitcnt vmcnt(0)
	v_mfma_f32_16x16x32_bf16 v[96:99], v[64:67], v[48:51], 0
	v_mfma_f32_16x16x32_bf16 v[96:99], v[68:71], v[52:55], v[96:99]
	v_mfma_f32_16x16x32_bf16 v[96:99], v[72:75], v[56:59], v[96:99]
	v_mfma_f32_16x16x32_bf16 v[96:99], v[76:79], v[60:63], v[96:99]
	v_mfma_f32_16x16x32_bf16 v[100:103], v[80:83], v[48:51], 0
	v_mfma_f32_16x16x32_bf16 v[100:103], v[84:87], v[52:55], v[100:103]
	v_mfma_f32_16x16x32_bf16 v[100:103], v[88:91], v[56:59], v[100:103]
	v_mfma_f32_16x16x32_bf16 v[100:103], v[92:95], v[60:63], v[100:103]
	s_mov_b32 s52, s42
	s_mov_b32 s53, s43
	global_load_dwordx4 v[64:67], v170, s[52:53] offset:0
	global_load_dwordx4 v[68:71], v171, s[52:53] offset:0
	global_load_dwordx4 v[72:75], v172, s[52:53] offset:0
	global_load_dwordx4 v[76:79], v173, s[52:53] offset:0
	s_mov_b32 s52, s42
	s_mov_b32 s53, s43
	global_load_dwordx4 v[80:83], v170, s[52:53] offset:64
	global_load_dwordx4 v[84:87], v171, s[52:53] offset:64
	global_load_dwordx4 v[88:91], v172, s[52:53] offset:64
	global_load_dwordx4 v[92:95], v173, s[52:53] offset:64
	ds_read_b128 v[104:107], v168 offset:384
	ds_read_b128 v[108:111], v168 offset:2432
	ds_read_b128 v[112:115], v168 offset:4480
	ds_read_b128 v[116:119], v168 offset:6528
	ds_read_b128 v[120:123], v168 offset:448
	ds_read_b128 v[124:127], v168 offset:2496
	ds_read_b128 v[128:131], v168 offset:4544
	ds_read_b128 v[132:135], v168 offset:6592
	ds_read_b64_tr_b16 v[140:141], v166 offset:52224
	ds_read_b64_tr_b16 v[142:143], v166 offset:60928
	ds_read_b64_tr_b16 v[144:145], v166 offset:52256
	ds_read_b64_tr_b16 v[146:147], v166 offset:60960
	s_waitcnt lgkmcnt(4)
	v_subrev_u32_e32 v236, 96, v175
	v_cmp_gt_i32_e64 s[78:79], v236, 0
	v_cmp_gt_i32_e64 s[80:81], v236, 1
	v_cmp_gt_i32_e64 s[82:83], v236, 2
	v_cmp_gt_i32_e64 s[84:85], v236, 3
	v_cmp_eq_u32_e64 s[86:87], v236, 0
	v_cmp_eq_u32_e64 s[88:89], v236, 1
	v_cmp_eq_u32_e64 s[90:91], v236, 2
	v_cmp_eq_u32_e64 s[92:93], v236, 3
	v_cndmask_b32_e64 v237, v116, v112, s[78:79]
	v_cndmask_b32_e64 v238, v157, v156, s[78:79]
	v_sub_f32_e32 v237, v238, v237
	v_min_f32_e32 v237, 0, v237
	v_mul_f32_e32 v237, 0x3fb8aa3b, v237
	v_exp_f32_e32 v237, v237
	v_cndmask_b32_e64 v239, v108, v104, s[78:79]
	v_add_f32_e32 v240, v104, v108
	v_mul_f32_e32 v237, v239, v237
	v_cndmask_b32_e64 v237, v237, v240, s[86:87]
	v_mul_f32_e32 v241, v96, v237
	v_cndmask_b32_e64 v237, v117, v113, s[80:81]
	v_cndmask_b32_e64 v238, v157, v156, s[80:81]
	v_sub_f32_e32 v237, v238, v237
	v_min_f32_e32 v237, 0, v237
	v_mul_f32_e32 v237, 0x3fb8aa3b, v237
	v_exp_f32_e32 v237, v237
	v_cndmask_b32_e64 v239, v109, v105, s[80:81]
	v_add_f32_e32 v240, v105, v109
	v_mul_f32_e32 v237, v239, v237
	v_cndmask_b32_e64 v237, v237, v240, s[88:89]
	v_mul_f32_e32 v242, v97, v237
	v_cndmask_b32_e64 v237, v118, v114, s[82:83]
	v_cndmask_b32_e64 v238, v157, v156, s[82:83]
	v_sub_f32_e32 v237, v238, v237
	v_min_f32_e32 v237, 0, v237
	v_mul_f32_e32 v237, 0x3fb8aa3b, v237
	v_exp_f32_e32 v237, v237
	v_cndmask_b32_e64 v239, v110, v106, s[82:83]
	v_add_f32_e32 v240, v106, v110
	v_mul_f32_e32 v237, v239, v237
	v_cndmask_b32_e64 v237, v237, v240, s[90:91]
	v_mul_f32_e32 v243, v98, v237
	v_cndmask_b32_e64 v237, v119, v115, s[84:85]
	v_cndmask_b32_e64 v238, v157, v156, s[84:85]
	v_sub_f32_e32 v237, v238, v237
	v_min_f32_e32 v237, 0, v237
	v_mul_f32_e32 v237, 0x3fb8aa3b, v237
	v_exp_f32_e32 v237, v237
	v_cndmask_b32_e64 v239, v111, v107, s[84:85]
	v_add_f32_e32 v240, v107, v111
	v_mul_f32_e32 v237, v239, v237
	v_cndmask_b32_e64 v237, v237, v240, s[92:93]
	v_mul_f32_e32 v244, v99, v237
	ds_read_b64_tr_b16 v[148:149], v166 offset:52288
	ds_read_b64_tr_b16 v[150:151], v166 offset:60992
	ds_read_b64_tr_b16 v[152:153], v166 offset:52320
	ds_read_b64_tr_b16 v[154:155], v166 offset:61024
	v_subrev_u32_e32 v236, 112, v175
	v_cmp_gt_i32_e64 s[78:79], v236, 0
	v_cmp_gt_i32_e64 s[80:81], v236, 1
	v_cmp_gt_i32_e64 s[82:83], v236, 2
	v_cmp_gt_i32_e64 s[84:85], v236, 3
	v_cmp_eq_u32_e64 s[86:87], v236, 0
	v_cmp_eq_u32_e64 s[88:89], v236, 1
	v_cmp_eq_u32_e64 s[90:91], v236, 2
	v_cmp_eq_u32_e64 s[92:93], v236, 3
	v_cndmask_b32_e64 v237, v132, v128, s[78:79]
	v_cndmask_b32_e64 v238, v157, v156, s[78:79]
	v_sub_f32_e32 v237, v238, v237
	v_min_f32_e32 v237, 0, v237
	v_mul_f32_e32 v237, 0x3fb8aa3b, v237
	v_exp_f32_e32 v237, v237
	v_cndmask_b32_e64 v239, v124, v120, s[78:79]
	v_add_f32_e32 v240, v120, v124
	v_mul_f32_e32 v237, v239, v237
	v_cndmask_b32_e64 v237, v237, v240, s[86:87]
	v_mul_f32_e32 v245, v100, v237
	v_cndmask_b32_e64 v237, v133, v129, s[80:81]
	v_cndmask_b32_e64 v238, v157, v156, s[80:81]
	v_sub_f32_e32 v237, v238, v237
	v_min_f32_e32 v237, 0, v237
	v_mul_f32_e32 v237, 0x3fb8aa3b, v237
	v_exp_f32_e32 v237, v237
	v_cndmask_b32_e64 v239, v125, v121, s[80:81]
	v_add_f32_e32 v240, v121, v125
	v_mul_f32_e32 v237, v239, v237
	v_cndmask_b32_e64 v237, v237, v240, s[88:89]
	v_mul_f32_e32 v246, v101, v237
	v_cndmask_b32_e64 v237, v134, v130, s[82:83]
	v_cndmask_b32_e64 v238, v157, v156, s[82:83]
	v_sub_f32_e32 v237, v238, v237
	v_min_f32_e32 v237, 0, v237
	v_mul_f32_e32 v237, 0x3fb8aa3b, v237
	v_exp_f32_e32 v237, v237
	v_cndmask_b32_e64 v239, v126, v122, s[82:83]
	v_add_f32_e32 v240, v122, v126
	v_mul_f32_e32 v237, v239, v237
	v_cndmask_b32_e64 v237, v237, v240, s[90:91]
	v_mul_f32_e32 v247, v102, v237
	v_cndmask_b32_e64 v237, v135, v131, s[84:85]
	v_cndmask_b32_e64 v238, v157, v156, s[84:85]
	v_sub_f32_e32 v237, v238, v237
	v_min_f32_e32 v237, 0, v237
	v_mul_f32_e32 v237, 0x3fb8aa3b, v237
	v_exp_f32_e32 v237, v237
	v_cndmask_b32_e64 v239, v127, v123, s[84:85]
	v_add_f32_e32 v240, v123, v127
	v_mul_f32_e32 v237, v239, v237
	v_cndmask_b32_e64 v237, v237, v240, s[92:93]
	v_mul_f32_e32 v248, v103, v237
	v_cvt_pk_bf16_f32 v136, v241, v242
	v_cvt_pk_bf16_f32 v137, v243, v244
	v_cvt_pk_bf16_f32 v138, v245, v246
	v_cvt_pk_bf16_f32 v139, v247, v248
	s_waitcnt lgkmcnt(0)
	s_nop 1
	v_mfma_f32_16x16x32_bf16 v[16:19], v[136:139], v[140:143], v[16:19]
	v_mfma_f32_16x16x32_bf16 v[20:23], v[136:139], v[144:147], v[20:23]
	v_mfma_f32_16x16x32_bf16 v[24:27], v[136:139], v[148:151], v[24:27]
	v_mfma_f32_16x16x32_bf16 v[28:31], v[136:139], v[152:155], v[28:31]
	ds_read_b128 v[104:107], v168 offset:896
	ds_read_b128 v[108:111], v168 offset:2944
	ds_read_b128 v[112:115], v168 offset:4992
	ds_read_b128 v[116:119], v168 offset:7040
	ds_read_b128 v[120:123], v168 offset:960
	ds_read_b128 v[124:127], v168 offset:3008
	ds_read_b128 v[128:131], v168 offset:5056
	ds_read_b128 v[132:135], v168 offset:7104
	ds_read_b64_tr_b16 v[140:141], v166 offset:52352
	ds_read_b64_tr_b16 v[142:143], v166 offset:61056
	ds_read_b64_tr_b16 v[144:145], v166 offset:52384
	ds_read_b64_tr_b16 v[146:147], v166 offset:61088
	s_waitcnt lgkmcnt(4)
	v_subrev_u32_e32 v236, 96, v175
	v_cmp_gt_i32_e64 s[78:79], v236, 0
	v_cmp_gt_i32_e64 s[80:81], v236, 1
	v_cmp_gt_i32_e64 s[82:83], v236, 2
	v_cmp_gt_i32_e64 s[84:85], v236, 3
	v_cmp_eq_u32_e64 s[86:87], v236, 0
	v_cmp_eq_u32_e64 s[88:89], v236, 1
	v_cmp_eq_u32_e64 s[90:91], v236, 2
	v_cmp_eq_u32_e64 s[92:93], v236, 3
	v_cndmask_b32_e64 v237, v116, v112, s[78:79]
	v_cndmask_b32_e64 v238, v159, v158, s[78:79]
	v_sub_f32_e32 v237, v238, v237
	v_min_f32_e32 v237, 0, v237
	v_mul_f32_e32 v237, 0x3fb8aa3b, v237
	v_exp_f32_e32 v237, v237
	v_cndmask_b32_e64 v239, v108, v104, s[78:79]
	v_add_f32_e32 v240, v104, v108
	v_mul_f32_e32 v237, v239, v237
	v_cndmask_b32_e64 v237, v237, v240, s[86:87]
	v_mul_f32_e32 v241, v96, v237
	v_cndmask_b32_e64 v237, v117, v113, s[80:81]
	v_cndmask_b32_e64 v238, v159, v158, s[80:81]
	v_sub_f32_e32 v237, v238, v237
	v_min_f32_e32 v237, 0, v237
	v_mul_f32_e32 v237, 0x3fb8aa3b, v237
	v_exp_f32_e32 v237, v237
	v_cndmask_b32_e64 v239, v109, v105, s[80:81]
	v_add_f32_e32 v240, v105, v109
	v_mul_f32_e32 v237, v239, v237
	v_cndmask_b32_e64 v237, v237, v240, s[88:89]
	v_mul_f32_e32 v242, v97, v237
	v_cndmask_b32_e64 v237, v118, v114, s[82:83]
	v_cndmask_b32_e64 v238, v159, v158, s[82:83]
	v_sub_f32_e32 v237, v238, v237
	v_min_f32_e32 v237, 0, v237
	v_mul_f32_e32 v237, 0x3fb8aa3b, v237
	v_exp_f32_e32 v237, v237
	v_cndmask_b32_e64 v239, v110, v106, s[82:83]
	v_add_f32_e32 v240, v106, v110
	v_mul_f32_e32 v237, v239, v237
	v_cndmask_b32_e64 v237, v237, v240, s[90:91]
	v_mul_f32_e32 v243, v98, v237
	v_cndmask_b32_e64 v237, v119, v115, s[84:85]
	v_cndmask_b32_e64 v238, v159, v158, s[84:85]
	v_sub_f32_e32 v237, v238, v237
	v_min_f32_e32 v237, 0, v237
	v_mul_f32_e32 v237, 0x3fb8aa3b, v237
	v_exp_f32_e32 v237, v237
	v_cndmask_b32_e64 v239, v111, v107, s[84:85]
	v_add_f32_e32 v240, v107, v111
	v_mul_f32_e32 v237, v239, v237
	v_cndmask_b32_e64 v237, v237, v240, s[92:93]
	v_mul_f32_e32 v244, v99, v237
	ds_read_b64_tr_b16 v[148:149], v166 offset:52416
	ds_read_b64_tr_b16 v[150:151], v166 offset:61120
	ds_read_b64_tr_b16 v[152:153], v166 offset:52448
	ds_read_b64_tr_b16 v[154:155], v166 offset:61152
	v_subrev_u32_e32 v236, 112, v175
	v_cmp_gt_i32_e64 s[78:79], v236, 0
	v_cmp_gt_i32_e64 s[80:81], v236, 1
	v_cmp_gt_i32_e64 s[82:83], v236, 2
	v_cmp_gt_i32_e64 s[84:85], v236, 3
	v_cmp_eq_u32_e64 s[86:87], v236, 0
	v_cmp_eq_u32_e64 s[88:89], v236, 1
	v_cmp_eq_u32_e64 s[90:91], v236, 2
	v_cmp_eq_u32_e64 s[92:93], v236, 3
	v_cndmask_b32_e64 v237, v132, v128, s[78:79]
	v_cndmask_b32_e64 v238, v159, v158, s[78:79]
	v_sub_f32_e32 v237, v238, v237
	v_min_f32_e32 v237, 0, v237
	v_mul_f32_e32 v237, 0x3fb8aa3b, v237
	v_exp_f32_e32 v237, v237
	v_cndmask_b32_e64 v239, v124, v120, s[78:79]
	v_add_f32_e32 v240, v120, v124
	v_mul_f32_e32 v237, v239, v237
	v_cndmask_b32_e64 v237, v237, v240, s[86:87]
	v_mul_f32_e32 v245, v100, v237
	v_cndmask_b32_e64 v237, v133, v129, s[80:81]
	v_cndmask_b32_e64 v238, v159, v158, s[80:81]
	v_sub_f32_e32 v237, v238, v237
	v_min_f32_e32 v237, 0, v237
	v_mul_f32_e32 v237, 0x3fb8aa3b, v237
	v_exp_f32_e32 v237, v237
	v_cndmask_b32_e64 v239, v125, v121, s[80:81]
	v_add_f32_e32 v240, v121, v125
	v_mul_f32_e32 v237, v239, v237
	v_cndmask_b32_e64 v237, v237, v240, s[88:89]
	v_mul_f32_e32 v246, v101, v237
	v_cndmask_b32_e64 v237, v134, v130, s[82:83]
	v_cndmask_b32_e64 v238, v159, v158, s[82:83]
	v_sub_f32_e32 v237, v238, v237
	v_min_f32_e32 v237, 0, v237
	v_mul_f32_e32 v237, 0x3fb8aa3b, v237
	v_exp_f32_e32 v237, v237
	v_cndmask_b32_e64 v239, v126, v122, s[82:83]
	v_add_f32_e32 v240, v122, v126
	v_mul_f32_e32 v237, v239, v237
	v_cndmask_b32_e64 v237, v237, v240, s[90:91]
	v_mul_f32_e32 v247, v102, v237
	v_cndmask_b32_e64 v237, v135, v131, s[84:85]
	v_cndmask_b32_e64 v238, v159, v158, s[84:85]
	v_sub_f32_e32 v237, v238, v237
	v_min_f32_e32 v237, 0, v237
	v_mul_f32_e32 v237, 0x3fb8aa3b, v237
	v_exp_f32_e32 v237, v237
	v_cndmask_b32_e64 v239, v127, v123, s[84:85]
	v_add_f32_e32 v240, v123, v127
	v_mul_f32_e32 v237, v239, v237
	v_cndmask_b32_e64 v237, v237, v240, s[92:93]
	v_mul_f32_e32 v248, v103, v237
	v_cvt_pk_bf16_f32 v136, v241, v242
	v_cvt_pk_bf16_f32 v137, v243, v244
	v_cvt_pk_bf16_f32 v138, v245, v246
	v_cvt_pk_bf16_f32 v139, v247, v248
	s_waitcnt lgkmcnt(0)
	s_nop 1
	v_mfma_f32_16x16x32_bf16 v[32:35], v[136:139], v[140:143], v[32:35]
	v_mfma_f32_16x16x32_bf16 v[36:39], v[136:139], v[144:147], v[36:39]
	v_mfma_f32_16x16x32_bf16 v[40:43], v[136:139], v[148:151], v[40:43]
	v_mfma_f32_16x16x32_bf16 v[44:47], v[136:139], v[152:155], v[44:47]
	s_mov_b32 s52, s42
	s_mov_b32 s53, s43
	global_load_dwordx4 v[140:143], v170, s[52:53] offset:128
	global_load_dwordx4 v[144:147], v171, s[52:53] offset:128
	global_load_dwordx4 v[148:151], v172, s[52:53] offset:128
	global_load_dwordx4 v[152:155], v173, s[52:53] offset:128
	s_mov_b32 s52, s42
	s_mov_b32 s53, s43
	global_load_dwordx4 v[104:107], v170, s[52:53] offset:192
	global_load_dwordx4 v[108:111], v171, s[52:53] offset:192
	global_load_dwordx4 v[112:115], v172, s[52:53] offset:192
	global_load_dwordx4 v[116:119], v173, s[52:53] offset:192
	s_add_u32 s52, s42, 0x4000
	s_addc_u32 s53, s43, 0
	global_load_dwordx4 v[120:123], v170, s[52:53] offset:0
	global_load_dwordx4 v[124:127], v171, s[52:53] offset:0
	global_load_dwordx4 v[128:131], v172, s[52:53] offset:0
	global_load_dwordx4 v[132:135], v173, s[52:53] offset:0
	v_mul_f32_e32 v236, 0x3fb8aa3b, v156
	v_exp_f32_e32 v236, v236
	s_nop 0
	v_lshlrev_b32_e32 v237, 16, v48
	v_and_b32_e32 v238, 0xffff0000, v48
	v_mul_f32_e32 v237, v236, v237
	v_mul_f32_e32 v238, v236, v238
	v_cvt_pk_bf16_f32 v136, v237, v238
	v_lshlrev_b32_e32 v237, 16, v49
	v_and_b32_e32 v238, 0xffff0000, v49
	v_mul_f32_e32 v237, v236, v237
	v_mul_f32_e32 v238, v236, v238
	v_cvt_pk_bf16_f32 v137, v237, v238
	v_lshlrev_b32_e32 v237, 16, v50
	v_and_b32_e32 v238, 0xffff0000, v50
	v_mul_f32_e32 v237, v236, v237
	v_mul_f32_e32 v238, v236, v238
	v_cvt_pk_bf16_f32 v138, v237, v238
	v_lshlrev_b32_e32 v237, 16, v51
	v_and_b32_e32 v238, 0xffff0000, v51
	v_mul_f32_e32 v237, v236, v237
	v_mul_f32_e32 v238, v236, v238
	v_cvt_pk_bf16_f32 v139, v237, v238
	s_waitcnt vmcnt(16)
	s_nop 0
	v_mfma_f32_16x16x32_bf16 v[16:19], v[136:139], v[64:67], v[16:19]
	v_mfma_f32_16x16x32_bf16 v[20:23], v[136:139], v[68:71], v[20:23]
	v_mfma_f32_16x16x32_bf16 v[24:27], v[136:139], v[72:75], v[24:27]
	v_mfma_f32_16x16x32_bf16 v[28:31], v[136:139], v[76:79], v[28:31]
	s_add_u32 s52, s42, 0x4000
	s_addc_u32 s53, s43, 0
	global_load_dwordx4 v[64:67], v170, s[52:53] offset:64
	global_load_dwordx4 v[68:71], v171, s[52:53] offset:64
	global_load_dwordx4 v[72:75], v172, s[52:53] offset:64
	global_load_dwordx4 v[76:79], v173, s[52:53] offset:64
	v_lshlrev_b32_e32 v237, 16, v52
	v_and_b32_e32 v238, 0xffff0000, v52
	v_mul_f32_e32 v237, v236, v237
	v_mul_f32_e32 v238, v236, v238
	v_cvt_pk_bf16_f32 v136, v237, v238
	v_lshlrev_b32_e32 v237, 16, v53
	v_and_b32_e32 v238, 0xffff0000, v53
	v_mul_f32_e32 v237, v236, v237
	v_mul_f32_e32 v238, v236, v238
	v_cvt_pk_bf16_f32 v137, v237, v238
	v_lshlrev_b32_e32 v237, 16, v54
	v_and_b32_e32 v238, 0xffff0000, v54
	v_mul_f32_e32 v237, v236, v237
	v_mul_f32_e32 v238, v236, v238
	v_cvt_pk_bf16_f32 v138, v237, v238
	v_lshlrev_b32_e32 v237, 16, v55
	v_and_b32_e32 v238, 0xffff0000, v55
	v_mul_f32_e32 v237, v236, v237
	v_mul_f32_e32 v238, v236, v238
	v_cvt_pk_bf16_f32 v139, v237, v238
	s_waitcnt vmcnt(16)
	s_nop 0
	v_mfma_f32_16x16x32_bf16 v[16:19], v[136:139], v[80:83], v[16:19]
	v_mfma_f32_16x16x32_bf16 v[20:23], v[136:139], v[84:87], v[20:23]
	v_mfma_f32_16x16x32_bf16 v[24:27], v[136:139], v[88:91], v[24:27]
	v_mfma_f32_16x16x32_bf16 v[28:31], v[136:139], v[92:95], v[28:31]
	s_add_u32 s52, s42, 0x4000
	s_addc_u32 s53, s43, 0
	global_load_dwordx4 v[80:83], v170, s[52:53] offset:128
	global_load_dwordx4 v[84:87], v171, s[52:53] offset:128
	global_load_dwordx4 v[88:91], v172, s[52:53] offset:128
	global_load_dwordx4 v[92:95], v173, s[52:53] offset:128
	v_lshlrev_b32_e32 v237, 16, v56
	v_and_b32_e32 v238, 0xffff0000, v56
	v_mul_f32_e32 v237, v236, v237
	v_mul_f32_e32 v238, v236, v238
	v_cvt_pk_bf16_f32 v136, v237, v238
	v_lshlrev_b32_e32 v237, 16, v57
	v_and_b32_e32 v238, 0xffff0000, v57
	v_mul_f32_e32 v237, v236, v237
	v_mul_f32_e32 v238, v236, v238
	v_cvt_pk_bf16_f32 v137, v237, v238
	v_lshlrev_b32_e32 v237, 16, v58
	v_and_b32_e32 v238, 0xffff0000, v58
	v_mul_f32_e32 v237, v236, v237
	v_mul_f32_e32 v238, v236, v238
	v_cvt_pk_bf16_f32 v138, v237, v238
	v_lshlrev_b32_e32 v237, 16, v59
	v_and_b32_e32 v238, 0xffff0000, v59
	v_mul_f32_e32 v237, v236, v237
	v_mul_f32_e32 v238, v236, v238
	v_cvt_pk_bf16_f32 v139, v237, v238
	s_waitcnt vmcnt(16)
	s_nop 0
	v_mfma_f32_16x16x32_bf16 v[16:19], v[136:139], v[140:143], v[16:19]
	v_mfma_f32_16x16x32_bf16 v[20:23], v[136:139], v[144:147], v[20:23]
	v_mfma_f32_16x16x32_bf16 v[24:27], v[136:139], v[148:151], v[24:27]
	v_mfma_f32_16x16x32_bf16 v[28:31], v[136:139], v[152:155], v[28:31]
	s_add_u32 s52, s42, 0x4000
	s_addc_u32 s53, s43, 0
	global_load_dwordx4 v[140:143], v170, s[52:53] offset:192
	global_load_dwordx4 v[144:147], v171, s[52:53] offset:192
	global_load_dwordx4 v[148:151], v172, s[52:53] offset:192
	global_load_dwordx4 v[152:155], v173, s[52:53] offset:192
	v_lshlrev_b32_e32 v237, 16, v60
	v_and_b32_e32 v238, 0xffff0000, v60
	v_mul_f32_e32 v237, v236, v237
	v_mul_f32_e32 v238, v236, v238
	v_cvt_pk_bf16_f32 v136, v237, v238
	v_lshlrev_b32_e32 v237, 16, v61
	v_and_b32_e32 v238, 0xffff0000, v61
	v_mul_f32_e32 v237, v236, v237
	v_mul_f32_e32 v238, v236, v238
	v_cvt_pk_bf16_f32 v137, v237, v238
	v_lshlrev_b32_e32 v237, 16, v62
	v_and_b32_e32 v238, 0xffff0000, v62
	v_mul_f32_e32 v237, v236, v237
	v_mul_f32_e32 v238, v236, v238
	v_cvt_pk_bf16_f32 v138, v237, v238
	v_lshlrev_b32_e32 v237, 16, v63
	v_and_b32_e32 v238, 0xffff0000, v63
	v_mul_f32_e32 v237, v236, v237
	v_mul_f32_e32 v238, v236, v238
	v_cvt_pk_bf16_f32 v139, v237, v238
	s_waitcnt vmcnt(16)
	s_nop 0
	v_mfma_f32_16x16x32_bf16 v[16:19], v[136:139], v[104:107], v[16:19]
	v_mfma_f32_16x16x32_bf16 v[20:23], v[136:139], v[108:111], v[20:23]
	v_mfma_f32_16x16x32_bf16 v[24:27], v[136:139], v[112:115], v[24:27]
	v_mfma_f32_16x16x32_bf16 v[28:31], v[136:139], v[116:119], v[28:31]
	s_add_u32 s52, s42, 0x8000
	s_addc_u32 s53, s43, 0
	global_load_dwordx4 v[104:107], v170, s[52:53] offset:0
	global_load_dwordx4 v[108:111], v171, s[52:53] offset:0
	global_load_dwordx4 v[112:115], v172, s[52:53] offset:0
	global_load_dwordx4 v[116:119], v173, s[52:53] offset:0
	v_mul_f32_e32 v236, 0x3fb8aa3b, v157
	v_exp_f32_e32 v236, v236
	s_nop 0
	v_lshlrev_b32_e32 v237, 16, v48
	v_and_b32_e32 v238, 0xffff0000, v48
	v_mul_f32_e32 v237, v236, v237
	v_mul_f32_e32 v238, v236, v238
	v_cvt_pk_bf16_f32 v136, v237, v238
	v_lshlrev_b32_e32 v237, 16, v49
	v_and_b32_e32 v238, 0xffff0000, v49
	v_mul_f32_e32 v237, v236, v237
	v_mul_f32_e32 v238, v236, v238
	v_cvt_pk_bf16_f32 v137, v237, v238
	v_lshlrev_b32_e32 v237, 16, v50
	v_and_b32_e32 v238, 0xffff0000, v50
	v_mul_f32_e32 v237, v236, v237
	v_mul_f32_e32 v238, v236, v238
	v_cvt_pk_bf16_f32 v138, v237, v238
	v_lshlrev_b32_e32 v237, 16, v51
	v_and_b32_e32 v238, 0xffff0000, v51
	v_mul_f32_e32 v237, v236, v237
	v_mul_f32_e32 v238, v236, v238
	v_cvt_pk_bf16_f32 v139, v237, v238
	s_waitcnt vmcnt(16)
	s_nop 0
	v_mfma_f32_16x16x32_bf16 v[16:19], v[136:139], v[120:123], v[16:19]
	v_mfma_f32_16x16x32_bf16 v[20:23], v[136:139], v[124:127], v[20:23]
	v_mfma_f32_16x16x32_bf16 v[24:27], v[136:139], v[128:131], v[24:27]
	v_mfma_f32_16x16x32_bf16 v[28:31], v[136:139], v[132:135], v[28:31]
	s_add_u32 s52, s42, 0x8000
	s_addc_u32 s53, s43, 0
	global_load_dwordx4 v[120:123], v170, s[52:53] offset:64
	global_load_dwordx4 v[124:127], v171, s[52:53] offset:64
	global_load_dwordx4 v[128:131], v172, s[52:53] offset:64
	global_load_dwordx4 v[132:135], v173, s[52:53] offset:64
	v_lshlrev_b32_e32 v237, 16, v52
	v_and_b32_e32 v238, 0xffff0000, v52
	v_mul_f32_e32 v237, v236, v237
	v_mul_f32_e32 v238, v236, v238
	v_cvt_pk_bf16_f32 v136, v237, v238
	v_lshlrev_b32_e32 v237, 16, v53
	v_and_b32_e32 v238, 0xffff0000, v53
	v_mul_f32_e32 v237, v236, v237
	v_mul_f32_e32 v238, v236, v238
	v_cvt_pk_bf16_f32 v137, v237, v238
	v_lshlrev_b32_e32 v237, 16, v54
	v_and_b32_e32 v238, 0xffff0000, v54
	v_mul_f32_e32 v237, v236, v237
	v_mul_f32_e32 v238, v236, v238
	v_cvt_pk_bf16_f32 v138, v237, v238
	v_lshlrev_b32_e32 v237, 16, v55
	v_and_b32_e32 v238, 0xffff0000, v55
	v_mul_f32_e32 v237, v236, v237
	v_mul_f32_e32 v238, v236, v238
	v_cvt_pk_bf16_f32 v139, v237, v238
	s_waitcnt vmcnt(16)
	s_nop 0
	v_mfma_f32_16x16x32_bf16 v[16:19], v[136:139], v[64:67], v[16:19]
	v_mfma_f32_16x16x32_bf16 v[20:23], v[136:139], v[68:71], v[20:23]
	v_mfma_f32_16x16x32_bf16 v[24:27], v[136:139], v[72:75], v[24:27]
	v_mfma_f32_16x16x32_bf16 v[28:31], v[136:139], v[76:79], v[28:31]
	s_add_u32 s52, s42, 0x8000
	s_addc_u32 s53, s43, 0
	global_load_dwordx4 v[64:67], v170, s[52:53] offset:128
	global_load_dwordx4 v[68:71], v171, s[52:53] offset:128
	global_load_dwordx4 v[72:75], v172, s[52:53] offset:128
	global_load_dwordx4 v[76:79], v173, s[52:53] offset:128
	v_lshlrev_b32_e32 v237, 16, v56
	v_and_b32_e32 v238, 0xffff0000, v56
	v_mul_f32_e32 v237, v236, v237
	v_mul_f32_e32 v238, v236, v238
	v_cvt_pk_bf16_f32 v136, v237, v238
	v_lshlrev_b32_e32 v237, 16, v57
	v_and_b32_e32 v238, 0xffff0000, v57
	v_mul_f32_e32 v237, v236, v237
	v_mul_f32_e32 v238, v236, v238
	v_cvt_pk_bf16_f32 v137, v237, v238
	v_lshlrev_b32_e32 v237, 16, v58
	v_and_b32_e32 v238, 0xffff0000, v58
	v_mul_f32_e32 v237, v236, v237
	v_mul_f32_e32 v238, v236, v238
	v_cvt_pk_bf16_f32 v138, v237, v238
	v_lshlrev_b32_e32 v237, 16, v59
	v_and_b32_e32 v238, 0xffff0000, v59
	v_mul_f32_e32 v237, v236, v237
	v_mul_f32_e32 v238, v236, v238
	v_cvt_pk_bf16_f32 v139, v237, v238
	s_waitcnt vmcnt(16)
	s_nop 0
	v_mfma_f32_16x16x32_bf16 v[16:19], v[136:139], v[80:83], v[16:19]
	v_mfma_f32_16x16x32_bf16 v[20:23], v[136:139], v[84:87], v[20:23]
	v_mfma_f32_16x16x32_bf16 v[24:27], v[136:139], v[88:91], v[24:27]
	v_mfma_f32_16x16x32_bf16 v[28:31], v[136:139], v[92:95], v[28:31]
	s_add_u32 s52, s42, 0x8000
	s_addc_u32 s53, s43, 0
	global_load_dwordx4 v[80:83], v170, s[52:53] offset:192
	global_load_dwordx4 v[84:87], v171, s[52:53] offset:192
	global_load_dwordx4 v[88:91], v172, s[52:53] offset:192
	global_load_dwordx4 v[92:95], v173, s[52:53] offset:192
	v_lshlrev_b32_e32 v237, 16, v60
	v_and_b32_e32 v238, 0xffff0000, v60
	v_mul_f32_e32 v237, v236, v237
	v_mul_f32_e32 v238, v236, v238
	v_cvt_pk_bf16_f32 v136, v237, v238
	v_lshlrev_b32_e32 v237, 16, v61
	v_and_b32_e32 v238, 0xffff0000, v61
	v_mul_f32_e32 v237, v236, v237
	v_mul_f32_e32 v238, v236, v238
	v_cvt_pk_bf16_f32 v137, v237, v238
	v_lshlrev_b32_e32 v237, 16, v62
	v_and_b32_e32 v238, 0xffff0000, v62
	v_mul_f32_e32 v237, v236, v237
	v_mul_f32_e32 v238, v236, v238
	v_cvt_pk_bf16_f32 v138, v237, v238
	v_lshlrev_b32_e32 v237, 16, v63
	v_and_b32_e32 v238, 0xffff0000, v63
	v_mul_f32_e32 v237, v236, v237
	v_mul_f32_e32 v238, v236, v238
	v_cvt_pk_bf16_f32 v139, v237, v238
	s_waitcnt vmcnt(16)
	s_nop 0
	v_mfma_f32_16x16x32_bf16 v[16:19], v[136:139], v[140:143], v[16:19]
	v_mfma_f32_16x16x32_bf16 v[20:23], v[136:139], v[144:147], v[20:23]
	v_mfma_f32_16x16x32_bf16 v[24:27], v[136:139], v[148:151], v[24:27]
	v_mfma_f32_16x16x32_bf16 v[28:31], v[136:139], v[152:155], v[28:31]
	s_add_u32 s52, s42, 0xc000
	s_addc_u32 s53, s43, 0
	global_load_dwordx4 v[140:143], v170, s[52:53] offset:0
	global_load_dwordx4 v[144:147], v171, s[52:53] offset:0
	global_load_dwordx4 v[148:151], v172, s[52:53] offset:0
	global_load_dwordx4 v[152:155], v173, s[52:53] offset:0
	v_mul_f32_e32 v236, 0x3fb8aa3b, v158
	v_exp_f32_e32 v236, v236
	s_nop 0
	v_lshlrev_b32_e32 v237, 16, v48
	v_and_b32_e32 v238, 0xffff0000, v48
	v_mul_f32_e32 v237, v236, v237
	v_mul_f32_e32 v238, v236, v238
	v_cvt_pk_bf16_f32 v136, v237, v238
	v_lshlrev_b32_e32 v237, 16, v49
	v_and_b32_e32 v238, 0xffff0000, v49
	v_mul_f32_e32 v237, v236, v237
	v_mul_f32_e32 v238, v236, v238
	v_cvt_pk_bf16_f32 v137, v237, v238
	v_lshlrev_b32_e32 v237, 16, v50
	v_and_b32_e32 v238, 0xffff0000, v50
	v_mul_f32_e32 v237, v236, v237
	v_mul_f32_e32 v238, v236, v238
	v_cvt_pk_bf16_f32 v138, v237, v238
	v_lshlrev_b32_e32 v237, 16, v51
	v_and_b32_e32 v238, 0xffff0000, v51
	v_mul_f32_e32 v237, v236, v237
	v_mul_f32_e32 v238, v236, v238
	v_cvt_pk_bf16_f32 v139, v237, v238
	s_waitcnt vmcnt(16)
	s_nop 0
	v_mfma_f32_16x16x32_bf16 v[32:35], v[136:139], v[104:107], v[32:35]
	v_mfma_f32_16x16x32_bf16 v[36:39], v[136:139], v[108:111], v[36:39]
	v_mfma_f32_16x16x32_bf16 v[40:43], v[136:139], v[112:115], v[40:43]
	v_mfma_f32_16x16x32_bf16 v[44:47], v[136:139], v[116:119], v[44:47]
	s_add_u32 s52, s42, 0xc000
	s_addc_u32 s53, s43, 0
	global_load_dwordx4 v[104:107], v170, s[52:53] offset:64
	global_load_dwordx4 v[108:111], v171, s[52:53] offset:64
	global_load_dwordx4 v[112:115], v172, s[52:53] offset:64
	global_load_dwordx4 v[116:119], v173, s[52:53] offset:64
	v_lshlrev_b32_e32 v237, 16, v52
	v_and_b32_e32 v238, 0xffff0000, v52
	v_mul_f32_e32 v237, v236, v237
	v_mul_f32_e32 v238, v236, v238
	v_cvt_pk_bf16_f32 v136, v237, v238
	v_lshlrev_b32_e32 v237, 16, v53
	v_and_b32_e32 v238, 0xffff0000, v53
	v_mul_f32_e32 v237, v236, v237
	v_mul_f32_e32 v238, v236, v238
	v_cvt_pk_bf16_f32 v137, v237, v238
	v_lshlrev_b32_e32 v237, 16, v54
	v_and_b32_e32 v238, 0xffff0000, v54
	v_mul_f32_e32 v237, v236, v237
	v_mul_f32_e32 v238, v236, v238
	v_cvt_pk_bf16_f32 v138, v237, v238
	v_lshlrev_b32_e32 v237, 16, v55
	v_and_b32_e32 v238, 0xffff0000, v55
	v_mul_f32_e32 v237, v236, v237
	v_mul_f32_e32 v238, v236, v238
	v_cvt_pk_bf16_f32 v139, v237, v238
	s_waitcnt vmcnt(16)
	s_nop 0
	v_mfma_f32_16x16x32_bf16 v[32:35], v[136:139], v[120:123], v[32:35]
	v_mfma_f32_16x16x32_bf16 v[36:39], v[136:139], v[124:127], v[36:39]
	v_mfma_f32_16x16x32_bf16 v[40:43], v[136:139], v[128:131], v[40:43]
	v_mfma_f32_16x16x32_bf16 v[44:47], v[136:139], v[132:135], v[44:47]
	s_add_u32 s52, s42, 0xc000
	s_addc_u32 s53, s43, 0
	global_load_dwordx4 v[120:123], v170, s[52:53] offset:128
	global_load_dwordx4 v[124:127], v171, s[52:53] offset:128
	global_load_dwordx4 v[128:131], v172, s[52:53] offset:128
	global_load_dwordx4 v[132:135], v173, s[52:53] offset:128
	v_lshlrev_b32_e32 v237, 16, v56
	v_and_b32_e32 v238, 0xffff0000, v56
	v_mul_f32_e32 v237, v236, v237
	v_mul_f32_e32 v238, v236, v238
	v_cvt_pk_bf16_f32 v136, v237, v238
	v_lshlrev_b32_e32 v237, 16, v57
	v_and_b32_e32 v238, 0xffff0000, v57
	v_mul_f32_e32 v237, v236, v237
	v_mul_f32_e32 v238, v236, v238
	v_cvt_pk_bf16_f32 v137, v237, v238
	v_lshlrev_b32_e32 v237, 16, v58
	v_and_b32_e32 v238, 0xffff0000, v58
	v_mul_f32_e32 v237, v236, v237
	v_mul_f32_e32 v238, v236, v238
	v_cvt_pk_bf16_f32 v138, v237, v238
	v_lshlrev_b32_e32 v237, 16, v59
	v_and_b32_e32 v238, 0xffff0000, v59
	v_mul_f32_e32 v237, v236, v237
	v_mul_f32_e32 v238, v236, v238
	v_cvt_pk_bf16_f32 v139, v237, v238
	s_waitcnt vmcnt(16)
	s_nop 0
	v_mfma_f32_16x16x32_bf16 v[32:35], v[136:139], v[64:67], v[32:35]
	v_mfma_f32_16x16x32_bf16 v[36:39], v[136:139], v[68:71], v[36:39]
	v_mfma_f32_16x16x32_bf16 v[40:43], v[136:139], v[72:75], v[40:43]
	v_mfma_f32_16x16x32_bf16 v[44:47], v[136:139], v[76:79], v[44:47]
	s_add_u32 s52, s42, 0xc000
	s_addc_u32 s53, s43, 0
	global_load_dwordx4 v[64:67], v170, s[52:53] offset:192
	global_load_dwordx4 v[68:71], v171, s[52:53] offset:192
	global_load_dwordx4 v[72:75], v172, s[52:53] offset:192
	global_load_dwordx4 v[76:79], v173, s[52:53] offset:192
	v_lshlrev_b32_e32 v237, 16, v60
	v_and_b32_e32 v238, 0xffff0000, v60
	v_mul_f32_e32 v237, v236, v237
	v_mul_f32_e32 v238, v236, v238
	v_cvt_pk_bf16_f32 v136, v237, v238
	v_lshlrev_b32_e32 v237, 16, v61
	v_and_b32_e32 v238, 0xffff0000, v61
	v_mul_f32_e32 v237, v236, v237
	v_mul_f32_e32 v238, v236, v238
	v_cvt_pk_bf16_f32 v137, v237, v238
	v_lshlrev_b32_e32 v237, 16, v62
	v_and_b32_e32 v238, 0xffff0000, v62
	v_mul_f32_e32 v237, v236, v237
	v_mul_f32_e32 v238, v236, v238
	v_cvt_pk_bf16_f32 v138, v237, v238
	v_lshlrev_b32_e32 v237, 16, v63
	v_and_b32_e32 v238, 0xffff0000, v63
	v_mul_f32_e32 v237, v236, v237
	v_mul_f32_e32 v238, v236, v238
	v_cvt_pk_bf16_f32 v139, v237, v238
	s_waitcnt vmcnt(16)
	s_nop 0
	v_mfma_f32_16x16x32_bf16 v[32:35], v[136:139], v[80:83], v[32:35]
	v_mfma_f32_16x16x32_bf16 v[36:39], v[136:139], v[84:87], v[36:39]
	v_mfma_f32_16x16x32_bf16 v[40:43], v[136:139], v[88:91], v[40:43]
	v_mfma_f32_16x16x32_bf16 v[44:47], v[136:139], v[92:95], v[44:47]
	v_mul_f32_e32 v236, 0x3fb8aa3b, v159
	v_exp_f32_e32 v236, v236
	s_nop 0
	v_lshlrev_b32_e32 v237, 16, v48
	v_and_b32_e32 v238, 0xffff0000, v48
	v_mul_f32_e32 v237, v236, v237
	v_mul_f32_e32 v238, v236, v238
	v_cvt_pk_bf16_f32 v136, v237, v238
	v_lshlrev_b32_e32 v237, 16, v49
	v_and_b32_e32 v238, 0xffff0000, v49
	v_mul_f32_e32 v237, v236, v237
	v_mul_f32_e32 v238, v236, v238
	v_cvt_pk_bf16_f32 v137, v237, v238
	v_lshlrev_b32_e32 v237, 16, v50
	v_and_b32_e32 v238, 0xffff0000, v50
	v_mul_f32_e32 v237, v236, v237
	v_mul_f32_e32 v238, v236, v238
	v_cvt_pk_bf16_f32 v138, v237, v238
	v_lshlrev_b32_e32 v237, 16, v51
	v_and_b32_e32 v238, 0xffff0000, v51
	v_mul_f32_e32 v237, v236, v237
	v_mul_f32_e32 v238, v236, v238
	v_cvt_pk_bf16_f32 v139, v237, v238
	s_waitcnt vmcnt(12)
	s_nop 0
	v_mfma_f32_16x16x32_bf16 v[32:35], v[136:139], v[140:143], v[32:35]
	v_mfma_f32_16x16x32_bf16 v[36:39], v[136:139], v[144:147], v[36:39]
	v_mfma_f32_16x16x32_bf16 v[40:43], v[136:139], v[148:151], v[40:43]
	v_mfma_f32_16x16x32_bf16 v[44:47], v[136:139], v[152:155], v[44:47]
	v_lshlrev_b32_e32 v237, 16, v52
	v_and_b32_e32 v238, 0xffff0000, v52
	v_mul_f32_e32 v237, v236, v237
	v_mul_f32_e32 v238, v236, v238
	v_cvt_pk_bf16_f32 v136, v237, v238
	v_lshlrev_b32_e32 v237, 16, v53
	v_and_b32_e32 v238, 0xffff0000, v53
	v_mul_f32_e32 v237, v236, v237
	v_mul_f32_e32 v238, v236, v238
	v_cvt_pk_bf16_f32 v137, v237, v238
	v_lshlrev_b32_e32 v237, 16, v54
	v_and_b32_e32 v238, 0xffff0000, v54
	v_mul_f32_e32 v237, v236, v237
	v_mul_f32_e32 v238, v236, v238
	v_cvt_pk_bf16_f32 v138, v237, v238
	v_lshlrev_b32_e32 v237, 16, v55
	v_and_b32_e32 v238, 0xffff0000, v55
	v_mul_f32_e32 v237, v236, v237
	v_mul_f32_e32 v238, v236, v238
	v_cvt_pk_bf16_f32 v139, v237, v238
	s_waitcnt vmcnt(8)
	s_nop 0
	v_mfma_f32_16x16x32_bf16 v[32:35], v[136:139], v[104:107], v[32:35]
	v_mfma_f32_16x16x32_bf16 v[36:39], v[136:139], v[108:111], v[36:39]
	v_mfma_f32_16x16x32_bf16 v[40:43], v[136:139], v[112:115], v[40:43]
	v_mfma_f32_16x16x32_bf16 v[44:47], v[136:139], v[116:119], v[44:47]
	v_lshlrev_b32_e32 v237, 16, v56
	v_and_b32_e32 v238, 0xffff0000, v56
	v_mul_f32_e32 v237, v236, v237
	v_mul_f32_e32 v238, v236, v238
	v_cvt_pk_bf16_f32 v136, v237, v238
	v_lshlrev_b32_e32 v237, 16, v57
	v_and_b32_e32 v238, 0xffff0000, v57
	v_mul_f32_e32 v237, v236, v237
	v_mul_f32_e32 v238, v236, v238
	v_cvt_pk_bf16_f32 v137, v237, v238
	v_lshlrev_b32_e32 v237, 16, v58
	v_and_b32_e32 v238, 0xffff0000, v58
	v_mul_f32_e32 v237, v236, v237
	v_mul_f32_e32 v238, v236, v238
	v_cvt_pk_bf16_f32 v138, v237, v238
	v_lshlrev_b32_e32 v237, 16, v59
	v_and_b32_e32 v238, 0xffff0000, v59
	v_mul_f32_e32 v237, v236, v237
	v_mul_f32_e32 v238, v236, v238
	v_cvt_pk_bf16_f32 v139, v237, v238
	s_waitcnt vmcnt(4)
	s_nop 0
	v_mfma_f32_16x16x32_bf16 v[32:35], v[136:139], v[120:123], v[32:35]
	v_mfma_f32_16x16x32_bf16 v[36:39], v[136:139], v[124:127], v[36:39]
	v_mfma_f32_16x16x32_bf16 v[40:43], v[136:139], v[128:131], v[40:43]
	v_mfma_f32_16x16x32_bf16 v[44:47], v[136:139], v[132:135], v[44:47]
	v_lshlrev_b32_e32 v237, 16, v60
	v_and_b32_e32 v238, 0xffff0000, v60
	v_mul_f32_e32 v237, v236, v237
	v_mul_f32_e32 v238, v236, v238
	v_cvt_pk_bf16_f32 v136, v237, v238
	v_lshlrev_b32_e32 v237, 16, v61
	v_and_b32_e32 v238, 0xffff0000, v61
	v_mul_f32_e32 v237, v236, v237
	v_mul_f32_e32 v238, v236, v238
	v_cvt_pk_bf16_f32 v137, v237, v238
	v_lshlrev_b32_e32 v237, 16, v62
	v_and_b32_e32 v238, 0xffff0000, v62
	v_mul_f32_e32 v237, v236, v237
	v_mul_f32_e32 v238, v236, v238
	v_cvt_pk_bf16_f32 v138, v237, v238
	v_lshlrev_b32_e32 v237, 16, v63
	v_and_b32_e32 v238, 0xffff0000, v63
	v_mul_f32_e32 v237, v236, v237
	v_mul_f32_e32 v238, v236, v238
	v_cvt_pk_bf16_f32 v139, v237, v238
	s_waitcnt vmcnt(0)
	s_nop 0
	v_mfma_f32_16x16x32_bf16 v[32:35], v[136:139], v[64:67], v[32:35]
	v_mfma_f32_16x16x32_bf16 v[36:39], v[136:139], v[68:71], v[36:39]
	v_mfma_f32_16x16x32_bf16 v[40:43], v[136:139], v[72:75], v[40:43]
	v_mfma_f32_16x16x32_bf16 v[44:47], v[136:139], v[76:79], v[44:47]
	global_load_dwordx4 v[48:51], v177, s[40:41] offset:256
	global_load_dwordx4 v[52:55], v177, s[40:41] offset:320
	global_load_dwordx4 v[56:59], v177, s[40:41] offset:384
	global_load_dwordx4 v[60:63], v177, s[40:41] offset:448
	s_mov_b32 s52, s40
	s_mov_b32 s53, s41
	global_load_dwordx4 v[64:67], v169, s[52:53] offset:256
	global_load_dwordx4 v[68:71], v169, s[52:53] offset:320
	global_load_dwordx4 v[72:75], v169, s[52:53] offset:384
	global_load_dwordx4 v[76:79], v169, s[52:53] offset:448
	s_add_u32 s52, s40, 0x6000
	s_addc_u32 s53, s41, 0
	global_load_dwordx4 v[80:83], v169, s[52:53] offset:256
	global_load_dwordx4 v[84:87], v169, s[52:53] offset:320
	global_load_dwordx4 v[88:91], v169, s[52:53] offset:384
	global_load_dwordx4 v[92:95], v169, s[52:53] offset:448
	s_nop 7
	ds_read_b64_tr_b16 v[140:141], v174 offset:0
	ds_read_b64_tr_b16 v[148:149], v227 offset:0
	ds_read_b64_tr_b16 v[142:143], v174 offset:32
	ds_read_b64_tr_b16 v[150:151], v227 offset:32
	ds_read_b64_tr_b16 v[144:145], v174 offset:64
	ds_read_b64_tr_b16 v[152:153], v227 offset:64
	ds_read_b64_tr_b16 v[146:147], v174 offset:96
	ds_read_b64_tr_b16 v[154:155], v227 offset:96
	s_waitcnt lgkmcnt(6)
	v_lshlrev_b32_e32 v236, 16, v140
	v_lshlrev_b32_e32 v237, 16, v148
	v_fma_f32 v238, s60, v236, v16
	v_mul_f32_e32 v239, 0xbfb8aa3b, v237
	v_exp_f32_e32 v239, v239
	s_nop 0
	v_add_f32_e32 v239, 1.0, v239
	v_div_scale_f32 v240, s[0:1], v239, v239, v237
	v_rcp_f32_e32 v241, v240
	s_nop 0
	v_fma_f32 v242, -v240, v241, 1.0
	v_fmac_f32_e32 v241, v242, v241
	v_div_scale_f32 v242, vcc, v237, v239, v237
	v_mul_f32_e32 v243, v242, v241
	v_fma_f32 v244, -v240, v243, v242
	v_fmac_f32_e32 v243, v244, v241
	v_fma_f32 v240, -v240, v243, v242
	v_div_fmas_f32 v240, v240, v241, v243
	v_div_fixup_f32 v240, v240, v239, v237
	v_mul_f32_e32 v246, v238, v240
	v_fmac_f32_e32 v228, v246, v246
	v_and_b32_e32 v236, 0xffff0000, v140
	v_and_b32_e32 v237, 0xffff0000, v148
	v_fma_f32 v238, s60, v236, v17
	v_mul_f32_e32 v239, 0xbfb8aa3b, v237
	v_exp_f32_e32 v239, v239
	s_nop 0
	v_add_f32_e32 v239, 1.0, v239
	v_div_scale_f32 v240, s[0:1], v239, v239, v237
	v_rcp_f32_e32 v241, v240
	s_nop 0
	v_fma_f32 v242, -v240, v241, 1.0
	v_fmac_f32_e32 v241, v242, v241
	v_div_scale_f32 v242, vcc, v237, v239, v237
	v_mul_f32_e32 v243, v242, v241
	v_fma_f32 v244, -v240, v243, v242
	v_fmac_f32_e32 v243, v244, v241
	v_fma_f32 v240, -v240, v243, v242
	v_div_fmas_f32 v240, v240, v241, v243
	v_div_fixup_f32 v240, v240, v239, v237
	v_mul_f32_e32 v247, v238, v240
	v_fmac_f32_e32 v229, v247, v247
	v_lshlrev_b32_e32 v236, 16, v141
	v_lshlrev_b32_e32 v237, 16, v149
	v_fma_f32 v238, s60, v236, v18
	v_mul_f32_e32 v239, 0xbfb8aa3b, v237
	v_exp_f32_e32 v239, v239
	s_nop 0
	v_add_f32_e32 v239, 1.0, v239
	v_div_scale_f32 v240, s[0:1], v239, v239, v237
	v_rcp_f32_e32 v241, v240
	s_nop 0
	v_fma_f32 v242, -v240, v241, 1.0
	v_fmac_f32_e32 v241, v242, v241
	v_div_scale_f32 v242, vcc, v237, v239, v237
	v_mul_f32_e32 v243, v242, v241
	v_fma_f32 v244, -v240, v243, v242
	v_fmac_f32_e32 v243, v244, v241
	v_fma_f32 v240, -v240, v243, v242
	v_div_fmas_f32 v240, v240, v241, v243
	v_div_fixup_f32 v240, v240, v239, v237
	v_mul_f32_e32 v248, v238, v240
	v_fmac_f32_e32 v230, v248, v248
	v_and_b32_e32 v236, 0xffff0000, v141
	v_and_b32_e32 v237, 0xffff0000, v149
	v_fma_f32 v238, s60, v236, v19
	v_mul_f32_e32 v239, 0xbfb8aa3b, v237
	v_exp_f32_e32 v239, v239
	s_nop 0
	v_add_f32_e32 v239, 1.0, v239
	v_div_scale_f32 v240, s[0:1], v239, v239, v237
	v_rcp_f32_e32 v241, v240
	s_nop 0
	v_fma_f32 v242, -v240, v241, 1.0
	v_fmac_f32_e32 v241, v242, v241
	v_div_scale_f32 v242, vcc, v237, v239, v237
	v_mul_f32_e32 v243, v242, v241
	v_fma_f32 v244, -v240, v243, v242
	v_fmac_f32_e32 v243, v244, v241
	v_fma_f32 v240, -v240, v243, v242
	v_div_fmas_f32 v240, v240, v241, v243
	v_div_fixup_f32 v240, v240, v239, v237
	v_mul_f32_e32 v249, v238, v240
	v_fmac_f32_e32 v231, v249, v249
	v_cvt_pk_bf16_f32 v178, v246, v247
	v_cvt_pk_bf16_f32 v179, v248, v249
	s_waitcnt lgkmcnt(4)
	v_lshlrev_b32_e32 v236, 16, v142
	v_lshlrev_b32_e32 v237, 16, v150
	v_fma_f32 v238, s60, v236, v20
	v_mul_f32_e32 v239, 0xbfb8aa3b, v237
	v_exp_f32_e32 v239, v239
	s_nop 0
	v_add_f32_e32 v239, 1.0, v239
	v_div_scale_f32 v240, s[0:1], v239, v239, v237
	v_rcp_f32_e32 v241, v240
	s_nop 0
	v_fma_f32 v242, -v240, v241, 1.0
	v_fmac_f32_e32 v241, v242, v241
	v_div_scale_f32 v242, vcc, v237, v239, v237
	v_mul_f32_e32 v243, v242, v241
	v_fma_f32 v244, -v240, v243, v242
	v_fmac_f32_e32 v243, v244, v241
	v_fma_f32 v240, -v240, v243, v242
	v_div_fmas_f32 v240, v240, v241, v243
	v_div_fixup_f32 v240, v240, v239, v237
	v_mul_f32_e32 v246, v238, v240
	v_fmac_f32_e32 v228, v246, v246
	v_and_b32_e32 v236, 0xffff0000, v142
	v_and_b32_e32 v237, 0xffff0000, v150
	v_fma_f32 v238, s60, v236, v21
	v_mul_f32_e32 v239, 0xbfb8aa3b, v237
	v_exp_f32_e32 v239, v239
	s_nop 0
	v_add_f32_e32 v239, 1.0, v239
	v_div_scale_f32 v240, s[0:1], v239, v239, v237
	v_rcp_f32_e32 v241, v240
	s_nop 0
	v_fma_f32 v242, -v240, v241, 1.0
	v_fmac_f32_e32 v241, v242, v241
	v_div_scale_f32 v242, vcc, v237, v239, v237
	v_mul_f32_e32 v243, v242, v241
	v_fma_f32 v244, -v240, v243, v242
	v_fmac_f32_e32 v243, v244, v241
	v_fma_f32 v240, -v240, v243, v242
	v_div_fmas_f32 v240, v240, v241, v243
	v_div_fixup_f32 v240, v240, v239, v237
	v_mul_f32_e32 v247, v238, v240
	v_fmac_f32_e32 v229, v247, v247
	v_lshlrev_b32_e32 v236, 16, v143
	v_lshlrev_b32_e32 v237, 16, v151
	v_fma_f32 v238, s60, v236, v22
	v_mul_f32_e32 v239, 0xbfb8aa3b, v237
	v_exp_f32_e32 v239, v239
	s_nop 0
	v_add_f32_e32 v239, 1.0, v239
	v_div_scale_f32 v240, s[0:1], v239, v239, v237
	v_rcp_f32_e32 v241, v240
	s_nop 0
	v_fma_f32 v242, -v240, v241, 1.0
	v_fmac_f32_e32 v241, v242, v241
	v_div_scale_f32 v242, vcc, v237, v239, v237
	v_mul_f32_e32 v243, v242, v241
	v_fma_f32 v244, -v240, v243, v242
	v_fmac_f32_e32 v243, v244, v241
	v_fma_f32 v240, -v240, v243, v242
	v_div_fmas_f32 v240, v240, v241, v243
	v_div_fixup_f32 v240, v240, v239, v237
	v_mul_f32_e32 v248, v238, v240
	v_fmac_f32_e32 v230, v248, v248
	v_and_b32_e32 v236, 0xffff0000, v143
	v_and_b32_e32 v237, 0xffff0000, v151
	v_fma_f32 v238, s60, v236, v23
	v_mul_f32_e32 v239, 0xbfb8aa3b, v237
	v_exp_f32_e32 v239, v239
	s_nop 0
	v_add_f32_e32 v239, 1.0, v239
	v_div_scale_f32 v240, s[0:1], v239, v239, v237
	v_rcp_f32_e32 v241, v240
	s_nop 0
	v_fma_f32 v242, -v240, v241, 1.0
	v_fmac_f32_e32 v241, v242, v241
	v_div_scale_f32 v242, vcc, v237, v239, v237
	v_mul_f32_e32 v243, v242, v241
	v_fma_f32 v244, -v240, v243, v242
	v_fmac_f32_e32 v243, v244, v241
	v_fma_f32 v240, -v240, v243, v242
	v_div_fmas_f32 v240, v240, v241, v243
	v_div_fixup_f32 v240, v240, v239, v237
	v_mul_f32_e32 v249, v238, v240
	v_fmac_f32_e32 v231, v249, v249
	v_cvt_pk_bf16_f32 v180, v246, v247
	v_cvt_pk_bf16_f32 v181, v248, v249
	s_waitcnt lgkmcnt(2)
	v_lshlrev_b32_e32 v236, 16, v144
	v_lshlrev_b32_e32 v237, 16, v152
	v_fma_f32 v238, s60, v236, v24
	v_mul_f32_e32 v239, 0xbfb8aa3b, v237
	v_exp_f32_e32 v239, v239
	s_nop 0
	v_add_f32_e32 v239, 1.0, v239
	v_div_scale_f32 v240, s[0:1], v239, v239, v237
	v_rcp_f32_e32 v241, v240
	s_nop 0
	v_fma_f32 v242, -v240, v241, 1.0
	v_fmac_f32_e32 v241, v242, v241
	v_div_scale_f32 v242, vcc, v237, v239, v237
	v_mul_f32_e32 v243, v242, v241
	v_fma_f32 v244, -v240, v243, v242
	v_fmac_f32_e32 v243, v244, v241
	v_fma_f32 v240, -v240, v243, v242
	v_div_fmas_f32 v240, v240, v241, v243
	v_div_fixup_f32 v240, v240, v239, v237
	v_mul_f32_e32 v246, v238, v240
	v_fmac_f32_e32 v228, v246, v246
	v_and_b32_e32 v236, 0xffff0000, v144
	v_and_b32_e32 v237, 0xffff0000, v152
	v_fma_f32 v238, s60, v236, v25
	v_mul_f32_e32 v239, 0xbfb8aa3b, v237
	v_exp_f32_e32 v239, v239
	s_nop 0
	v_add_f32_e32 v239, 1.0, v239
	v_div_scale_f32 v240, s[0:1], v239, v239, v237
	v_rcp_f32_e32 v241, v240
	s_nop 0
	v_fma_f32 v242, -v240, v241, 1.0
	v_fmac_f32_e32 v241, v242, v241
	v_div_scale_f32 v242, vcc, v237, v239, v237
	v_mul_f32_e32 v243, v242, v241
	v_fma_f32 v244, -v240, v243, v242
	v_fmac_f32_e32 v243, v244, v241
	v_fma_f32 v240, -v240, v243, v242
	v_div_fmas_f32 v240, v240, v241, v243
	v_div_fixup_f32 v240, v240, v239, v237
	v_mul_f32_e32 v247, v238, v240
	v_fmac_f32_e32 v229, v247, v247
	v_lshlrev_b32_e32 v236, 16, v145
	v_lshlrev_b32_e32 v237, 16, v153
	v_fma_f32 v238, s60, v236, v26
	v_mul_f32_e32 v239, 0xbfb8aa3b, v237
	v_exp_f32_e32 v239, v239
	s_nop 0
	v_add_f32_e32 v239, 1.0, v239
	v_div_scale_f32 v240, s[0:1], v239, v239, v237
	v_rcp_f32_e32 v241, v240
	s_nop 0
	v_fma_f32 v242, -v240, v241, 1.0
	v_fmac_f32_e32 v241, v242, v241
	v_div_scale_f32 v242, vcc, v237, v239, v237
	v_mul_f32_e32 v243, v242, v241
	v_fma_f32 v244, -v240, v243, v242
	v_fmac_f32_e32 v243, v244, v241
	v_fma_f32 v240, -v240, v243, v242
	v_div_fmas_f32 v240, v240, v241, v243
	v_div_fixup_f32 v240, v240, v239, v237
	v_mul_f32_e32 v248, v238, v240
	v_fmac_f32_e32 v230, v248, v248
	v_and_b32_e32 v236, 0xffff0000, v145
	v_and_b32_e32 v237, 0xffff0000, v153
	v_fma_f32 v238, s60, v236, v27
	v_mul_f32_e32 v239, 0xbfb8aa3b, v237
	v_exp_f32_e32 v239, v239
	s_nop 0
	v_add_f32_e32 v239, 1.0, v239
	v_div_scale_f32 v240, s[0:1], v239, v239, v237
	v_rcp_f32_e32 v241, v240
	s_nop 0
	v_fma_f32 v242, -v240, v241, 1.0
	v_fmac_f32_e32 v241, v242, v241
	v_div_scale_f32 v242, vcc, v237, v239, v237
	v_mul_f32_e32 v243, v242, v241
	v_fma_f32 v244, -v240, v243, v242
	v_fmac_f32_e32 v243, v244, v241
	v_fma_f32 v240, -v240, v243, v242
	v_div_fmas_f32 v240, v240, v241, v243
	v_div_fixup_f32 v240, v240, v239, v237
	v_mul_f32_e32 v249, v238, v240
	v_fmac_f32_e32 v231, v249, v249
	v_cvt_pk_bf16_f32 v182, v246, v247
	v_cvt_pk_bf16_f32 v183, v248, v249
	s_waitcnt lgkmcnt(0)
	v_lshlrev_b32_e32 v236, 16, v146
	v_lshlrev_b32_e32 v237, 16, v154
	v_fma_f32 v238, s60, v236, v28
	v_mul_f32_e32 v239, 0xbfb8aa3b, v237
	v_exp_f32_e32 v239, v239
	s_nop 0
	v_add_f32_e32 v239, 1.0, v239
	v_div_scale_f32 v240, s[0:1], v239, v239, v237
	v_rcp_f32_e32 v241, v240
	s_nop 0
	v_fma_f32 v242, -v240, v241, 1.0
	v_fmac_f32_e32 v241, v242, v241
	v_div_scale_f32 v242, vcc, v237, v239, v237
	v_mul_f32_e32 v243, v242, v241
	v_fma_f32 v244, -v240, v243, v242
	v_fmac_f32_e32 v243, v244, v241
	v_fma_f32 v240, -v240, v243, v242
	v_div_fmas_f32 v240, v240, v241, v243
	v_div_fixup_f32 v240, v240, v239, v237
	v_mul_f32_e32 v246, v238, v240
	v_fmac_f32_e32 v228, v246, v246
	v_and_b32_e32 v236, 0xffff0000, v146
	v_and_b32_e32 v237, 0xffff0000, v154
	v_fma_f32 v238, s60, v236, v29
	v_mul_f32_e32 v239, 0xbfb8aa3b, v237
	v_exp_f32_e32 v239, v239
	s_nop 0
	v_add_f32_e32 v239, 1.0, v239
	v_div_scale_f32 v240, s[0:1], v239, v239, v237
	v_rcp_f32_e32 v241, v240
	s_nop 0
	v_fma_f32 v242, -v240, v241, 1.0
	v_fmac_f32_e32 v241, v242, v241
	v_div_scale_f32 v242, vcc, v237, v239, v237
	v_mul_f32_e32 v243, v242, v241
	v_fma_f32 v244, -v240, v243, v242
	v_fmac_f32_e32 v243, v244, v241
	v_fma_f32 v240, -v240, v243, v242
	v_div_fmas_f32 v240, v240, v241, v243
	v_div_fixup_f32 v240, v240, v239, v237
	v_mul_f32_e32 v247, v238, v240
	v_fmac_f32_e32 v229, v247, v247
	v_lshlrev_b32_e32 v236, 16, v147
	v_lshlrev_b32_e32 v237, 16, v155
	v_fma_f32 v238, s60, v236, v30
	v_mul_f32_e32 v239, 0xbfb8aa3b, v237
	v_exp_f32_e32 v239, v239
	s_nop 0
	v_add_f32_e32 v239, 1.0, v239
	v_div_scale_f32 v240, s[0:1], v239, v239, v237
	v_rcp_f32_e32 v241, v240
	s_nop 0
	v_fma_f32 v242, -v240, v241, 1.0
	v_fmac_f32_e32 v241, v242, v241
	v_div_scale_f32 v242, vcc, v237, v239, v237
	v_mul_f32_e32 v243, v242, v241
	v_fma_f32 v244, -v240, v243, v242
	v_fmac_f32_e32 v243, v244, v241
	v_fma_f32 v240, -v240, v243, v242
	v_div_fmas_f32 v240, v240, v241, v243
	v_div_fixup_f32 v240, v240, v239, v237
	v_mul_f32_e32 v248, v238, v240
	v_fmac_f32_e32 v230, v248, v248
	v_and_b32_e32 v236, 0xffff0000, v147
	v_and_b32_e32 v237, 0xffff0000, v155
	v_fma_f32 v238, s60, v236, v31
	v_mul_f32_e32 v239, 0xbfb8aa3b, v237
	v_exp_f32_e32 v239, v239
	s_nop 0
	v_add_f32_e32 v239, 1.0, v239
	v_div_scale_f32 v240, s[0:1], v239, v239, v237
	v_rcp_f32_e32 v241, v240
	s_nop 0
	v_fma_f32 v242, -v240, v241, 1.0
	v_fmac_f32_e32 v241, v242, v241
	v_div_scale_f32 v242, vcc, v237, v239, v237
	v_mul_f32_e32 v243, v242, v241
	v_fma_f32 v244, -v240, v243, v242
	v_fmac_f32_e32 v243, v244, v241
	v_fma_f32 v240, -v240, v243, v242
	v_div_fmas_f32 v240, v240, v241, v243
	v_div_fixup_f32 v240, v240, v239, v237
	v_mul_f32_e32 v249, v238, v240
	v_fmac_f32_e32 v231, v249, v249
	v_cvt_pk_bf16_f32 v184, v246, v247
	v_cvt_pk_bf16_f32 v185, v248, v249
	ds_read_b64_tr_b16 v[140:141], v174 offset:128
	ds_read_b64_tr_b16 v[148:149], v227 offset:128
	ds_read_b64_tr_b16 v[142:143], v174 offset:160
	ds_read_b64_tr_b16 v[150:151], v227 offset:160
	ds_read_b64_tr_b16 v[144:145], v174 offset:192
	ds_read_b64_tr_b16 v[152:153], v227 offset:192
	ds_read_b64_tr_b16 v[146:147], v174 offset:224
	ds_read_b64_tr_b16 v[154:155], v227 offset:224
	s_waitcnt lgkmcnt(6)
	v_lshlrev_b32_e32 v236, 16, v140
	v_lshlrev_b32_e32 v237, 16, v148
	v_fma_f32 v238, s61, v236, v32
	v_mul_f32_e32 v239, 0xbfb8aa3b, v237
	v_exp_f32_e32 v239, v239
	s_nop 0
	v_add_f32_e32 v239, 1.0, v239
	v_div_scale_f32 v240, s[0:1], v239, v239, v237
	v_rcp_f32_e32 v241, v240
	s_nop 0
	v_fma_f32 v242, -v240, v241, 1.0
	v_fmac_f32_e32 v241, v242, v241
	v_div_scale_f32 v242, vcc, v237, v239, v237
	v_mul_f32_e32 v243, v242, v241
	v_fma_f32 v244, -v240, v243, v242
	v_fmac_f32_e32 v243, v244, v241
	v_fma_f32 v240, -v240, v243, v242
	v_div_fmas_f32 v240, v240, v241, v243
	v_div_fixup_f32 v240, v240, v239, v237
	v_mul_f32_e32 v246, v238, v240
	v_fmac_f32_e32 v228, v246, v246
	v_and_b32_e32 v236, 0xffff0000, v140
	v_and_b32_e32 v237, 0xffff0000, v148
	v_fma_f32 v238, s61, v236, v33
	v_mul_f32_e32 v239, 0xbfb8aa3b, v237
	v_exp_f32_e32 v239, v239
	s_nop 0
	v_add_f32_e32 v239, 1.0, v239
	v_div_scale_f32 v240, s[0:1], v239, v239, v237
	v_rcp_f32_e32 v241, v240
	s_nop 0
	v_fma_f32 v242, -v240, v241, 1.0
	v_fmac_f32_e32 v241, v242, v241
	v_div_scale_f32 v242, vcc, v237, v239, v237
	v_mul_f32_e32 v243, v242, v241
	v_fma_f32 v244, -v240, v243, v242
	v_fmac_f32_e32 v243, v244, v241
	v_fma_f32 v240, -v240, v243, v242
	v_div_fmas_f32 v240, v240, v241, v243
	v_div_fixup_f32 v240, v240, v239, v237
	v_mul_f32_e32 v247, v238, v240
	v_fmac_f32_e32 v229, v247, v247
	v_lshlrev_b32_e32 v236, 16, v141
	v_lshlrev_b32_e32 v237, 16, v149
	v_fma_f32 v238, s61, v236, v34
	v_mul_f32_e32 v239, 0xbfb8aa3b, v237
	v_exp_f32_e32 v239, v239
	s_nop 0
	v_add_f32_e32 v239, 1.0, v239
	v_div_scale_f32 v240, s[0:1], v239, v239, v237
	v_rcp_f32_e32 v241, v240
	s_nop 0
	v_fma_f32 v242, -v240, v241, 1.0
	v_fmac_f32_e32 v241, v242, v241
	v_div_scale_f32 v242, vcc, v237, v239, v237
	v_mul_f32_e32 v243, v242, v241
	v_fma_f32 v244, -v240, v243, v242
	v_fmac_f32_e32 v243, v244, v241
	v_fma_f32 v240, -v240, v243, v242
	v_div_fmas_f32 v240, v240, v241, v243
	v_div_fixup_f32 v240, v240, v239, v237
	v_mul_f32_e32 v248, v238, v240
	v_fmac_f32_e32 v230, v248, v248
	v_and_b32_e32 v236, 0xffff0000, v141
	v_and_b32_e32 v237, 0xffff0000, v149
	v_fma_f32 v238, s61, v236, v35
	v_mul_f32_e32 v239, 0xbfb8aa3b, v237
	v_exp_f32_e32 v239, v239
	s_nop 0
	v_add_f32_e32 v239, 1.0, v239
	v_div_scale_f32 v240, s[0:1], v239, v239, v237
	v_rcp_f32_e32 v241, v240
	s_nop 0
	v_fma_f32 v242, -v240, v241, 1.0
	v_fmac_f32_e32 v241, v242, v241
	v_div_scale_f32 v242, vcc, v237, v239, v237
	v_mul_f32_e32 v243, v242, v241
	v_fma_f32 v244, -v240, v243, v242
	v_fmac_f32_e32 v243, v244, v241
	v_fma_f32 v240, -v240, v243, v242
	v_div_fmas_f32 v240, v240, v241, v243
	v_div_fixup_f32 v240, v240, v239, v237
	v_mul_f32_e32 v249, v238, v240
	v_fmac_f32_e32 v231, v249, v249
	v_cvt_pk_bf16_f32 v186, v246, v247
	v_cvt_pk_bf16_f32 v187, v248, v249
	s_waitcnt lgkmcnt(4)
	v_lshlrev_b32_e32 v236, 16, v142
	v_lshlrev_b32_e32 v237, 16, v150
	v_fma_f32 v238, s61, v236, v36
	v_mul_f32_e32 v239, 0xbfb8aa3b, v237
	v_exp_f32_e32 v239, v239
	s_nop 0
	v_add_f32_e32 v239, 1.0, v239
	v_div_scale_f32 v240, s[0:1], v239, v239, v237
	v_rcp_f32_e32 v241, v240
	s_nop 0
	v_fma_f32 v242, -v240, v241, 1.0
	v_fmac_f32_e32 v241, v242, v241
	v_div_scale_f32 v242, vcc, v237, v239, v237
	v_mul_f32_e32 v243, v242, v241
	v_fma_f32 v244, -v240, v243, v242
	v_fmac_f32_e32 v243, v244, v241
	v_fma_f32 v240, -v240, v243, v242
	v_div_fmas_f32 v240, v240, v241, v243
	v_div_fixup_f32 v240, v240, v239, v237
	v_mul_f32_e32 v246, v238, v240
	v_fmac_f32_e32 v228, v246, v246
	v_and_b32_e32 v236, 0xffff0000, v142
	v_and_b32_e32 v237, 0xffff0000, v150
	v_fma_f32 v238, s61, v236, v37
	v_mul_f32_e32 v239, 0xbfb8aa3b, v237
	v_exp_f32_e32 v239, v239
	s_nop 0
	v_add_f32_e32 v239, 1.0, v239
	v_div_scale_f32 v240, s[0:1], v239, v239, v237
	v_rcp_f32_e32 v241, v240
	s_nop 0
	v_fma_f32 v242, -v240, v241, 1.0
	v_fmac_f32_e32 v241, v242, v241
	v_div_scale_f32 v242, vcc, v237, v239, v237
	v_mul_f32_e32 v243, v242, v241
	v_fma_f32 v244, -v240, v243, v242
	v_fmac_f32_e32 v243, v244, v241
	v_fma_f32 v240, -v240, v243, v242
	v_div_fmas_f32 v240, v240, v241, v243
	v_div_fixup_f32 v240, v240, v239, v237
	v_mul_f32_e32 v247, v238, v240
	v_fmac_f32_e32 v229, v247, v247
	v_lshlrev_b32_e32 v236, 16, v143
	v_lshlrev_b32_e32 v237, 16, v151
	v_fma_f32 v238, s61, v236, v38
	v_mul_f32_e32 v239, 0xbfb8aa3b, v237
	v_exp_f32_e32 v239, v239
	s_nop 0
	v_add_f32_e32 v239, 1.0, v239
	v_div_scale_f32 v240, s[0:1], v239, v239, v237
	v_rcp_f32_e32 v241, v240
	s_nop 0
	v_fma_f32 v242, -v240, v241, 1.0
	v_fmac_f32_e32 v241, v242, v241
	v_div_scale_f32 v242, vcc, v237, v239, v237
	v_mul_f32_e32 v243, v242, v241
	v_fma_f32 v244, -v240, v243, v242
	v_fmac_f32_e32 v243, v244, v241
	v_fma_f32 v240, -v240, v243, v242
	v_div_fmas_f32 v240, v240, v241, v243
	v_div_fixup_f32 v240, v240, v239, v237
	v_mul_f32_e32 v248, v238, v240
	v_fmac_f32_e32 v230, v248, v248
	v_and_b32_e32 v236, 0xffff0000, v143
	v_and_b32_e32 v237, 0xffff0000, v151
	v_fma_f32 v238, s61, v236, v39
	v_mul_f32_e32 v239, 0xbfb8aa3b, v237
	v_exp_f32_e32 v239, v239
	s_nop 0
	v_add_f32_e32 v239, 1.0, v239
	v_div_scale_f32 v240, s[0:1], v239, v239, v237
	v_rcp_f32_e32 v241, v240
	s_nop 0
	v_fma_f32 v242, -v240, v241, 1.0
	v_fmac_f32_e32 v241, v242, v241
	v_div_scale_f32 v242, vcc, v237, v239, v237
	v_mul_f32_e32 v243, v242, v241
	v_fma_f32 v244, -v240, v243, v242
	v_fmac_f32_e32 v243, v244, v241
	v_fma_f32 v240, -v240, v243, v242
	v_div_fmas_f32 v240, v240, v241, v243
	v_div_fixup_f32 v240, v240, v239, v237
	v_mul_f32_e32 v249, v238, v240
	v_fmac_f32_e32 v231, v249, v249
	v_cvt_pk_bf16_f32 v188, v246, v247
	v_cvt_pk_bf16_f32 v189, v248, v249
	s_waitcnt lgkmcnt(2)
	v_lshlrev_b32_e32 v236, 16, v144
	v_lshlrev_b32_e32 v237, 16, v152
	v_fma_f32 v238, s61, v236, v40
	v_mul_f32_e32 v239, 0xbfb8aa3b, v237
	v_exp_f32_e32 v239, v239
	s_nop 0
	v_add_f32_e32 v239, 1.0, v239
	v_div_scale_f32 v240, s[0:1], v239, v239, v237
	v_rcp_f32_e32 v241, v240
	s_nop 0
	v_fma_f32 v242, -v240, v241, 1.0
	v_fmac_f32_e32 v241, v242, v241
	v_div_scale_f32 v242, vcc, v237, v239, v237
	v_mul_f32_e32 v243, v242, v241
	v_fma_f32 v244, -v240, v243, v242
	v_fmac_f32_e32 v243, v244, v241
	v_fma_f32 v240, -v240, v243, v242
	v_div_fmas_f32 v240, v240, v241, v243
	v_div_fixup_f32 v240, v240, v239, v237
	v_mul_f32_e32 v246, v238, v240
	v_fmac_f32_e32 v228, v246, v246
	v_and_b32_e32 v236, 0xffff0000, v144
	v_and_b32_e32 v237, 0xffff0000, v152
	v_fma_f32 v238, s61, v236, v41
	v_mul_f32_e32 v239, 0xbfb8aa3b, v237
	v_exp_f32_e32 v239, v239
	s_nop 0
	v_add_f32_e32 v239, 1.0, v239
	v_div_scale_f32 v240, s[0:1], v239, v239, v237
	v_rcp_f32_e32 v241, v240
	s_nop 0
	v_fma_f32 v242, -v240, v241, 1.0
	v_fmac_f32_e32 v241, v242, v241
	v_div_scale_f32 v242, vcc, v237, v239, v237
	v_mul_f32_e32 v243, v242, v241
	v_fma_f32 v244, -v240, v243, v242
	v_fmac_f32_e32 v243, v244, v241
	v_fma_f32 v240, -v240, v243, v242
	v_div_fmas_f32 v240, v240, v241, v243
	v_div_fixup_f32 v240, v240, v239, v237
	v_mul_f32_e32 v247, v238, v240
	v_fmac_f32_e32 v229, v247, v247
	v_lshlrev_b32_e32 v236, 16, v145
	v_lshlrev_b32_e32 v237, 16, v153
	v_fma_f32 v238, s61, v236, v42
	v_mul_f32_e32 v239, 0xbfb8aa3b, v237
	v_exp_f32_e32 v239, v239
	s_nop 0
	v_add_f32_e32 v239, 1.0, v239
	v_div_scale_f32 v240, s[0:1], v239, v239, v237
	v_rcp_f32_e32 v241, v240
	s_nop 0
	v_fma_f32 v242, -v240, v241, 1.0
	v_fmac_f32_e32 v241, v242, v241
	v_div_scale_f32 v242, vcc, v237, v239, v237
	v_mul_f32_e32 v243, v242, v241
	v_fma_f32 v244, -v240, v243, v242
	v_fmac_f32_e32 v243, v244, v241
	v_fma_f32 v240, -v240, v243, v242
	v_div_fmas_f32 v240, v240, v241, v243
	v_div_fixup_f32 v240, v240, v239, v237
	v_mul_f32_e32 v248, v238, v240
	v_fmac_f32_e32 v230, v248, v248
	v_and_b32_e32 v236, 0xffff0000, v145
	v_and_b32_e32 v237, 0xffff0000, v153
	v_fma_f32 v238, s61, v236, v43
	v_mul_f32_e32 v239, 0xbfb8aa3b, v237
	v_exp_f32_e32 v239, v239
	s_nop 0
	v_add_f32_e32 v239, 1.0, v239
	v_div_scale_f32 v240, s[0:1], v239, v239, v237
	v_rcp_f32_e32 v241, v240
	s_nop 0
	v_fma_f32 v242, -v240, v241, 1.0
	v_fmac_f32_e32 v241, v242, v241
	v_div_scale_f32 v242, vcc, v237, v239, v237
	v_mul_f32_e32 v243, v242, v241
	v_fma_f32 v244, -v240, v243, v242
	v_fmac_f32_e32 v243, v244, v241
	v_fma_f32 v240, -v240, v243, v242
	v_div_fmas_f32 v240, v240, v241, v243
	v_div_fixup_f32 v240, v240, v239, v237
	v_mul_f32_e32 v249, v238, v240
	v_fmac_f32_e32 v231, v249, v249
	v_cvt_pk_bf16_f32 v190, v246, v247
	v_cvt_pk_bf16_f32 v191, v248, v249
	s_waitcnt lgkmcnt(0)
	v_lshlrev_b32_e32 v236, 16, v146
	v_lshlrev_b32_e32 v237, 16, v154
	v_fma_f32 v238, s61, v236, v44
	v_mul_f32_e32 v239, 0xbfb8aa3b, v237
	v_exp_f32_e32 v239, v239
	s_nop 0
	v_add_f32_e32 v239, 1.0, v239
	v_div_scale_f32 v240, s[0:1], v239, v239, v237
	v_rcp_f32_e32 v241, v240
	s_nop 0
	v_fma_f32 v242, -v240, v241, 1.0
	v_fmac_f32_e32 v241, v242, v241
	v_div_scale_f32 v242, vcc, v237, v239, v237
	v_mul_f32_e32 v243, v242, v241
	v_fma_f32 v244, -v240, v243, v242
	v_fmac_f32_e32 v243, v244, v241
	v_fma_f32 v240, -v240, v243, v242
	v_div_fmas_f32 v240, v240, v241, v243
	v_div_fixup_f32 v240, v240, v239, v237
	v_mul_f32_e32 v246, v238, v240
	v_fmac_f32_e32 v228, v246, v246
	v_and_b32_e32 v236, 0xffff0000, v146
	v_and_b32_e32 v237, 0xffff0000, v154
	v_fma_f32 v238, s61, v236, v45
	v_mul_f32_e32 v239, 0xbfb8aa3b, v237
	v_exp_f32_e32 v239, v239
	s_nop 0
	v_add_f32_e32 v239, 1.0, v239
	v_div_scale_f32 v240, s[0:1], v239, v239, v237
	v_rcp_f32_e32 v241, v240
	s_nop 0
	v_fma_f32 v242, -v240, v241, 1.0
	v_fmac_f32_e32 v241, v242, v241
	v_div_scale_f32 v242, vcc, v237, v239, v237
	v_mul_f32_e32 v243, v242, v241
	v_fma_f32 v244, -v240, v243, v242
	v_fmac_f32_e32 v243, v244, v241
	v_fma_f32 v240, -v240, v243, v242
	v_div_fmas_f32 v240, v240, v241, v243
	v_div_fixup_f32 v240, v240, v239, v237
	v_mul_f32_e32 v247, v238, v240
	v_fmac_f32_e32 v229, v247, v247
	v_lshlrev_b32_e32 v236, 16, v147
	v_lshlrev_b32_e32 v237, 16, v155
	v_fma_f32 v238, s61, v236, v46
	v_mul_f32_e32 v239, 0xbfb8aa3b, v237
	v_exp_f32_e32 v239, v239
	s_nop 0
	v_add_f32_e32 v239, 1.0, v239
	v_div_scale_f32 v240, s[0:1], v239, v239, v237
	v_rcp_f32_e32 v241, v240
	s_nop 0
	v_fma_f32 v242, -v240, v241, 1.0
	v_fmac_f32_e32 v241, v242, v241
	v_div_scale_f32 v242, vcc, v237, v239, v237
	v_mul_f32_e32 v243, v242, v241
	v_fma_f32 v244, -v240, v243, v242
	v_fmac_f32_e32 v243, v244, v241
	v_fma_f32 v240, -v240, v243, v242
	v_div_fmas_f32 v240, v240, v241, v243
	v_div_fixup_f32 v240, v240, v239, v237
	v_mul_f32_e32 v248, v238, v240
	v_fmac_f32_e32 v230, v248, v248
	v_and_b32_e32 v236, 0xffff0000, v147
	v_and_b32_e32 v237, 0xffff0000, v155
	v_fma_f32 v238, s61, v236, v47
	v_mul_f32_e32 v239, 0xbfb8aa3b, v237
	v_exp_f32_e32 v239, v239
	s_nop 0
	v_add_f32_e32 v239, 1.0, v239
	v_div_scale_f32 v240, s[0:1], v239, v239, v237
	v_rcp_f32_e32 v241, v240
	s_nop 0
	v_fma_f32 v242, -v240, v241, 1.0
	v_fmac_f32_e32 v241, v242, v241
	v_div_scale_f32 v242, vcc, v237, v239, v237
	v_mul_f32_e32 v243, v242, v241
	v_fma_f32 v244, -v240, v243, v242
	v_fmac_f32_e32 v243, v244, v241
	v_fma_f32 v240, -v240, v243, v242
	v_div_fmas_f32 v240, v240, v241, v243
	v_div_fixup_f32 v240, v240, v239, v237
	v_mul_f32_e32 v249, v238, v240
	v_fmac_f32_e32 v231, v249, v249
	v_cvt_pk_bf16_f32 v192, v246, v247
	v_cvt_pk_bf16_f32 v193, v248, v249
	ds_read_b32 v156, v167 offset:5120
	ds_read_b32 v157, v167 offset:7168
	ds_read_b32 v158, v167 offset:5632
	ds_read_b32 v159, v167 offset:7680
	s_waitcnt vmcnt(0)
	v_mfma_f32_16x16x32_bf16 v[96:99], v[64:67], v[48:51], 0
	v_mfma_f32_16x16x32_bf16 v[96:99], v[68:71], v[52:55], v[96:99]
	v_mfma_f32_16x16x32_bf16 v[96:99], v[72:75], v[56:59], v[96:99]
	v_mfma_f32_16x16x32_bf16 v[96:99], v[76:79], v[60:63], v[96:99]
	v_mfma_f32_16x16x32_bf16 v[100:103], v[80:83], v[48:51], 0
	v_mfma_f32_16x16x32_bf16 v[100:103], v[84:87], v[52:55], v[100:103]
	v_mfma_f32_16x16x32_bf16 v[100:103], v[88:91], v[56:59], v[100:103]
	v_mfma_f32_16x16x32_bf16 v[100:103], v[92:95], v[60:63], v[100:103]
	s_add_u32 s52, s40, 0xc000
	s_addc_u32 s53, s41, 0
	global_load_dwordx4 v[64:67], v169, s[52:53] offset:256
	global_load_dwordx4 v[68:71], v169, s[52:53] offset:320
	global_load_dwordx4 v[72:75], v169, s[52:53] offset:384
	global_load_dwordx4 v[76:79], v169, s[52:53] offset:448
	s_add_u32 s52, s40, 0x12000
	s_addc_u32 s53, s41, 0
	global_load_dwordx4 v[80:83], v169, s[52:53] offset:256
	global_load_dwordx4 v[84:87], v169, s[52:53] offset:320
	global_load_dwordx4 v[88:91], v169, s[52:53] offset:384
	global_load_dwordx4 v[92:95], v169, s[52:53] offset:448
	ds_read_b128 v[104:107], v168 offset:1024
	ds_read_b128 v[108:111], v168 offset:3072
	ds_read_b128 v[112:115], v168 offset:5120
	ds_read_b128 v[116:119], v168 offset:7168
	ds_read_b128 v[120:123], v168 offset:1088
	ds_read_b128 v[124:127], v168 offset:3136
	ds_read_b128 v[128:131], v168 offset:5184
	ds_read_b128 v[132:135], v168 offset:7232
	ds_read_b64_tr_b16 v[140:141], v166 offset:256
	ds_read_b64_tr_b16 v[142:143], v166 offset:8960
	ds_read_b64_tr_b16 v[144:145], v166 offset:288
	ds_read_b64_tr_b16 v[146:147], v166 offset:8992
	s_waitcnt lgkmcnt(4)
	v_subrev_u32_e32 v236, 0, v175
	v_cmp_gt_i32_e64 s[78:79], v236, 0
	v_cmp_gt_i32_e64 s[80:81], v236, 1
	v_cmp_gt_i32_e64 s[82:83], v236, 2
	v_cmp_gt_i32_e64 s[84:85], v236, 3
	v_cmp_eq_u32_e64 s[86:87], v236, 0
	v_cmp_eq_u32_e64 s[88:89], v236, 1
	v_cmp_eq_u32_e64 s[90:91], v236, 2
	v_cmp_eq_u32_e64 s[92:93], v236, 3
	v_cndmask_b32_e64 v237, v116, v112, s[78:79]
	v_cndmask_b32_e64 v238, v157, v156, s[78:79]
	v_sub_f32_e32 v237, v238, v237
	v_min_f32_e32 v237, 0, v237
	v_mul_f32_e32 v237, 0x3fb8aa3b, v237
	v_exp_f32_e32 v237, v237
	v_cndmask_b32_e64 v239, v108, v104, s[78:79]
	v_add_f32_e32 v240, v104, v108
	v_mul_f32_e32 v237, v239, v237
	v_cndmask_b32_e64 v237, v237, v240, s[86:87]
	v_mul_f32_e32 v241, v96, v237
	v_cndmask_b32_e64 v237, v117, v113, s[80:81]
	v_cndmask_b32_e64 v238, v157, v156, s[80:81]
	v_sub_f32_e32 v237, v238, v237
	v_min_f32_e32 v237, 0, v237
	v_mul_f32_e32 v237, 0x3fb8aa3b, v237
	v_exp_f32_e32 v237, v237
	v_cndmask_b32_e64 v239, v109, v105, s[80:81]
	v_add_f32_e32 v240, v105, v109
	v_mul_f32_e32 v237, v239, v237
	v_cndmask_b32_e64 v237, v237, v240, s[88:89]
	v_mul_f32_e32 v242, v97, v237
	v_cndmask_b32_e64 v237, v118, v114, s[82:83]
	v_cndmask_b32_e64 v238, v157, v156, s[82:83]
	v_sub_f32_e32 v237, v238, v237
	v_min_f32_e32 v237, 0, v237
	v_mul_f32_e32 v237, 0x3fb8aa3b, v237
	v_exp_f32_e32 v237, v237
	v_cndmask_b32_e64 v239, v110, v106, s[82:83]
	v_add_f32_e32 v240, v106, v110
	v_mul_f32_e32 v237, v239, v237
	v_cndmask_b32_e64 v237, v237, v240, s[90:91]
	v_mul_f32_e32 v243, v98, v237
	v_cndmask_b32_e64 v237, v119, v115, s[84:85]
	v_cndmask_b32_e64 v238, v157, v156, s[84:85]
	v_sub_f32_e32 v237, v238, v237
	v_min_f32_e32 v237, 0, v237
	v_mul_f32_e32 v237, 0x3fb8aa3b, v237
	v_exp_f32_e32 v237, v237
	v_cndmask_b32_e64 v239, v111, v107, s[84:85]
	v_add_f32_e32 v240, v107, v111
	v_mul_f32_e32 v237, v239, v237
	v_cndmask_b32_e64 v237, v237, v240, s[92:93]
	v_mul_f32_e32 v244, v99, v237
	ds_read_b64_tr_b16 v[148:149], v166 offset:320
	ds_read_b64_tr_b16 v[150:151], v166 offset:9024
	ds_read_b64_tr_b16 v[152:153], v166 offset:352
	ds_read_b64_tr_b16 v[154:155], v166 offset:9056
	v_subrev_u32_e32 v236, 16, v175
	v_cmp_gt_i32_e64 s[78:79], v236, 0
	v_cmp_gt_i32_e64 s[80:81], v236, 1
	v_cmp_gt_i32_e64 s[82:83], v236, 2
	v_cmp_gt_i32_e64 s[84:85], v236, 3
	v_cmp_eq_u32_e64 s[86:87], v236, 0
	v_cmp_eq_u32_e64 s[88:89], v236, 1
	v_cmp_eq_u32_e64 s[90:91], v236, 2
	v_cmp_eq_u32_e64 s[92:93], v236, 3
	v_cndmask_b32_e64 v237, v132, v128, s[78:79]
	v_cndmask_b32_e64 v238, v157, v156, s[78:79]
	v_sub_f32_e32 v237, v238, v237
	v_min_f32_e32 v237, 0, v237
	v_mul_f32_e32 v237, 0x3fb8aa3b, v237
	v_exp_f32_e32 v237, v237
	v_cndmask_b32_e64 v239, v124, v120, s[78:79]
	v_add_f32_e32 v240, v120, v124
	v_mul_f32_e32 v237, v239, v237
	v_cndmask_b32_e64 v237, v237, v240, s[86:87]
	v_mul_f32_e32 v245, v100, v237
	v_cndmask_b32_e64 v237, v133, v129, s[80:81]
	v_cndmask_b32_e64 v238, v157, v156, s[80:81]
	v_sub_f32_e32 v237, v238, v237
	v_min_f32_e32 v237, 0, v237
	v_mul_f32_e32 v237, 0x3fb8aa3b, v237
	v_exp_f32_e32 v237, v237
	v_cndmask_b32_e64 v239, v125, v121, s[80:81]
	v_add_f32_e32 v240, v121, v125
	v_mul_f32_e32 v237, v239, v237
	v_cndmask_b32_e64 v237, v237, v240, s[88:89]
	v_mul_f32_e32 v246, v101, v237
	v_cndmask_b32_e64 v237, v134, v130, s[82:83]
	v_cndmask_b32_e64 v238, v157, v156, s[82:83]
	v_sub_f32_e32 v237, v238, v237
	v_min_f32_e32 v237, 0, v237
	v_mul_f32_e32 v237, 0x3fb8aa3b, v237
	v_exp_f32_e32 v237, v237
	v_cndmask_b32_e64 v239, v126, v122, s[82:83]
	v_add_f32_e32 v240, v122, v126
	v_mul_f32_e32 v237, v239, v237
	v_cndmask_b32_e64 v237, v237, v240, s[90:91]
	v_mul_f32_e32 v247, v102, v237
	v_cndmask_b32_e64 v237, v135, v131, s[84:85]
	v_cndmask_b32_e64 v238, v157, v156, s[84:85]
	v_sub_f32_e32 v237, v238, v237
	v_min_f32_e32 v237, 0, v237
	v_mul_f32_e32 v237, 0x3fb8aa3b, v237
	v_exp_f32_e32 v237, v237
	v_cndmask_b32_e64 v239, v127, v123, s[84:85]
	v_add_f32_e32 v240, v123, v127
	v_mul_f32_e32 v237, v239, v237
	v_cndmask_b32_e64 v237, v237, v240, s[92:93]
	v_mul_f32_e32 v248, v103, v237
	v_cvt_pk_bf16_f32 v136, v241, v242
	v_cvt_pk_bf16_f32 v137, v243, v244
	v_cvt_pk_bf16_f32 v138, v245, v246
	v_cvt_pk_bf16_f32 v139, v247, v248
	s_waitcnt lgkmcnt(0)
	s_nop 1
	v_mfma_f32_16x16x32_bf16 v[16:19], v[136:139], v[140:143], 0
	v_mfma_f32_16x16x32_bf16 v[20:23], v[136:139], v[144:147], 0
	v_mfma_f32_16x16x32_bf16 v[24:27], v[136:139], v[148:151], 0
	v_mfma_f32_16x16x32_bf16 v[28:31], v[136:139], v[152:155], 0
	ds_read_b128 v[104:107], v168 offset:1536
	ds_read_b128 v[108:111], v168 offset:3584
	ds_read_b128 v[112:115], v168 offset:5632
	ds_read_b128 v[116:119], v168 offset:7680
	ds_read_b128 v[120:123], v168 offset:1600
	ds_read_b128 v[124:127], v168 offset:3648
	ds_read_b128 v[128:131], v168 offset:5696
	ds_read_b128 v[132:135], v168 offset:7744
	ds_read_b64_tr_b16 v[140:141], v166 offset:384
	ds_read_b64_tr_b16 v[142:143], v166 offset:9088
	ds_read_b64_tr_b16 v[144:145], v166 offset:416
	ds_read_b64_tr_b16 v[146:147], v166 offset:9120
	s_waitcnt lgkmcnt(4)
	v_subrev_u32_e32 v236, 0, v175
	v_cmp_gt_i32_e64 s[78:79], v236, 0
	v_cmp_gt_i32_e64 s[80:81], v236, 1
	v_cmp_gt_i32_e64 s[82:83], v236, 2
	v_cmp_gt_i32_e64 s[84:85], v236, 3
	v_cmp_eq_u32_e64 s[86:87], v236, 0
	v_cmp_eq_u32_e64 s[88:89], v236, 1
	v_cmp_eq_u32_e64 s[90:91], v236, 2
	v_cmp_eq_u32_e64 s[92:93], v236, 3
	v_cndmask_b32_e64 v237, v116, v112, s[78:79]
	v_cndmask_b32_e64 v238, v159, v158, s[78:79]
	v_sub_f32_e32 v237, v238, v237
	v_min_f32_e32 v237, 0, v237
	v_mul_f32_e32 v237, 0x3fb8aa3b, v237
	v_exp_f32_e32 v237, v237
	v_cndmask_b32_e64 v239, v108, v104, s[78:79]
	v_add_f32_e32 v240, v104, v108
	v_mul_f32_e32 v237, v239, v237
	v_cndmask_b32_e64 v237, v237, v240, s[86:87]
	v_mul_f32_e32 v241, v96, v237
	v_cndmask_b32_e64 v237, v117, v113, s[80:81]
	v_cndmask_b32_e64 v238, v159, v158, s[80:81]
	v_sub_f32_e32 v237, v238, v237
	v_min_f32_e32 v237, 0, v237
	v_mul_f32_e32 v237, 0x3fb8aa3b, v237
	v_exp_f32_e32 v237, v237
	v_cndmask_b32_e64 v239, v109, v105, s[80:81]
	v_add_f32_e32 v240, v105, v109
	v_mul_f32_e32 v237, v239, v237
	v_cndmask_b32_e64 v237, v237, v240, s[88:89]
	v_mul_f32_e32 v242, v97, v237
	v_cndmask_b32_e64 v237, v118, v114, s[82:83]
	v_cndmask_b32_e64 v238, v159, v158, s[82:83]
	v_sub_f32_e32 v237, v238, v237
	v_min_f32_e32 v237, 0, v237
	v_mul_f32_e32 v237, 0x3fb8aa3b, v237
	v_exp_f32_e32 v237, v237
	v_cndmask_b32_e64 v239, v110, v106, s[82:83]
	v_add_f32_e32 v240, v106, v110
	v_mul_f32_e32 v237, v239, v237
	v_cndmask_b32_e64 v237, v237, v240, s[90:91]
	v_mul_f32_e32 v243, v98, v237
	v_cndmask_b32_e64 v237, v119, v115, s[84:85]
	v_cndmask_b32_e64 v238, v159, v158, s[84:85]
	v_sub_f32_e32 v237, v238, v237
	v_min_f32_e32 v237, 0, v237
	v_mul_f32_e32 v237, 0x3fb8aa3b, v237
	v_exp_f32_e32 v237, v237
	v_cndmask_b32_e64 v239, v111, v107, s[84:85]
	v_add_f32_e32 v240, v107, v111
	v_mul_f32_e32 v237, v239, v237
	v_cndmask_b32_e64 v237, v237, v240, s[92:93]
	v_mul_f32_e32 v244, v99, v237
	ds_read_b64_tr_b16 v[148:149], v166 offset:448
	ds_read_b64_tr_b16 v[150:151], v166 offset:9152
	ds_read_b64_tr_b16 v[152:153], v166 offset:480
	ds_read_b64_tr_b16 v[154:155], v166 offset:9184
	v_subrev_u32_e32 v236, 16, v175
	v_cmp_gt_i32_e64 s[78:79], v236, 0
	v_cmp_gt_i32_e64 s[80:81], v236, 1
	v_cmp_gt_i32_e64 s[82:83], v236, 2
	v_cmp_gt_i32_e64 s[84:85], v236, 3
	v_cmp_eq_u32_e64 s[86:87], v236, 0
	v_cmp_eq_u32_e64 s[88:89], v236, 1
	v_cmp_eq_u32_e64 s[90:91], v236, 2
	v_cmp_eq_u32_e64 s[92:93], v236, 3
	v_cndmask_b32_e64 v237, v132, v128, s[78:79]
	v_cndmask_b32_e64 v238, v159, v158, s[78:79]
	v_sub_f32_e32 v237, v238, v237
	v_min_f32_e32 v237, 0, v237
	v_mul_f32_e32 v237, 0x3fb8aa3b, v237
	v_exp_f32_e32 v237, v237
	v_cndmask_b32_e64 v239, v124, v120, s[78:79]
	v_add_f32_e32 v240, v120, v124
	v_mul_f32_e32 v237, v239, v237
	v_cndmask_b32_e64 v237, v237, v240, s[86:87]
	v_mul_f32_e32 v245, v100, v237
	v_cndmask_b32_e64 v237, v133, v129, s[80:81]
	v_cndmask_b32_e64 v238, v159, v158, s[80:81]
	v_sub_f32_e32 v237, v238, v237
	v_min_f32_e32 v237, 0, v237
	v_mul_f32_e32 v237, 0x3fb8aa3b, v237
	v_exp_f32_e32 v237, v237
	v_cndmask_b32_e64 v239, v125, v121, s[80:81]
	v_add_f32_e32 v240, v121, v125
	v_mul_f32_e32 v237, v239, v237
	v_cndmask_b32_e64 v237, v237, v240, s[88:89]
	v_mul_f32_e32 v246, v101, v237
	v_cndmask_b32_e64 v237, v134, v130, s[82:83]
	v_cndmask_b32_e64 v238, v159, v158, s[82:83]
	v_sub_f32_e32 v237, v238, v237
	v_min_f32_e32 v237, 0, v237
	v_mul_f32_e32 v237, 0x3fb8aa3b, v237
	v_exp_f32_e32 v237, v237
	v_cndmask_b32_e64 v239, v126, v122, s[82:83]
	v_add_f32_e32 v240, v122, v126
	v_mul_f32_e32 v237, v239, v237
	v_cndmask_b32_e64 v237, v237, v240, s[90:91]
	v_mul_f32_e32 v247, v102, v237
	v_cndmask_b32_e64 v237, v135, v131, s[84:85]
	v_cndmask_b32_e64 v238, v159, v158, s[84:85]
	v_sub_f32_e32 v237, v238, v237
	v_min_f32_e32 v237, 0, v237
	v_mul_f32_e32 v237, 0x3fb8aa3b, v237
	v_exp_f32_e32 v237, v237
	v_cndmask_b32_e64 v239, v127, v123, s[84:85]
	v_add_f32_e32 v240, v123, v127
	v_mul_f32_e32 v237, v239, v237
	v_cndmask_b32_e64 v237, v237, v240, s[92:93]
	v_mul_f32_e32 v248, v103, v237
	v_cvt_pk_bf16_f32 v136, v241, v242
	v_cvt_pk_bf16_f32 v137, v243, v244
	v_cvt_pk_bf16_f32 v138, v245, v246
	v_cvt_pk_bf16_f32 v139, v247, v248
	s_waitcnt lgkmcnt(0)
	s_nop 1
	v_mfma_f32_16x16x32_bf16 v[32:35], v[136:139], v[140:143], 0
	v_mfma_f32_16x16x32_bf16 v[36:39], v[136:139], v[144:147], 0
	v_mfma_f32_16x16x32_bf16 v[40:43], v[136:139], v[148:151], 0
	v_mfma_f32_16x16x32_bf16 v[44:47], v[136:139], v[152:155], 0
	s_waitcnt vmcnt(0)
	v_mfma_f32_16x16x32_bf16 v[96:99], v[64:67], v[48:51], 0
	v_mfma_f32_16x16x32_bf16 v[96:99], v[68:71], v[52:55], v[96:99]
	v_mfma_f32_16x16x32_bf16 v[96:99], v[72:75], v[56:59], v[96:99]
	v_mfma_f32_16x16x32_bf16 v[96:99], v[76:79], v[60:63], v[96:99]
	v_mfma_f32_16x16x32_bf16 v[100:103], v[80:83], v[48:51], 0
	v_mfma_f32_16x16x32_bf16 v[100:103], v[84:87], v[52:55], v[100:103]
	v_mfma_f32_16x16x32_bf16 v[100:103], v[88:91], v[56:59], v[100:103]
	v_mfma_f32_16x16x32_bf16 v[100:103], v[92:95], v[60:63], v[100:103]
	s_add_u32 s52, s40, 0x18000
	s_addc_u32 s53, s41, 0
	global_load_dwordx4 v[64:67], v169, s[52:53] offset:256
	global_load_dwordx4 v[68:71], v169, s[52:53] offset:320
	global_load_dwordx4 v[72:75], v169, s[52:53] offset:384
	global_load_dwordx4 v[76:79], v169, s[52:53] offset:448
	s_add_u32 s52, s40, 0x1e000
	s_addc_u32 s53, s41, 0
	global_load_dwordx4 v[80:83], v169, s[52:53] offset:256
	global_load_dwordx4 v[84:87], v169, s[52:53] offset:320
	global_load_dwordx4 v[88:91], v169, s[52:53] offset:384
	global_load_dwordx4 v[92:95], v169, s[52:53] offset:448
	ds_read_b128 v[104:107], v168 offset:1152
	ds_read_b128 v[108:111], v168 offset:3200
	ds_read_b128 v[112:115], v168 offset:5248
	ds_read_b128 v[116:119], v168 offset:7296
	ds_read_b128 v[120:123], v168 offset:1216
	ds_read_b128 v[124:127], v168 offset:3264
	ds_read_b128 v[128:131], v168 offset:5312
	ds_read_b128 v[132:135], v168 offset:7360
	ds_read_b64_tr_b16 v[140:141], v166 offset:17664
	ds_read_b64_tr_b16 v[142:143], v166 offset:26368
	ds_read_b64_tr_b16 v[144:145], v166 offset:17696
	ds_read_b64_tr_b16 v[146:147], v166 offset:26400
	s_waitcnt lgkmcnt(4)
	v_subrev_u32_e32 v236, 32, v175
	v_cmp_gt_i32_e64 s[78:79], v236, 0
	v_cmp_gt_i32_e64 s[80:81], v236, 1
	v_cmp_gt_i32_e64 s[82:83], v236, 2
	v_cmp_gt_i32_e64 s[84:85], v236, 3
	v_cmp_eq_u32_e64 s[86:87], v236, 0
	v_cmp_eq_u32_e64 s[88:89], v236, 1
	v_cmp_eq_u32_e64 s[90:91], v236, 2
	v_cmp_eq_u32_e64 s[92:93], v236, 3
	v_cndmask_b32_e64 v237, v116, v112, s[78:79]
	v_cndmask_b32_e64 v238, v157, v156, s[78:79]
	v_sub_f32_e32 v237, v238, v237
	v_min_f32_e32 v237, 0, v237
	v_mul_f32_e32 v237, 0x3fb8aa3b, v237
	v_exp_f32_e32 v237, v237
	v_cndmask_b32_e64 v239, v108, v104, s[78:79]
	v_add_f32_e32 v240, v104, v108
	v_mul_f32_e32 v237, v239, v237
	v_cndmask_b32_e64 v237, v237, v240, s[86:87]
	v_mul_f32_e32 v241, v96, v237
	v_cndmask_b32_e64 v237, v117, v113, s[80:81]
	v_cndmask_b32_e64 v238, v157, v156, s[80:81]
	v_sub_f32_e32 v237, v238, v237
	v_min_f32_e32 v237, 0, v237
	v_mul_f32_e32 v237, 0x3fb8aa3b, v237
	v_exp_f32_e32 v237, v237
	v_cndmask_b32_e64 v239, v109, v105, s[80:81]
	v_add_f32_e32 v240, v105, v109
	v_mul_f32_e32 v237, v239, v237
	v_cndmask_b32_e64 v237, v237, v240, s[88:89]
	v_mul_f32_e32 v242, v97, v237
	v_cndmask_b32_e64 v237, v118, v114, s[82:83]
	v_cndmask_b32_e64 v238, v157, v156, s[82:83]
	v_sub_f32_e32 v237, v238, v237
	v_min_f32_e32 v237, 0, v237
	v_mul_f32_e32 v237, 0x3fb8aa3b, v237
	v_exp_f32_e32 v237, v237
	v_cndmask_b32_e64 v239, v110, v106, s[82:83]
	v_add_f32_e32 v240, v106, v110
	v_mul_f32_e32 v237, v239, v237
	v_cndmask_b32_e64 v237, v237, v240, s[90:91]
	v_mul_f32_e32 v243, v98, v237
	v_cndmask_b32_e64 v237, v119, v115, s[84:85]
	v_cndmask_b32_e64 v238, v157, v156, s[84:85]
	v_sub_f32_e32 v237, v238, v237
	v_min_f32_e32 v237, 0, v237
	v_mul_f32_e32 v237, 0x3fb8aa3b, v237
	v_exp_f32_e32 v237, v237
	v_cndmask_b32_e64 v239, v111, v107, s[84:85]
	v_add_f32_e32 v240, v107, v111
	v_mul_f32_e32 v237, v239, v237
	v_cndmask_b32_e64 v237, v237, v240, s[92:93]
	v_mul_f32_e32 v244, v99, v237
	ds_read_b64_tr_b16 v[148:149], v166 offset:17728
	ds_read_b64_tr_b16 v[150:151], v166 offset:26432
	ds_read_b64_tr_b16 v[152:153], v166 offset:17760
	ds_read_b64_tr_b16 v[154:155], v166 offset:26464
	v_subrev_u32_e32 v236, 48, v175
	v_cmp_gt_i32_e64 s[78:79], v236, 0
	v_cmp_gt_i32_e64 s[80:81], v236, 1
	v_cmp_gt_i32_e64 s[82:83], v236, 2
	v_cmp_gt_i32_e64 s[84:85], v236, 3
	v_cmp_eq_u32_e64 s[86:87], v236, 0
	v_cmp_eq_u32_e64 s[88:89], v236, 1
	v_cmp_eq_u32_e64 s[90:91], v236, 2
	v_cmp_eq_u32_e64 s[92:93], v236, 3
	v_cndmask_b32_e64 v237, v132, v128, s[78:79]
	v_cndmask_b32_e64 v238, v157, v156, s[78:79]
	v_sub_f32_e32 v237, v238, v237
	v_min_f32_e32 v237, 0, v237
	v_mul_f32_e32 v237, 0x3fb8aa3b, v237
	v_exp_f32_e32 v237, v237
	v_cndmask_b32_e64 v239, v124, v120, s[78:79]
	v_add_f32_e32 v240, v120, v124
	v_mul_f32_e32 v237, v239, v237
	v_cndmask_b32_e64 v237, v237, v240, s[86:87]
	v_mul_f32_e32 v245, v100, v237
	v_cndmask_b32_e64 v237, v133, v129, s[80:81]
	v_cndmask_b32_e64 v238, v157, v156, s[80:81]
	v_sub_f32_e32 v237, v238, v237
	v_min_f32_e32 v237, 0, v237
	v_mul_f32_e32 v237, 0x3fb8aa3b, v237
	v_exp_f32_e32 v237, v237
	v_cndmask_b32_e64 v239, v125, v121, s[80:81]
	v_add_f32_e32 v240, v121, v125
	v_mul_f32_e32 v237, v239, v237
	v_cndmask_b32_e64 v237, v237, v240, s[88:89]
	v_mul_f32_e32 v246, v101, v237
	v_cndmask_b32_e64 v237, v134, v130, s[82:83]
	v_cndmask_b32_e64 v238, v157, v156, s[82:83]
	v_sub_f32_e32 v237, v238, v237
	v_min_f32_e32 v237, 0, v237
	v_mul_f32_e32 v237, 0x3fb8aa3b, v237
	v_exp_f32_e32 v237, v237
	v_cndmask_b32_e64 v239, v126, v122, s[82:83]
	v_add_f32_e32 v240, v122, v126
	v_mul_f32_e32 v237, v239, v237
	v_cndmask_b32_e64 v237, v237, v240, s[90:91]
	v_mul_f32_e32 v247, v102, v237
	v_cndmask_b32_e64 v237, v135, v131, s[84:85]
	v_cndmask_b32_e64 v238, v157, v156, s[84:85]
	v_sub_f32_e32 v237, v238, v237
	v_min_f32_e32 v237, 0, v237
	v_mul_f32_e32 v237, 0x3fb8aa3b, v237
	v_exp_f32_e32 v237, v237
	v_cndmask_b32_e64 v239, v127, v123, s[84:85]
	v_add_f32_e32 v240, v123, v127
	v_mul_f32_e32 v237, v239, v237
	v_cndmask_b32_e64 v237, v237, v240, s[92:93]
	v_mul_f32_e32 v248, v103, v237
	v_cvt_pk_bf16_f32 v136, v241, v242
	v_cvt_pk_bf16_f32 v137, v243, v244
	v_cvt_pk_bf16_f32 v138, v245, v246
	v_cvt_pk_bf16_f32 v139, v247, v248
	s_waitcnt lgkmcnt(0)
	s_nop 1
	v_mfma_f32_16x16x32_bf16 v[16:19], v[136:139], v[140:143], v[16:19]
	v_mfma_f32_16x16x32_bf16 v[20:23], v[136:139], v[144:147], v[20:23]
	v_mfma_f32_16x16x32_bf16 v[24:27], v[136:139], v[148:151], v[24:27]
	v_mfma_f32_16x16x32_bf16 v[28:31], v[136:139], v[152:155], v[28:31]
	ds_read_b128 v[104:107], v168 offset:1664
	ds_read_b128 v[108:111], v168 offset:3712
	ds_read_b128 v[112:115], v168 offset:5760
	ds_read_b128 v[116:119], v168 offset:7808
	ds_read_b128 v[120:123], v168 offset:1728
	ds_read_b128 v[124:127], v168 offset:3776
	ds_read_b128 v[128:131], v168 offset:5824
	ds_read_b128 v[132:135], v168 offset:7872
	ds_read_b64_tr_b16 v[140:141], v166 offset:17792
	ds_read_b64_tr_b16 v[142:143], v166 offset:26496
	ds_read_b64_tr_b16 v[144:145], v166 offset:17824
	ds_read_b64_tr_b16 v[146:147], v166 offset:26528
	s_waitcnt lgkmcnt(4)
	v_subrev_u32_e32 v236, 32, v175
	v_cmp_gt_i32_e64 s[78:79], v236, 0
	v_cmp_gt_i32_e64 s[80:81], v236, 1
	v_cmp_gt_i32_e64 s[82:83], v236, 2
	v_cmp_gt_i32_e64 s[84:85], v236, 3
	v_cmp_eq_u32_e64 s[86:87], v236, 0
	v_cmp_eq_u32_e64 s[88:89], v236, 1
	v_cmp_eq_u32_e64 s[90:91], v236, 2
	v_cmp_eq_u32_e64 s[92:93], v236, 3
	v_cndmask_b32_e64 v237, v116, v112, s[78:79]
	v_cndmask_b32_e64 v238, v159, v158, s[78:79]
	v_sub_f32_e32 v237, v238, v237
	v_min_f32_e32 v237, 0, v237
	v_mul_f32_e32 v237, 0x3fb8aa3b, v237
	v_exp_f32_e32 v237, v237
	v_cndmask_b32_e64 v239, v108, v104, s[78:79]
	v_add_f32_e32 v240, v104, v108
	v_mul_f32_e32 v237, v239, v237
	v_cndmask_b32_e64 v237, v237, v240, s[86:87]
	v_mul_f32_e32 v241, v96, v237
	v_cndmask_b32_e64 v237, v117, v113, s[80:81]
	v_cndmask_b32_e64 v238, v159, v158, s[80:81]
	v_sub_f32_e32 v237, v238, v237
	v_min_f32_e32 v237, 0, v237
	v_mul_f32_e32 v237, 0x3fb8aa3b, v237
	v_exp_f32_e32 v237, v237
	v_cndmask_b32_e64 v239, v109, v105, s[80:81]
	v_add_f32_e32 v240, v105, v109
	v_mul_f32_e32 v237, v239, v237
	v_cndmask_b32_e64 v237, v237, v240, s[88:89]
	v_mul_f32_e32 v242, v97, v237
	v_cndmask_b32_e64 v237, v118, v114, s[82:83]
	v_cndmask_b32_e64 v238, v159, v158, s[82:83]
	v_sub_f32_e32 v237, v238, v237
	v_min_f32_e32 v237, 0, v237
	v_mul_f32_e32 v237, 0x3fb8aa3b, v237
	v_exp_f32_e32 v237, v237
	v_cndmask_b32_e64 v239, v110, v106, s[82:83]
	v_add_f32_e32 v240, v106, v110
	v_mul_f32_e32 v237, v239, v237
	v_cndmask_b32_e64 v237, v237, v240, s[90:91]
	v_mul_f32_e32 v243, v98, v237
	v_cndmask_b32_e64 v237, v119, v115, s[84:85]
	v_cndmask_b32_e64 v238, v159, v158, s[84:85]
	v_sub_f32_e32 v237, v238, v237
	v_min_f32_e32 v237, 0, v237
	v_mul_f32_e32 v237, 0x3fb8aa3b, v237
	v_exp_f32_e32 v237, v237
	v_cndmask_b32_e64 v239, v111, v107, s[84:85]
	v_add_f32_e32 v240, v107, v111
	v_mul_f32_e32 v237, v239, v237
	v_cndmask_b32_e64 v237, v237, v240, s[92:93]
	v_mul_f32_e32 v244, v99, v237
	ds_read_b64_tr_b16 v[148:149], v166 offset:17856
	ds_read_b64_tr_b16 v[150:151], v166 offset:26560
	ds_read_b64_tr_b16 v[152:153], v166 offset:17888
	ds_read_b64_tr_b16 v[154:155], v166 offset:26592
	v_subrev_u32_e32 v236, 48, v175
	v_cmp_gt_i32_e64 s[78:79], v236, 0
	v_cmp_gt_i32_e64 s[80:81], v236, 1
	v_cmp_gt_i32_e64 s[82:83], v236, 2
	v_cmp_gt_i32_e64 s[84:85], v236, 3
	v_cmp_eq_u32_e64 s[86:87], v236, 0
	v_cmp_eq_u32_e64 s[88:89], v236, 1
	v_cmp_eq_u32_e64 s[90:91], v236, 2
	v_cmp_eq_u32_e64 s[92:93], v236, 3
	v_cndmask_b32_e64 v237, v132, v128, s[78:79]
	v_cndmask_b32_e64 v238, v159, v158, s[78:79]
	v_sub_f32_e32 v237, v238, v237
	v_min_f32_e32 v237, 0, v237
	v_mul_f32_e32 v237, 0x3fb8aa3b, v237
	v_exp_f32_e32 v237, v237
	v_cndmask_b32_e64 v239, v124, v120, s[78:79]
	v_add_f32_e32 v240, v120, v124
	v_mul_f32_e32 v237, v239, v237
	v_cndmask_b32_e64 v237, v237, v240, s[86:87]
	v_mul_f32_e32 v245, v100, v237
	v_cndmask_b32_e64 v237, v133, v129, s[80:81]
	v_cndmask_b32_e64 v238, v159, v158, s[80:81]
	v_sub_f32_e32 v237, v238, v237
	v_min_f32_e32 v237, 0, v237
	v_mul_f32_e32 v237, 0x3fb8aa3b, v237
	v_exp_f32_e32 v237, v237
	v_cndmask_b32_e64 v239, v125, v121, s[80:81]
	v_add_f32_e32 v240, v121, v125
	v_mul_f32_e32 v237, v239, v237
	v_cndmask_b32_e64 v237, v237, v240, s[88:89]
	v_mul_f32_e32 v246, v101, v237
	v_cndmask_b32_e64 v237, v134, v130, s[82:83]
	v_cndmask_b32_e64 v238, v159, v158, s[82:83]
	v_sub_f32_e32 v237, v238, v237
	v_min_f32_e32 v237, 0, v237
	v_mul_f32_e32 v237, 0x3fb8aa3b, v237
	v_exp_f32_e32 v237, v237
	v_cndmask_b32_e64 v239, v126, v122, s[82:83]
	v_add_f32_e32 v240, v122, v126
	v_mul_f32_e32 v237, v239, v237
	v_cndmask_b32_e64 v237, v237, v240, s[90:91]
	v_mul_f32_e32 v247, v102, v237
	v_cndmask_b32_e64 v237, v135, v131, s[84:85]
	v_cndmask_b32_e64 v238, v159, v158, s[84:85]
	v_sub_f32_e32 v237, v238, v237
	v_min_f32_e32 v237, 0, v237
	v_mul_f32_e32 v237, 0x3fb8aa3b, v237
	v_exp_f32_e32 v237, v237
	v_cndmask_b32_e64 v239, v127, v123, s[84:85]
	v_add_f32_e32 v240, v123, v127
	v_mul_f32_e32 v237, v239, v237
	v_cndmask_b32_e64 v237, v237, v240, s[92:93]
	v_mul_f32_e32 v248, v103, v237
	v_cvt_pk_bf16_f32 v136, v241, v242
	v_cvt_pk_bf16_f32 v137, v243, v244
	v_cvt_pk_bf16_f32 v138, v245, v246
	v_cvt_pk_bf16_f32 v139, v247, v248
	s_waitcnt lgkmcnt(0)
	s_nop 1
	v_mfma_f32_16x16x32_bf16 v[32:35], v[136:139], v[140:143], v[32:35]
	v_mfma_f32_16x16x32_bf16 v[36:39], v[136:139], v[144:147], v[36:39]
	v_mfma_f32_16x16x32_bf16 v[40:43], v[136:139], v[148:151], v[40:43]
	v_mfma_f32_16x16x32_bf16 v[44:47], v[136:139], v[152:155], v[44:47]
	s_waitcnt vmcnt(0)
	v_mfma_f32_16x16x32_bf16 v[96:99], v[64:67], v[48:51], 0
	v_mfma_f32_16x16x32_bf16 v[96:99], v[68:71], v[52:55], v[96:99]
	v_mfma_f32_16x16x32_bf16 v[96:99], v[72:75], v[56:59], v[96:99]
	v_mfma_f32_16x16x32_bf16 v[96:99], v[76:79], v[60:63], v[96:99]
	v_mfma_f32_16x16x32_bf16 v[100:103], v[80:83], v[48:51], 0
	v_mfma_f32_16x16x32_bf16 v[100:103], v[84:87], v[52:55], v[100:103]
	v_mfma_f32_16x16x32_bf16 v[100:103], v[88:91], v[56:59], v[100:103]
	v_mfma_f32_16x16x32_bf16 v[100:103], v[92:95], v[60:63], v[100:103]
	s_add_u32 s52, s40, 0x24000
	s_addc_u32 s53, s41, 0
	global_load_dwordx4 v[64:67], v169, s[52:53] offset:256
	global_load_dwordx4 v[68:71], v169, s[52:53] offset:320
	global_load_dwordx4 v[72:75], v169, s[52:53] offset:384
	global_load_dwordx4 v[76:79], v169, s[52:53] offset:448
	s_add_u32 s52, s40, 0x2a000
	s_addc_u32 s53, s41, 0
	global_load_dwordx4 v[80:83], v169, s[52:53] offset:256
	global_load_dwordx4 v[84:87], v169, s[52:53] offset:320
	global_load_dwordx4 v[88:91], v169, s[52:53] offset:384
	global_load_dwordx4 v[92:95], v169, s[52:53] offset:448
	ds_read_b128 v[104:107], v168 offset:1280
	ds_read_b128 v[108:111], v168 offset:3328
	ds_read_b128 v[112:115], v168 offset:5376
	ds_read_b128 v[116:119], v168 offset:7424
	ds_read_b128 v[120:123], v168 offset:1344
	ds_read_b128 v[124:127], v168 offset:3392
	ds_read_b128 v[128:131], v168 offset:5440
	ds_read_b128 v[132:135], v168 offset:7488
	ds_read_b64_tr_b16 v[140:141], v166 offset:35072
	ds_read_b64_tr_b16 v[142:143], v166 offset:43776
	ds_read_b64_tr_b16 v[144:145], v166 offset:35104
	ds_read_b64_tr_b16 v[146:147], v166 offset:43808
	s_waitcnt lgkmcnt(4)
	v_subrev_u32_e32 v236, 64, v175
	v_cmp_gt_i32_e64 s[78:79], v236, 0
	v_cmp_gt_i32_e64 s[80:81], v236, 1
	v_cmp_gt_i32_e64 s[82:83], v236, 2
	v_cmp_gt_i32_e64 s[84:85], v236, 3
	v_cmp_eq_u32_e64 s[86:87], v236, 0
	v_cmp_eq_u32_e64 s[88:89], v236, 1
	v_cmp_eq_u32_e64 s[90:91], v236, 2
	v_cmp_eq_u32_e64 s[92:93], v236, 3
	v_cndmask_b32_e64 v237, v116, v112, s[78:79]
	v_cndmask_b32_e64 v238, v157, v156, s[78:79]
	v_sub_f32_e32 v237, v238, v237
	v_min_f32_e32 v237, 0, v237
	v_mul_f32_e32 v237, 0x3fb8aa3b, v237
	v_exp_f32_e32 v237, v237
	v_cndmask_b32_e64 v239, v108, v104, s[78:79]
	v_add_f32_e32 v240, v104, v108
	v_mul_f32_e32 v237, v239, v237
	v_cndmask_b32_e64 v237, v237, v240, s[86:87]
	v_mul_f32_e32 v241, v96, v237
	v_cndmask_b32_e64 v237, v117, v113, s[80:81]
	v_cndmask_b32_e64 v238, v157, v156, s[80:81]
	v_sub_f32_e32 v237, v238, v237
	v_min_f32_e32 v237, 0, v237
	v_mul_f32_e32 v237, 0x3fb8aa3b, v237
	v_exp_f32_e32 v237, v237
	v_cndmask_b32_e64 v239, v109, v105, s[80:81]
	v_add_f32_e32 v240, v105, v109
	v_mul_f32_e32 v237, v239, v237
	v_cndmask_b32_e64 v237, v237, v240, s[88:89]
	v_mul_f32_e32 v242, v97, v237
	v_cndmask_b32_e64 v237, v118, v114, s[82:83]
	v_cndmask_b32_e64 v238, v157, v156, s[82:83]
	v_sub_f32_e32 v237, v238, v237
	v_min_f32_e32 v237, 0, v237
	v_mul_f32_e32 v237, 0x3fb8aa3b, v237
	v_exp_f32_e32 v237, v237
	v_cndmask_b32_e64 v239, v110, v106, s[82:83]
	v_add_f32_e32 v240, v106, v110
	v_mul_f32_e32 v237, v239, v237
	v_cndmask_b32_e64 v237, v237, v240, s[90:91]
	v_mul_f32_e32 v243, v98, v237
	v_cndmask_b32_e64 v237, v119, v115, s[84:85]
	v_cndmask_b32_e64 v238, v157, v156, s[84:85]
	v_sub_f32_e32 v237, v238, v237
	v_min_f32_e32 v237, 0, v237
	v_mul_f32_e32 v237, 0x3fb8aa3b, v237
	v_exp_f32_e32 v237, v237
	v_cndmask_b32_e64 v239, v111, v107, s[84:85]
	v_add_f32_e32 v240, v107, v111
	v_mul_f32_e32 v237, v239, v237
	v_cndmask_b32_e64 v237, v237, v240, s[92:93]
	v_mul_f32_e32 v244, v99, v237
	ds_read_b64_tr_b16 v[148:149], v166 offset:35136
	ds_read_b64_tr_b16 v[150:151], v166 offset:43840
	ds_read_b64_tr_b16 v[152:153], v166 offset:35168
	ds_read_b64_tr_b16 v[154:155], v166 offset:43872
	v_subrev_u32_e32 v236, 80, v175
	v_cmp_gt_i32_e64 s[78:79], v236, 0
	v_cmp_gt_i32_e64 s[80:81], v236, 1
	v_cmp_gt_i32_e64 s[82:83], v236, 2
	v_cmp_gt_i32_e64 s[84:85], v236, 3
	v_cmp_eq_u32_e64 s[86:87], v236, 0
	v_cmp_eq_u32_e64 s[88:89], v236, 1
	v_cmp_eq_u32_e64 s[90:91], v236, 2
	v_cmp_eq_u32_e64 s[92:93], v236, 3
	v_cndmask_b32_e64 v237, v132, v128, s[78:79]
	v_cndmask_b32_e64 v238, v157, v156, s[78:79]
	v_sub_f32_e32 v237, v238, v237
	v_min_f32_e32 v237, 0, v237
	v_mul_f32_e32 v237, 0x3fb8aa3b, v237
	v_exp_f32_e32 v237, v237
	v_cndmask_b32_e64 v239, v124, v120, s[78:79]
	v_add_f32_e32 v240, v120, v124
	v_mul_f32_e32 v237, v239, v237
	v_cndmask_b32_e64 v237, v237, v240, s[86:87]
	v_mul_f32_e32 v245, v100, v237
	v_cndmask_b32_e64 v237, v133, v129, s[80:81]
	v_cndmask_b32_e64 v238, v157, v156, s[80:81]
	v_sub_f32_e32 v237, v238, v237
	v_min_f32_e32 v237, 0, v237
	v_mul_f32_e32 v237, 0x3fb8aa3b, v237
	v_exp_f32_e32 v237, v237
	v_cndmask_b32_e64 v239, v125, v121, s[80:81]
	v_add_f32_e32 v240, v121, v125
	v_mul_f32_e32 v237, v239, v237
	v_cndmask_b32_e64 v237, v237, v240, s[88:89]
	v_mul_f32_e32 v246, v101, v237
	v_cndmask_b32_e64 v237, v134, v130, s[82:83]
	v_cndmask_b32_e64 v238, v157, v156, s[82:83]
	v_sub_f32_e32 v237, v238, v237
	v_min_f32_e32 v237, 0, v237
	v_mul_f32_e32 v237, 0x3fb8aa3b, v237
	v_exp_f32_e32 v237, v237
	v_cndmask_b32_e64 v239, v126, v122, s[82:83]
	v_add_f32_e32 v240, v122, v126
	v_mul_f32_e32 v237, v239, v237
	v_cndmask_b32_e64 v237, v237, v240, s[90:91]
	v_mul_f32_e32 v247, v102, v237
	v_cndmask_b32_e64 v237, v135, v131, s[84:85]
	v_cndmask_b32_e64 v238, v157, v156, s[84:85]
	v_sub_f32_e32 v237, v238, v237
	v_min_f32_e32 v237, 0, v237
	v_mul_f32_e32 v237, 0x3fb8aa3b, v237
	v_exp_f32_e32 v237, v237
	v_cndmask_b32_e64 v239, v127, v123, s[84:85]
	v_add_f32_e32 v240, v123, v127
	v_mul_f32_e32 v237, v239, v237
	v_cndmask_b32_e64 v237, v237, v240, s[92:93]
	v_mul_f32_e32 v248, v103, v237
	v_cvt_pk_bf16_f32 v136, v241, v242
	v_cvt_pk_bf16_f32 v137, v243, v244
	v_cvt_pk_bf16_f32 v138, v245, v246
	v_cvt_pk_bf16_f32 v139, v247, v248
	s_waitcnt lgkmcnt(0)
	s_nop 1
	v_mfma_f32_16x16x32_bf16 v[16:19], v[136:139], v[140:143], v[16:19]
	v_mfma_f32_16x16x32_bf16 v[20:23], v[136:139], v[144:147], v[20:23]
	v_mfma_f32_16x16x32_bf16 v[24:27], v[136:139], v[148:151], v[24:27]
	v_mfma_f32_16x16x32_bf16 v[28:31], v[136:139], v[152:155], v[28:31]
	ds_read_b128 v[104:107], v168 offset:1792
	ds_read_b128 v[108:111], v168 offset:3840
	ds_read_b128 v[112:115], v168 offset:5888
	ds_read_b128 v[116:119], v168 offset:7936
	ds_read_b128 v[120:123], v168 offset:1856
	ds_read_b128 v[124:127], v168 offset:3904
	ds_read_b128 v[128:131], v168 offset:5952
	ds_read_b128 v[132:135], v168 offset:8000
	ds_read_b64_tr_b16 v[140:141], v166 offset:35200
	ds_read_b64_tr_b16 v[142:143], v166 offset:43904
	ds_read_b64_tr_b16 v[144:145], v166 offset:35232
	ds_read_b64_tr_b16 v[146:147], v166 offset:43936
	s_waitcnt lgkmcnt(4)
	v_subrev_u32_e32 v236, 64, v175
	v_cmp_gt_i32_e64 s[78:79], v236, 0
	v_cmp_gt_i32_e64 s[80:81], v236, 1
	v_cmp_gt_i32_e64 s[82:83], v236, 2
	v_cmp_gt_i32_e64 s[84:85], v236, 3
	v_cmp_eq_u32_e64 s[86:87], v236, 0
	v_cmp_eq_u32_e64 s[88:89], v236, 1
	v_cmp_eq_u32_e64 s[90:91], v236, 2
	v_cmp_eq_u32_e64 s[92:93], v236, 3
	v_cndmask_b32_e64 v237, v116, v112, s[78:79]
	v_cndmask_b32_e64 v238, v159, v158, s[78:79]
	v_sub_f32_e32 v237, v238, v237
	v_min_f32_e32 v237, 0, v237
	v_mul_f32_e32 v237, 0x3fb8aa3b, v237
	v_exp_f32_e32 v237, v237
	v_cndmask_b32_e64 v239, v108, v104, s[78:79]
	v_add_f32_e32 v240, v104, v108
	v_mul_f32_e32 v237, v239, v237
	v_cndmask_b32_e64 v237, v237, v240, s[86:87]
	v_mul_f32_e32 v241, v96, v237
	v_cndmask_b32_e64 v237, v117, v113, s[80:81]
	v_cndmask_b32_e64 v238, v159, v158, s[80:81]
	v_sub_f32_e32 v237, v238, v237
	v_min_f32_e32 v237, 0, v237
	v_mul_f32_e32 v237, 0x3fb8aa3b, v237
	v_exp_f32_e32 v237, v237
	v_cndmask_b32_e64 v239, v109, v105, s[80:81]
	v_add_f32_e32 v240, v105, v109
	v_mul_f32_e32 v237, v239, v237
	v_cndmask_b32_e64 v237, v237, v240, s[88:89]
	v_mul_f32_e32 v242, v97, v237
	v_cndmask_b32_e64 v237, v118, v114, s[82:83]
	v_cndmask_b32_e64 v238, v159, v158, s[82:83]
	v_sub_f32_e32 v237, v238, v237
	v_min_f32_e32 v237, 0, v237
	v_mul_f32_e32 v237, 0x3fb8aa3b, v237
	v_exp_f32_e32 v237, v237
	v_cndmask_b32_e64 v239, v110, v106, s[82:83]
	v_add_f32_e32 v240, v106, v110
	v_mul_f32_e32 v237, v239, v237
	v_cndmask_b32_e64 v237, v237, v240, s[90:91]
	v_mul_f32_e32 v243, v98, v237
	v_cndmask_b32_e64 v237, v119, v115, s[84:85]
	v_cndmask_b32_e64 v238, v159, v158, s[84:85]
	v_sub_f32_e32 v237, v238, v237
	v_min_f32_e32 v237, 0, v237
	v_mul_f32_e32 v237, 0x3fb8aa3b, v237
	v_exp_f32_e32 v237, v237
	v_cndmask_b32_e64 v239, v111, v107, s[84:85]
	v_add_f32_e32 v240, v107, v111
	v_mul_f32_e32 v237, v239, v237
	v_cndmask_b32_e64 v237, v237, v240, s[92:93]
	v_mul_f32_e32 v244, v99, v237
	ds_read_b64_tr_b16 v[148:149], v166 offset:35264
	ds_read_b64_tr_b16 v[150:151], v166 offset:43968
	ds_read_b64_tr_b16 v[152:153], v166 offset:35296
	ds_read_b64_tr_b16 v[154:155], v166 offset:44000
	v_subrev_u32_e32 v236, 80, v175
	v_cmp_gt_i32_e64 s[78:79], v236, 0
	v_cmp_gt_i32_e64 s[80:81], v236, 1
	v_cmp_gt_i32_e64 s[82:83], v236, 2
	v_cmp_gt_i32_e64 s[84:85], v236, 3
	v_cmp_eq_u32_e64 s[86:87], v236, 0
	v_cmp_eq_u32_e64 s[88:89], v236, 1
	v_cmp_eq_u32_e64 s[90:91], v236, 2
	v_cmp_eq_u32_e64 s[92:93], v236, 3
	v_cndmask_b32_e64 v237, v132, v128, s[78:79]
	v_cndmask_b32_e64 v238, v159, v158, s[78:79]
	v_sub_f32_e32 v237, v238, v237
	v_min_f32_e32 v237, 0, v237
	v_mul_f32_e32 v237, 0x3fb8aa3b, v237
	v_exp_f32_e32 v237, v237
	v_cndmask_b32_e64 v239, v124, v120, s[78:79]
	v_add_f32_e32 v240, v120, v124
	v_mul_f32_e32 v237, v239, v237
	v_cndmask_b32_e64 v237, v237, v240, s[86:87]
	v_mul_f32_e32 v245, v100, v237
	v_cndmask_b32_e64 v237, v133, v129, s[80:81]
	v_cndmask_b32_e64 v238, v159, v158, s[80:81]
	v_sub_f32_e32 v237, v238, v237
	v_min_f32_e32 v237, 0, v237
	v_mul_f32_e32 v237, 0x3fb8aa3b, v237
	v_exp_f32_e32 v237, v237
	v_cndmask_b32_e64 v239, v125, v121, s[80:81]
	v_add_f32_e32 v240, v121, v125
	v_mul_f32_e32 v237, v239, v237
	v_cndmask_b32_e64 v237, v237, v240, s[88:89]
	v_mul_f32_e32 v246, v101, v237
	v_cndmask_b32_e64 v237, v134, v130, s[82:83]
	v_cndmask_b32_e64 v238, v159, v158, s[82:83]
	v_sub_f32_e32 v237, v238, v237
	v_min_f32_e32 v237, 0, v237
	v_mul_f32_e32 v237, 0x3fb8aa3b, v237
	v_exp_f32_e32 v237, v237
	v_cndmask_b32_e64 v239, v126, v122, s[82:83]
	v_add_f32_e32 v240, v122, v126
	v_mul_f32_e32 v237, v239, v237
	v_cndmask_b32_e64 v237, v237, v240, s[90:91]
	v_mul_f32_e32 v247, v102, v237
	v_cndmask_b32_e64 v237, v135, v131, s[84:85]
	v_cndmask_b32_e64 v238, v159, v158, s[84:85]
	v_sub_f32_e32 v237, v238, v237
	v_min_f32_e32 v237, 0, v237
	v_mul_f32_e32 v237, 0x3fb8aa3b, v237
	v_exp_f32_e32 v237, v237
	v_cndmask_b32_e64 v239, v127, v123, s[84:85]
	v_add_f32_e32 v240, v123, v127
	v_mul_f32_e32 v237, v239, v237
	v_cndmask_b32_e64 v237, v237, v240, s[92:93]
	v_mul_f32_e32 v248, v103, v237
	v_cvt_pk_bf16_f32 v136, v241, v242
	v_cvt_pk_bf16_f32 v137, v243, v244
	v_cvt_pk_bf16_f32 v138, v245, v246
	v_cvt_pk_bf16_f32 v139, v247, v248
	s_waitcnt lgkmcnt(0)
	s_nop 1
	v_mfma_f32_16x16x32_bf16 v[32:35], v[136:139], v[140:143], v[32:35]
	v_mfma_f32_16x16x32_bf16 v[36:39], v[136:139], v[144:147], v[36:39]
	v_mfma_f32_16x16x32_bf16 v[40:43], v[136:139], v[148:151], v[40:43]
	v_mfma_f32_16x16x32_bf16 v[44:47], v[136:139], v[152:155], v[44:47]
	s_waitcnt vmcnt(0)
	v_mfma_f32_16x16x32_bf16 v[96:99], v[64:67], v[48:51], 0
	v_mfma_f32_16x16x32_bf16 v[96:99], v[68:71], v[52:55], v[96:99]
	v_mfma_f32_16x16x32_bf16 v[96:99], v[72:75], v[56:59], v[96:99]
	v_mfma_f32_16x16x32_bf16 v[96:99], v[76:79], v[60:63], v[96:99]
	v_mfma_f32_16x16x32_bf16 v[100:103], v[80:83], v[48:51], 0
	v_mfma_f32_16x16x32_bf16 v[100:103], v[84:87], v[52:55], v[100:103]
	v_mfma_f32_16x16x32_bf16 v[100:103], v[88:91], v[56:59], v[100:103]
	v_mfma_f32_16x16x32_bf16 v[100:103], v[92:95], v[60:63], v[100:103]
	s_add_u32 s52, s42, 0x10000
	s_addc_u32 s53, s43, 0
	global_load_dwordx4 v[64:67], v170, s[52:53] offset:0
	global_load_dwordx4 v[68:71], v171, s[52:53] offset:0
	global_load_dwordx4 v[72:75], v172, s[52:53] offset:0
	global_load_dwordx4 v[76:79], v173, s[52:53] offset:0
	s_add_u32 s52, s42, 0x10000
	s_addc_u32 s53, s43, 0
	global_load_dwordx4 v[80:83], v170, s[52:53] offset:64
	global_load_dwordx4 v[84:87], v171, s[52:53] offset:64
	global_load_dwordx4 v[88:91], v172, s[52:53] offset:64
	global_load_dwordx4 v[92:95], v173, s[52:53] offset:64
	ds_read_b128 v[104:107], v168 offset:1408
	ds_read_b128 v[108:111], v168 offset:3456
	ds_read_b128 v[112:115], v168 offset:5504
	ds_read_b128 v[116:119], v168 offset:7552
	ds_read_b128 v[120:123], v168 offset:1472
	ds_read_b128 v[124:127], v168 offset:3520
	ds_read_b128 v[128:131], v168 offset:5568
	ds_read_b128 v[132:135], v168 offset:7616
	ds_read_b64_tr_b16 v[140:141], v166 offset:52480
	ds_read_b64_tr_b16 v[142:143], v166 offset:61184
	ds_read_b64_tr_b16 v[144:145], v166 offset:52512
	ds_read_b64_tr_b16 v[146:147], v166 offset:61216
	s_waitcnt lgkmcnt(4)
	v_subrev_u32_e32 v236, 96, v175
	v_cmp_gt_i32_e64 s[78:79], v236, 0
	v_cmp_gt_i32_e64 s[80:81], v236, 1
	v_cmp_gt_i32_e64 s[82:83], v236, 2
	v_cmp_gt_i32_e64 s[84:85], v236, 3
	v_cmp_eq_u32_e64 s[86:87], v236, 0
	v_cmp_eq_u32_e64 s[88:89], v236, 1
	v_cmp_eq_u32_e64 s[90:91], v236, 2
	v_cmp_eq_u32_e64 s[92:93], v236, 3
	v_cndmask_b32_e64 v237, v116, v112, s[78:79]
	v_cndmask_b32_e64 v238, v157, v156, s[78:79]
	v_sub_f32_e32 v237, v238, v237
	v_min_f32_e32 v237, 0, v237
	v_mul_f32_e32 v237, 0x3fb8aa3b, v237
	v_exp_f32_e32 v237, v237
	v_cndmask_b32_e64 v239, v108, v104, s[78:79]
	v_add_f32_e32 v240, v104, v108
	v_mul_f32_e32 v237, v239, v237
	v_cndmask_b32_e64 v237, v237, v240, s[86:87]
	v_mul_f32_e32 v241, v96, v237
	v_cndmask_b32_e64 v237, v117, v113, s[80:81]
	v_cndmask_b32_e64 v238, v157, v156, s[80:81]
	v_sub_f32_e32 v237, v238, v237
	v_min_f32_e32 v237, 0, v237
	v_mul_f32_e32 v237, 0x3fb8aa3b, v237
	v_exp_f32_e32 v237, v237
	v_cndmask_b32_e64 v239, v109, v105, s[80:81]
	v_add_f32_e32 v240, v105, v109
	v_mul_f32_e32 v237, v239, v237
	v_cndmask_b32_e64 v237, v237, v240, s[88:89]
	v_mul_f32_e32 v242, v97, v237
	v_cndmask_b32_e64 v237, v118, v114, s[82:83]
	v_cndmask_b32_e64 v238, v157, v156, s[82:83]
	v_sub_f32_e32 v237, v238, v237
	v_min_f32_e32 v237, 0, v237
	v_mul_f32_e32 v237, 0x3fb8aa3b, v237
	v_exp_f32_e32 v237, v237
	v_cndmask_b32_e64 v239, v110, v106, s[82:83]
	v_add_f32_e32 v240, v106, v110
	v_mul_f32_e32 v237, v239, v237
	v_cndmask_b32_e64 v237, v237, v240, s[90:91]
	v_mul_f32_e32 v243, v98, v237
	v_cndmask_b32_e64 v237, v119, v115, s[84:85]
	v_cndmask_b32_e64 v238, v157, v156, s[84:85]
	v_sub_f32_e32 v237, v238, v237
	v_min_f32_e32 v237, 0, v237
	v_mul_f32_e32 v237, 0x3fb8aa3b, v237
	v_exp_f32_e32 v237, v237
	v_cndmask_b32_e64 v239, v111, v107, s[84:85]
	v_add_f32_e32 v240, v107, v111
	v_mul_f32_e32 v237, v239, v237
	v_cndmask_b32_e64 v237, v237, v240, s[92:93]
	v_mul_f32_e32 v244, v99, v237
	ds_read_b64_tr_b16 v[148:149], v166 offset:52544
	ds_read_b64_tr_b16 v[150:151], v166 offset:61248
	ds_read_b64_tr_b16 v[152:153], v166 offset:52576
	ds_read_b64_tr_b16 v[154:155], v166 offset:61280
	v_subrev_u32_e32 v236, 112, v175
	v_cmp_gt_i32_e64 s[78:79], v236, 0
	v_cmp_gt_i32_e64 s[80:81], v236, 1
	v_cmp_gt_i32_e64 s[82:83], v236, 2
	v_cmp_gt_i32_e64 s[84:85], v236, 3
	v_cmp_eq_u32_e64 s[86:87], v236, 0
	v_cmp_eq_u32_e64 s[88:89], v236, 1
	v_cmp_eq_u32_e64 s[90:91], v236, 2
	v_cmp_eq_u32_e64 s[92:93], v236, 3
	v_cndmask_b32_e64 v237, v132, v128, s[78:79]
	v_cndmask_b32_e64 v238, v157, v156, s[78:79]
	v_sub_f32_e32 v237, v238, v237
	v_min_f32_e32 v237, 0, v237
	v_mul_f32_e32 v237, 0x3fb8aa3b, v237
	v_exp_f32_e32 v237, v237
	v_cndmask_b32_e64 v239, v124, v120, s[78:79]
	v_add_f32_e32 v240, v120, v124
	v_mul_f32_e32 v237, v239, v237
	v_cndmask_b32_e64 v237, v237, v240, s[86:87]
	v_mul_f32_e32 v245, v100, v237
	v_cndmask_b32_e64 v237, v133, v129, s[80:81]
	v_cndmask_b32_e64 v238, v157, v156, s[80:81]
	v_sub_f32_e32 v237, v238, v237
	v_min_f32_e32 v237, 0, v237
	v_mul_f32_e32 v237, 0x3fb8aa3b, v237
	v_exp_f32_e32 v237, v237
	v_cndmask_b32_e64 v239, v125, v121, s[80:81]
	v_add_f32_e32 v240, v121, v125
	v_mul_f32_e32 v237, v239, v237
	v_cndmask_b32_e64 v237, v237, v240, s[88:89]
	v_mul_f32_e32 v246, v101, v237
	v_cndmask_b32_e64 v237, v134, v130, s[82:83]
	v_cndmask_b32_e64 v238, v157, v156, s[82:83]
	v_sub_f32_e32 v237, v238, v237
	v_min_f32_e32 v237, 0, v237
	v_mul_f32_e32 v237, 0x3fb8aa3b, v237
	v_exp_f32_e32 v237, v237
	v_cndmask_b32_e64 v239, v126, v122, s[82:83]
	v_add_f32_e32 v240, v122, v126
	v_mul_f32_e32 v237, v239, v237
	v_cndmask_b32_e64 v237, v237, v240, s[90:91]
	v_mul_f32_e32 v247, v102, v237
	v_cndmask_b32_e64 v237, v135, v131, s[84:85]
	v_cndmask_b32_e64 v238, v157, v156, s[84:85]
	v_sub_f32_e32 v237, v238, v237
	v_min_f32_e32 v237, 0, v237
	v_mul_f32_e32 v237, 0x3fb8aa3b, v237
	v_exp_f32_e32 v237, v237
	v_cndmask_b32_e64 v239, v127, v123, s[84:85]
	v_add_f32_e32 v240, v123, v127
	v_mul_f32_e32 v237, v239, v237
	v_cndmask_b32_e64 v237, v237, v240, s[92:93]
	v_mul_f32_e32 v248, v103, v237
	v_cvt_pk_bf16_f32 v136, v241, v242
	v_cvt_pk_bf16_f32 v137, v243, v244
	v_cvt_pk_bf16_f32 v138, v245, v246
	v_cvt_pk_bf16_f32 v139, v247, v248
	s_waitcnt lgkmcnt(0)
	s_nop 1
	v_mfma_f32_16x16x32_bf16 v[16:19], v[136:139], v[140:143], v[16:19]
	v_mfma_f32_16x16x32_bf16 v[20:23], v[136:139], v[144:147], v[20:23]
	v_mfma_f32_16x16x32_bf16 v[24:27], v[136:139], v[148:151], v[24:27]
	v_mfma_f32_16x16x32_bf16 v[28:31], v[136:139], v[152:155], v[28:31]
	ds_read_b128 v[104:107], v168 offset:1920
	ds_read_b128 v[108:111], v168 offset:3968
	ds_read_b128 v[112:115], v168 offset:6016
	ds_read_b128 v[116:119], v168 offset:8064
	ds_read_b128 v[120:123], v168 offset:1984
	ds_read_b128 v[124:127], v168 offset:4032
	ds_read_b128 v[128:131], v168 offset:6080
	ds_read_b128 v[132:135], v168 offset:8128
	ds_read_b64_tr_b16 v[140:141], v166 offset:52608
	ds_read_b64_tr_b16 v[142:143], v166 offset:61312
	ds_read_b64_tr_b16 v[144:145], v166 offset:52640
	ds_read_b64_tr_b16 v[146:147], v166 offset:61344
	s_waitcnt lgkmcnt(4)
	v_subrev_u32_e32 v236, 96, v175
	v_cmp_gt_i32_e64 s[78:79], v236, 0
	v_cmp_gt_i32_e64 s[80:81], v236, 1
	v_cmp_gt_i32_e64 s[82:83], v236, 2
	v_cmp_gt_i32_e64 s[84:85], v236, 3
	v_cmp_eq_u32_e64 s[86:87], v236, 0
	v_cmp_eq_u32_e64 s[88:89], v236, 1
	v_cmp_eq_u32_e64 s[90:91], v236, 2
	v_cmp_eq_u32_e64 s[92:93], v236, 3
	v_cndmask_b32_e64 v237, v116, v112, s[78:79]
	v_cndmask_b32_e64 v238, v159, v158, s[78:79]
	v_sub_f32_e32 v237, v238, v237
	v_min_f32_e32 v237, 0, v237
	v_mul_f32_e32 v237, 0x3fb8aa3b, v237
	v_exp_f32_e32 v237, v237
	v_cndmask_b32_e64 v239, v108, v104, s[78:79]
	v_add_f32_e32 v240, v104, v108
	v_mul_f32_e32 v237, v239, v237
	v_cndmask_b32_e64 v237, v237, v240, s[86:87]
	v_mul_f32_e32 v241, v96, v237
	v_cndmask_b32_e64 v237, v117, v113, s[80:81]
	v_cndmask_b32_e64 v238, v159, v158, s[80:81]
	v_sub_f32_e32 v237, v238, v237
	v_min_f32_e32 v237, 0, v237
	v_mul_f32_e32 v237, 0x3fb8aa3b, v237
	v_exp_f32_e32 v237, v237
	v_cndmask_b32_e64 v239, v109, v105, s[80:81]
	v_add_f32_e32 v240, v105, v109
	v_mul_f32_e32 v237, v239, v237
	v_cndmask_b32_e64 v237, v237, v240, s[88:89]
	v_mul_f32_e32 v242, v97, v237
	v_cndmask_b32_e64 v237, v118, v114, s[82:83]
	v_cndmask_b32_e64 v238, v159, v158, s[82:83]
	v_sub_f32_e32 v237, v238, v237
	v_min_f32_e32 v237, 0, v237
	v_mul_f32_e32 v237, 0x3fb8aa3b, v237
	v_exp_f32_e32 v237, v237
	v_cndmask_b32_e64 v239, v110, v106, s[82:83]
	v_add_f32_e32 v240, v106, v110
	v_mul_f32_e32 v237, v239, v237
	v_cndmask_b32_e64 v237, v237, v240, s[90:91]
	v_mul_f32_e32 v243, v98, v237
	v_cndmask_b32_e64 v237, v119, v115, s[84:85]
	v_cndmask_b32_e64 v238, v159, v158, s[84:85]
	v_sub_f32_e32 v237, v238, v237
	v_min_f32_e32 v237, 0, v237
	v_mul_f32_e32 v237, 0x3fb8aa3b, v237
	v_exp_f32_e32 v237, v237
	v_cndmask_b32_e64 v239, v111, v107, s[84:85]
	v_add_f32_e32 v240, v107, v111
	v_mul_f32_e32 v237, v239, v237
	v_cndmask_b32_e64 v237, v237, v240, s[92:93]
	v_mul_f32_e32 v244, v99, v237
	ds_read_b64_tr_b16 v[148:149], v166 offset:52672
	ds_read_b64_tr_b16 v[150:151], v166 offset:61376
	ds_read_b64_tr_b16 v[152:153], v166 offset:52704
	ds_read_b64_tr_b16 v[154:155], v166 offset:61408
	v_subrev_u32_e32 v236, 112, v175
	v_cmp_gt_i32_e64 s[78:79], v236, 0
	v_cmp_gt_i32_e64 s[80:81], v236, 1
	v_cmp_gt_i32_e64 s[82:83], v236, 2
	v_cmp_gt_i32_e64 s[84:85], v236, 3
	v_cmp_eq_u32_e64 s[86:87], v236, 0
	v_cmp_eq_u32_e64 s[88:89], v236, 1
	v_cmp_eq_u32_e64 s[90:91], v236, 2
	v_cmp_eq_u32_e64 s[92:93], v236, 3
	v_cndmask_b32_e64 v237, v132, v128, s[78:79]
	v_cndmask_b32_e64 v238, v159, v158, s[78:79]
	v_sub_f32_e32 v237, v238, v237
	v_min_f32_e32 v237, 0, v237
	v_mul_f32_e32 v237, 0x3fb8aa3b, v237
	v_exp_f32_e32 v237, v237
	v_cndmask_b32_e64 v239, v124, v120, s[78:79]
	v_add_f32_e32 v240, v120, v124
	v_mul_f32_e32 v237, v239, v237
	v_cndmask_b32_e64 v237, v237, v240, s[86:87]
	v_mul_f32_e32 v245, v100, v237
	v_cndmask_b32_e64 v237, v133, v129, s[80:81]
	v_cndmask_b32_e64 v238, v159, v158, s[80:81]
	v_sub_f32_e32 v237, v238, v237
	v_min_f32_e32 v237, 0, v237
	v_mul_f32_e32 v237, 0x3fb8aa3b, v237
	v_exp_f32_e32 v237, v237
	v_cndmask_b32_e64 v239, v125, v121, s[80:81]
	v_add_f32_e32 v240, v121, v125
	v_mul_f32_e32 v237, v239, v237
	v_cndmask_b32_e64 v237, v237, v240, s[88:89]
	v_mul_f32_e32 v246, v101, v237
	v_cndmask_b32_e64 v237, v134, v130, s[82:83]
	v_cndmask_b32_e64 v238, v159, v158, s[82:83]
	v_sub_f32_e32 v237, v238, v237
	v_min_f32_e32 v237, 0, v237
	v_mul_f32_e32 v237, 0x3fb8aa3b, v237
	v_exp_f32_e32 v237, v237
	v_cndmask_b32_e64 v239, v126, v122, s[82:83]
	v_add_f32_e32 v240, v122, v126
	v_mul_f32_e32 v237, v239, v237
	v_cndmask_b32_e64 v237, v237, v240, s[90:91]
	v_mul_f32_e32 v247, v102, v237
	v_cndmask_b32_e64 v237, v135, v131, s[84:85]
	v_cndmask_b32_e64 v238, v159, v158, s[84:85]
	v_sub_f32_e32 v237, v238, v237
	v_min_f32_e32 v237, 0, v237
	v_mul_f32_e32 v237, 0x3fb8aa3b, v237
	v_exp_f32_e32 v237, v237
	v_cndmask_b32_e64 v239, v127, v123, s[84:85]
	v_add_f32_e32 v240, v123, v127
	v_mul_f32_e32 v237, v239, v237
	v_cndmask_b32_e64 v237, v237, v240, s[92:93]
	v_mul_f32_e32 v248, v103, v237
	v_cvt_pk_bf16_f32 v136, v241, v242
	v_cvt_pk_bf16_f32 v137, v243, v244
	v_cvt_pk_bf16_f32 v138, v245, v246
	v_cvt_pk_bf16_f32 v139, v247, v248
	s_waitcnt lgkmcnt(0)
	s_nop 1
	v_mfma_f32_16x16x32_bf16 v[32:35], v[136:139], v[140:143], v[32:35]
	v_mfma_f32_16x16x32_bf16 v[36:39], v[136:139], v[144:147], v[36:39]
	v_mfma_f32_16x16x32_bf16 v[40:43], v[136:139], v[148:151], v[40:43]
	v_mfma_f32_16x16x32_bf16 v[44:47], v[136:139], v[152:155], v[44:47]
	s_add_u32 s52, s42, 0x10000
	s_addc_u32 s53, s43, 0
	global_load_dwordx4 v[140:143], v170, s[52:53] offset:128
	global_load_dwordx4 v[144:147], v171, s[52:53] offset:128
	global_load_dwordx4 v[148:151], v172, s[52:53] offset:128
	global_load_dwordx4 v[152:155], v173, s[52:53] offset:128
	s_add_u32 s52, s42, 0x10000
	s_addc_u32 s53, s43, 0
	global_load_dwordx4 v[104:107], v170, s[52:53] offset:192
	global_load_dwordx4 v[108:111], v171, s[52:53] offset:192
	global_load_dwordx4 v[112:115], v172, s[52:53] offset:192
	global_load_dwordx4 v[116:119], v173, s[52:53] offset:192
	s_add_u32 s52, s42, 0x14000
	s_addc_u32 s53, s43, 0
	global_load_dwordx4 v[120:123], v170, s[52:53] offset:0
	global_load_dwordx4 v[124:127], v171, s[52:53] offset:0
	global_load_dwordx4 v[128:131], v172, s[52:53] offset:0
	global_load_dwordx4 v[132:135], v173, s[52:53] offset:0
	v_mul_f32_e32 v236, 0x3fb8aa3b, v156
	v_exp_f32_e32 v236, v236
	s_nop 0
	v_lshlrev_b32_e32 v237, 16, v48
	v_and_b32_e32 v238, 0xffff0000, v48
	v_mul_f32_e32 v237, v236, v237
	v_mul_f32_e32 v238, v236, v238
	v_cvt_pk_bf16_f32 v136, v237, v238
	v_lshlrev_b32_e32 v237, 16, v49
	v_and_b32_e32 v238, 0xffff0000, v49
	v_mul_f32_e32 v237, v236, v237
	v_mul_f32_e32 v238, v236, v238
	v_cvt_pk_bf16_f32 v137, v237, v238
	v_lshlrev_b32_e32 v237, 16, v50
	v_and_b32_e32 v238, 0xffff0000, v50
	v_mul_f32_e32 v237, v236, v237
	v_mul_f32_e32 v238, v236, v238
	v_cvt_pk_bf16_f32 v138, v237, v238
	v_lshlrev_b32_e32 v237, 16, v51
	v_and_b32_e32 v238, 0xffff0000, v51
	v_mul_f32_e32 v237, v236, v237
	v_mul_f32_e32 v238, v236, v238
	v_cvt_pk_bf16_f32 v139, v237, v238
	s_waitcnt vmcnt(16)
	s_nop 0
	v_mfma_f32_16x16x32_bf16 v[16:19], v[136:139], v[64:67], v[16:19]
	v_mfma_f32_16x16x32_bf16 v[20:23], v[136:139], v[68:71], v[20:23]
	v_mfma_f32_16x16x32_bf16 v[24:27], v[136:139], v[72:75], v[24:27]
	v_mfma_f32_16x16x32_bf16 v[28:31], v[136:139], v[76:79], v[28:31]
	s_add_u32 s52, s42, 0x14000
	s_addc_u32 s53, s43, 0
	global_load_dwordx4 v[64:67], v170, s[52:53] offset:64
	global_load_dwordx4 v[68:71], v171, s[52:53] offset:64
	global_load_dwordx4 v[72:75], v172, s[52:53] offset:64
	global_load_dwordx4 v[76:79], v173, s[52:53] offset:64
	v_lshlrev_b32_e32 v237, 16, v52
	v_and_b32_e32 v238, 0xffff0000, v52
	v_mul_f32_e32 v237, v236, v237
	v_mul_f32_e32 v238, v236, v238
	v_cvt_pk_bf16_f32 v136, v237, v238
	v_lshlrev_b32_e32 v237, 16, v53
	v_and_b32_e32 v238, 0xffff0000, v53
	v_mul_f32_e32 v237, v236, v237
	v_mul_f32_e32 v238, v236, v238
	v_cvt_pk_bf16_f32 v137, v237, v238
	v_lshlrev_b32_e32 v237, 16, v54
	v_and_b32_e32 v238, 0xffff0000, v54
	v_mul_f32_e32 v237, v236, v237
	v_mul_f32_e32 v238, v236, v238
	v_cvt_pk_bf16_f32 v138, v237, v238
	v_lshlrev_b32_e32 v237, 16, v55
	v_and_b32_e32 v238, 0xffff0000, v55
	v_mul_f32_e32 v237, v236, v237
	v_mul_f32_e32 v238, v236, v238
	v_cvt_pk_bf16_f32 v139, v237, v238
	s_waitcnt vmcnt(16)
	s_nop 0
	v_mfma_f32_16x16x32_bf16 v[16:19], v[136:139], v[80:83], v[16:19]
	v_mfma_f32_16x16x32_bf16 v[20:23], v[136:139], v[84:87], v[20:23]
	v_mfma_f32_16x16x32_bf16 v[24:27], v[136:139], v[88:91], v[24:27]
	v_mfma_f32_16x16x32_bf16 v[28:31], v[136:139], v[92:95], v[28:31]
	s_add_u32 s52, s42, 0x14000
	s_addc_u32 s53, s43, 0
	global_load_dwordx4 v[80:83], v170, s[52:53] offset:128
	global_load_dwordx4 v[84:87], v171, s[52:53] offset:128
	global_load_dwordx4 v[88:91], v172, s[52:53] offset:128
	global_load_dwordx4 v[92:95], v173, s[52:53] offset:128
	v_lshlrev_b32_e32 v237, 16, v56
	v_and_b32_e32 v238, 0xffff0000, v56
	v_mul_f32_e32 v237, v236, v237
	v_mul_f32_e32 v238, v236, v238
	v_cvt_pk_bf16_f32 v136, v237, v238
	v_lshlrev_b32_e32 v237, 16, v57
	v_and_b32_e32 v238, 0xffff0000, v57
	v_mul_f32_e32 v237, v236, v237
	v_mul_f32_e32 v238, v236, v238
	v_cvt_pk_bf16_f32 v137, v237, v238
	v_lshlrev_b32_e32 v237, 16, v58
	v_and_b32_e32 v238, 0xffff0000, v58
	v_mul_f32_e32 v237, v236, v237
	v_mul_f32_e32 v238, v236, v238
	v_cvt_pk_bf16_f32 v138, v237, v238
	v_lshlrev_b32_e32 v237, 16, v59
	v_and_b32_e32 v238, 0xffff0000, v59
	v_mul_f32_e32 v237, v236, v237
	v_mul_f32_e32 v238, v236, v238
	v_cvt_pk_bf16_f32 v139, v237, v238
	s_waitcnt vmcnt(16)
	s_nop 0
	v_mfma_f32_16x16x32_bf16 v[16:19], v[136:139], v[140:143], v[16:19]
	v_mfma_f32_16x16x32_bf16 v[20:23], v[136:139], v[144:147], v[20:23]
	v_mfma_f32_16x16x32_bf16 v[24:27], v[136:139], v[148:151], v[24:27]
	v_mfma_f32_16x16x32_bf16 v[28:31], v[136:139], v[152:155], v[28:31]
	s_add_u32 s52, s42, 0x14000
	s_addc_u32 s53, s43, 0
	global_load_dwordx4 v[140:143], v170, s[52:53] offset:192
	global_load_dwordx4 v[144:147], v171, s[52:53] offset:192
	global_load_dwordx4 v[148:151], v172, s[52:53] offset:192
	global_load_dwordx4 v[152:155], v173, s[52:53] offset:192
	v_lshlrev_b32_e32 v237, 16, v60
	v_and_b32_e32 v238, 0xffff0000, v60
	v_mul_f32_e32 v237, v236, v237
	v_mul_f32_e32 v238, v236, v238
	v_cvt_pk_bf16_f32 v136, v237, v238
	v_lshlrev_b32_e32 v237, 16, v61
	v_and_b32_e32 v238, 0xffff0000, v61
	v_mul_f32_e32 v237, v236, v237
	v_mul_f32_e32 v238, v236, v238
	v_cvt_pk_bf16_f32 v137, v237, v238
	v_lshlrev_b32_e32 v237, 16, v62
	v_and_b32_e32 v238, 0xffff0000, v62
	v_mul_f32_e32 v237, v236, v237
	v_mul_f32_e32 v238, v236, v238
	v_cvt_pk_bf16_f32 v138, v237, v238
	v_lshlrev_b32_e32 v237, 16, v63
	v_and_b32_e32 v238, 0xffff0000, v63
	v_mul_f32_e32 v237, v236, v237
	v_mul_f32_e32 v238, v236, v238
	v_cvt_pk_bf16_f32 v139, v237, v238
	s_waitcnt vmcnt(16)
	s_nop 0
	v_mfma_f32_16x16x32_bf16 v[16:19], v[136:139], v[104:107], v[16:19]
	v_mfma_f32_16x16x32_bf16 v[20:23], v[136:139], v[108:111], v[20:23]
	v_mfma_f32_16x16x32_bf16 v[24:27], v[136:139], v[112:115], v[24:27]
	v_mfma_f32_16x16x32_bf16 v[28:31], v[136:139], v[116:119], v[28:31]
	s_add_u32 s52, s42, 0x18000
	s_addc_u32 s53, s43, 0
	global_load_dwordx4 v[104:107], v170, s[52:53] offset:0
	global_load_dwordx4 v[108:111], v171, s[52:53] offset:0
	global_load_dwordx4 v[112:115], v172, s[52:53] offset:0
	global_load_dwordx4 v[116:119], v173, s[52:53] offset:0
	v_mul_f32_e32 v236, 0x3fb8aa3b, v157
	v_exp_f32_e32 v236, v236
	s_nop 0
	v_lshlrev_b32_e32 v237, 16, v48
	v_and_b32_e32 v238, 0xffff0000, v48
	v_mul_f32_e32 v237, v236, v237
	v_mul_f32_e32 v238, v236, v238
	v_cvt_pk_bf16_f32 v136, v237, v238
	v_lshlrev_b32_e32 v237, 16, v49
	v_and_b32_e32 v238, 0xffff0000, v49
	v_mul_f32_e32 v237, v236, v237
	v_mul_f32_e32 v238, v236, v238
	v_cvt_pk_bf16_f32 v137, v237, v238
	v_lshlrev_b32_e32 v237, 16, v50
	v_and_b32_e32 v238, 0xffff0000, v50
	v_mul_f32_e32 v237, v236, v237
	v_mul_f32_e32 v238, v236, v238
	v_cvt_pk_bf16_f32 v138, v237, v238
	v_lshlrev_b32_e32 v237, 16, v51
	v_and_b32_e32 v238, 0xffff0000, v51
	v_mul_f32_e32 v237, v236, v237
	v_mul_f32_e32 v238, v236, v238
	v_cvt_pk_bf16_f32 v139, v237, v238
	s_waitcnt vmcnt(16)
	s_nop 0
	v_mfma_f32_16x16x32_bf16 v[16:19], v[136:139], v[120:123], v[16:19]
	v_mfma_f32_16x16x32_bf16 v[20:23], v[136:139], v[124:127], v[20:23]
	v_mfma_f32_16x16x32_bf16 v[24:27], v[136:139], v[128:131], v[24:27]
	v_mfma_f32_16x16x32_bf16 v[28:31], v[136:139], v[132:135], v[28:31]
	s_add_u32 s52, s42, 0x18000
	s_addc_u32 s53, s43, 0
	global_load_dwordx4 v[120:123], v170, s[52:53] offset:64
	global_load_dwordx4 v[124:127], v171, s[52:53] offset:64
	global_load_dwordx4 v[128:131], v172, s[52:53] offset:64
	global_load_dwordx4 v[132:135], v173, s[52:53] offset:64
	v_lshlrev_b32_e32 v237, 16, v52
	v_and_b32_e32 v238, 0xffff0000, v52
	v_mul_f32_e32 v237, v236, v237
	v_mul_f32_e32 v238, v236, v238
	v_cvt_pk_bf16_f32 v136, v237, v238
	v_lshlrev_b32_e32 v237, 16, v53
	v_and_b32_e32 v238, 0xffff0000, v53
	v_mul_f32_e32 v237, v236, v237
	v_mul_f32_e32 v238, v236, v238
	v_cvt_pk_bf16_f32 v137, v237, v238
	v_lshlrev_b32_e32 v237, 16, v54
	v_and_b32_e32 v238, 0xffff0000, v54
	v_mul_f32_e32 v237, v236, v237
	v_mul_f32_e32 v238, v236, v238
	v_cvt_pk_bf16_f32 v138, v237, v238
	v_lshlrev_b32_e32 v237, 16, v55
	v_and_b32_e32 v238, 0xffff0000, v55
	v_mul_f32_e32 v237, v236, v237
	v_mul_f32_e32 v238, v236, v238
	v_cvt_pk_bf16_f32 v139, v237, v238
	s_waitcnt vmcnt(16)
	s_nop 0
	v_mfma_f32_16x16x32_bf16 v[16:19], v[136:139], v[64:67], v[16:19]
	v_mfma_f32_16x16x32_bf16 v[20:23], v[136:139], v[68:71], v[20:23]
	v_mfma_f32_16x16x32_bf16 v[24:27], v[136:139], v[72:75], v[24:27]
	v_mfma_f32_16x16x32_bf16 v[28:31], v[136:139], v[76:79], v[28:31]
	s_add_u32 s52, s42, 0x18000
	s_addc_u32 s53, s43, 0
	global_load_dwordx4 v[64:67], v170, s[52:53] offset:128
	global_load_dwordx4 v[68:71], v171, s[52:53] offset:128
	global_load_dwordx4 v[72:75], v172, s[52:53] offset:128
	global_load_dwordx4 v[76:79], v173, s[52:53] offset:128
	v_lshlrev_b32_e32 v237, 16, v56
	v_and_b32_e32 v238, 0xffff0000, v56
	v_mul_f32_e32 v237, v236, v237
	v_mul_f32_e32 v238, v236, v238
	v_cvt_pk_bf16_f32 v136, v237, v238
	v_lshlrev_b32_e32 v237, 16, v57
	v_and_b32_e32 v238, 0xffff0000, v57
	v_mul_f32_e32 v237, v236, v237
	v_mul_f32_e32 v238, v236, v238
	v_cvt_pk_bf16_f32 v137, v237, v238
	v_lshlrev_b32_e32 v237, 16, v58
	v_and_b32_e32 v238, 0xffff0000, v58
	v_mul_f32_e32 v237, v236, v237
	v_mul_f32_e32 v238, v236, v238
	v_cvt_pk_bf16_f32 v138, v237, v238
	v_lshlrev_b32_e32 v237, 16, v59
	v_and_b32_e32 v238, 0xffff0000, v59
	v_mul_f32_e32 v237, v236, v237
	v_mul_f32_e32 v238, v236, v238
	v_cvt_pk_bf16_f32 v139, v237, v238
	s_waitcnt vmcnt(16)
	s_nop 0
	v_mfma_f32_16x16x32_bf16 v[16:19], v[136:139], v[80:83], v[16:19]
	v_mfma_f32_16x16x32_bf16 v[20:23], v[136:139], v[84:87], v[20:23]
	v_mfma_f32_16x16x32_bf16 v[24:27], v[136:139], v[88:91], v[24:27]
	v_mfma_f32_16x16x32_bf16 v[28:31], v[136:139], v[92:95], v[28:31]
	s_add_u32 s52, s42, 0x18000
	s_addc_u32 s53, s43, 0
	global_load_dwordx4 v[80:83], v170, s[52:53] offset:192
	global_load_dwordx4 v[84:87], v171, s[52:53] offset:192
	global_load_dwordx4 v[88:91], v172, s[52:53] offset:192
	global_load_dwordx4 v[92:95], v173, s[52:53] offset:192
	v_lshlrev_b32_e32 v237, 16, v60
	v_and_b32_e32 v238, 0xffff0000, v60
	v_mul_f32_e32 v237, v236, v237
	v_mul_f32_e32 v238, v236, v238
	v_cvt_pk_bf16_f32 v136, v237, v238
	v_lshlrev_b32_e32 v237, 16, v61
	v_and_b32_e32 v238, 0xffff0000, v61
	v_mul_f32_e32 v237, v236, v237
	v_mul_f32_e32 v238, v236, v238
	v_cvt_pk_bf16_f32 v137, v237, v238
	v_lshlrev_b32_e32 v237, 16, v62
	v_and_b32_e32 v238, 0xffff0000, v62
	v_mul_f32_e32 v237, v236, v237
	v_mul_f32_e32 v238, v236, v238
	v_cvt_pk_bf16_f32 v138, v237, v238
	v_lshlrev_b32_e32 v237, 16, v63
	v_and_b32_e32 v238, 0xffff0000, v63
	v_mul_f32_e32 v237, v236, v237
	v_mul_f32_e32 v238, v236, v238
	v_cvt_pk_bf16_f32 v139, v237, v238
	s_waitcnt vmcnt(16)
	s_nop 0
	v_mfma_f32_16x16x32_bf16 v[16:19], v[136:139], v[140:143], v[16:19]
	v_mfma_f32_16x16x32_bf16 v[20:23], v[136:139], v[144:147], v[20:23]
	v_mfma_f32_16x16x32_bf16 v[24:27], v[136:139], v[148:151], v[24:27]
	v_mfma_f32_16x16x32_bf16 v[28:31], v[136:139], v[152:155], v[28:31]
	s_add_u32 s52, s42, 0x1c000
	s_addc_u32 s53, s43, 0
	global_load_dwordx4 v[140:143], v170, s[52:53] offset:0
	global_load_dwordx4 v[144:147], v171, s[52:53] offset:0
	global_load_dwordx4 v[148:151], v172, s[52:53] offset:0
	global_load_dwordx4 v[152:155], v173, s[52:53] offset:0
	v_mul_f32_e32 v236, 0x3fb8aa3b, v158
	v_exp_f32_e32 v236, v236
	s_nop 0
	v_lshlrev_b32_e32 v237, 16, v48
	v_and_b32_e32 v238, 0xffff0000, v48
	v_mul_f32_e32 v237, v236, v237
	v_mul_f32_e32 v238, v236, v238
	v_cvt_pk_bf16_f32 v136, v237, v238
	v_lshlrev_b32_e32 v237, 16, v49
	v_and_b32_e32 v238, 0xffff0000, v49
	v_mul_f32_e32 v237, v236, v237
	v_mul_f32_e32 v238, v236, v238
	v_cvt_pk_bf16_f32 v137, v237, v238
	v_lshlrev_b32_e32 v237, 16, v50
	v_and_b32_e32 v238, 0xffff0000, v50
	v_mul_f32_e32 v237, v236, v237
	v_mul_f32_e32 v238, v236, v238
	v_cvt_pk_bf16_f32 v138, v237, v238
	v_lshlrev_b32_e32 v237, 16, v51
	v_and_b32_e32 v238, 0xffff0000, v51
	v_mul_f32_e32 v237, v236, v237
	v_mul_f32_e32 v238, v236, v238
	v_cvt_pk_bf16_f32 v139, v237, v238
	s_waitcnt vmcnt(16)
	s_nop 0
	v_mfma_f32_16x16x32_bf16 v[32:35], v[136:139], v[104:107], v[32:35]
	v_mfma_f32_16x16x32_bf16 v[36:39], v[136:139], v[108:111], v[36:39]
	v_mfma_f32_16x16x32_bf16 v[40:43], v[136:139], v[112:115], v[40:43]
	v_mfma_f32_16x16x32_bf16 v[44:47], v[136:139], v[116:119], v[44:47]
	s_add_u32 s52, s42, 0x1c000
	s_addc_u32 s53, s43, 0
	global_load_dwordx4 v[104:107], v170, s[52:53] offset:64
	global_load_dwordx4 v[108:111], v171, s[52:53] offset:64
	global_load_dwordx4 v[112:115], v172, s[52:53] offset:64
	global_load_dwordx4 v[116:119], v173, s[52:53] offset:64
	v_lshlrev_b32_e32 v237, 16, v52
	v_and_b32_e32 v238, 0xffff0000, v52
	v_mul_f32_e32 v237, v236, v237
	v_mul_f32_e32 v238, v236, v238
	v_cvt_pk_bf16_f32 v136, v237, v238
	v_lshlrev_b32_e32 v237, 16, v53
	v_and_b32_e32 v238, 0xffff0000, v53
	v_mul_f32_e32 v237, v236, v237
	v_mul_f32_e32 v238, v236, v238
	v_cvt_pk_bf16_f32 v137, v237, v238
	v_lshlrev_b32_e32 v237, 16, v54
	v_and_b32_e32 v238, 0xffff0000, v54
	v_mul_f32_e32 v237, v236, v237
	v_mul_f32_e32 v238, v236, v238
	v_cvt_pk_bf16_f32 v138, v237, v238
	v_lshlrev_b32_e32 v237, 16, v55
	v_and_b32_e32 v238, 0xffff0000, v55
	v_mul_f32_e32 v237, v236, v237
	v_mul_f32_e32 v238, v236, v238
	v_cvt_pk_bf16_f32 v139, v237, v238
	s_waitcnt vmcnt(16)
	s_nop 0
	v_mfma_f32_16x16x32_bf16 v[32:35], v[136:139], v[120:123], v[32:35]
	v_mfma_f32_16x16x32_bf16 v[36:39], v[136:139], v[124:127], v[36:39]
	v_mfma_f32_16x16x32_bf16 v[40:43], v[136:139], v[128:131], v[40:43]
	v_mfma_f32_16x16x32_bf16 v[44:47], v[136:139], v[132:135], v[44:47]
	s_add_u32 s52, s42, 0x1c000
	s_addc_u32 s53, s43, 0
	global_load_dwordx4 v[120:123], v170, s[52:53] offset:128
	global_load_dwordx4 v[124:127], v171, s[52:53] offset:128
	global_load_dwordx4 v[128:131], v172, s[52:53] offset:128
	global_load_dwordx4 v[132:135], v173, s[52:53] offset:128
	v_lshlrev_b32_e32 v237, 16, v56
	v_and_b32_e32 v238, 0xffff0000, v56
	v_mul_f32_e32 v237, v236, v237
	v_mul_f32_e32 v238, v236, v238
	v_cvt_pk_bf16_f32 v136, v237, v238
	v_lshlrev_b32_e32 v237, 16, v57
	v_and_b32_e32 v238, 0xffff0000, v57
	v_mul_f32_e32 v237, v236, v237
	v_mul_f32_e32 v238, v236, v238
	v_cvt_pk_bf16_f32 v137, v237, v238
	v_lshlrev_b32_e32 v237, 16, v58
	v_and_b32_e32 v238, 0xffff0000, v58
	v_mul_f32_e32 v237, v236, v237
	v_mul_f32_e32 v238, v236, v238
	v_cvt_pk_bf16_f32 v138, v237, v238
	v_lshlrev_b32_e32 v237, 16, v59
	v_and_b32_e32 v238, 0xffff0000, v59
	v_mul_f32_e32 v237, v236, v237
	v_mul_f32_e32 v238, v236, v238
	v_cvt_pk_bf16_f32 v139, v237, v238
	s_waitcnt vmcnt(16)
	s_nop 0
	v_mfma_f32_16x16x32_bf16 v[32:35], v[136:139], v[64:67], v[32:35]
	v_mfma_f32_16x16x32_bf16 v[36:39], v[136:139], v[68:71], v[36:39]
	v_mfma_f32_16x16x32_bf16 v[40:43], v[136:139], v[72:75], v[40:43]
	v_mfma_f32_16x16x32_bf16 v[44:47], v[136:139], v[76:79], v[44:47]
	s_add_u32 s52, s42, 0x1c000
	s_addc_u32 s53, s43, 0
	global_load_dwordx4 v[64:67], v170, s[52:53] offset:192
	global_load_dwordx4 v[68:71], v171, s[52:53] offset:192
	global_load_dwordx4 v[72:75], v172, s[52:53] offset:192
	global_load_dwordx4 v[76:79], v173, s[52:53] offset:192
	v_lshlrev_b32_e32 v237, 16, v60
	v_and_b32_e32 v238, 0xffff0000, v60
	v_mul_f32_e32 v237, v236, v237
	v_mul_f32_e32 v238, v236, v238
	v_cvt_pk_bf16_f32 v136, v237, v238
	v_lshlrev_b32_e32 v237, 16, v61
	v_and_b32_e32 v238, 0xffff0000, v61
	v_mul_f32_e32 v237, v236, v237
	v_mul_f32_e32 v238, v236, v238
	v_cvt_pk_bf16_f32 v137, v237, v238
	v_lshlrev_b32_e32 v237, 16, v62
	v_and_b32_e32 v238, 0xffff0000, v62
	v_mul_f32_e32 v237, v236, v237
	v_mul_f32_e32 v238, v236, v238
	v_cvt_pk_bf16_f32 v138, v237, v238
	v_lshlrev_b32_e32 v237, 16, v63
	v_and_b32_e32 v238, 0xffff0000, v63
	v_mul_f32_e32 v237, v236, v237
	v_mul_f32_e32 v238, v236, v238
	v_cvt_pk_bf16_f32 v139, v237, v238
	s_waitcnt vmcnt(16)
	s_nop 0
	v_mfma_f32_16x16x32_bf16 v[32:35], v[136:139], v[80:83], v[32:35]
	v_mfma_f32_16x16x32_bf16 v[36:39], v[136:139], v[84:87], v[36:39]
	v_mfma_f32_16x16x32_bf16 v[40:43], v[136:139], v[88:91], v[40:43]
	v_mfma_f32_16x16x32_bf16 v[44:47], v[136:139], v[92:95], v[44:47]
	v_mul_f32_e32 v236, 0x3fb8aa3b, v159
	v_exp_f32_e32 v236, v236
	s_nop 0
	v_lshlrev_b32_e32 v237, 16, v48
	v_and_b32_e32 v238, 0xffff0000, v48
	v_mul_f32_e32 v237, v236, v237
	v_mul_f32_e32 v238, v236, v238
	v_cvt_pk_bf16_f32 v136, v237, v238
	v_lshlrev_b32_e32 v237, 16, v49
	v_and_b32_e32 v238, 0xffff0000, v49
	v_mul_f32_e32 v237, v236, v237
	v_mul_f32_e32 v238, v236, v238
	v_cvt_pk_bf16_f32 v137, v237, v238
	v_lshlrev_b32_e32 v237, 16, v50
	v_and_b32_e32 v238, 0xffff0000, v50
	v_mul_f32_e32 v237, v236, v237
	v_mul_f32_e32 v238, v236, v238
	v_cvt_pk_bf16_f32 v138, v237, v238
	v_lshlrev_b32_e32 v237, 16, v51
	v_and_b32_e32 v238, 0xffff0000, v51
	v_mul_f32_e32 v237, v236, v237
	v_mul_f32_e32 v238, v236, v238
	v_cvt_pk_bf16_f32 v139, v237, v238
	s_waitcnt vmcnt(12)
	s_nop 0
	v_mfma_f32_16x16x32_bf16 v[32:35], v[136:139], v[140:143], v[32:35]
	v_mfma_f32_16x16x32_bf16 v[36:39], v[136:139], v[144:147], v[36:39]
	v_mfma_f32_16x16x32_bf16 v[40:43], v[136:139], v[148:151], v[40:43]
	v_mfma_f32_16x16x32_bf16 v[44:47], v[136:139], v[152:155], v[44:47]
	v_lshlrev_b32_e32 v237, 16, v52
	v_and_b32_e32 v238, 0xffff0000, v52
	v_mul_f32_e32 v237, v236, v237
	v_mul_f32_e32 v238, v236, v238
	v_cvt_pk_bf16_f32 v136, v237, v238
	v_lshlrev_b32_e32 v237, 16, v53
	v_and_b32_e32 v238, 0xffff0000, v53
	v_mul_f32_e32 v237, v236, v237
	v_mul_f32_e32 v238, v236, v238
	v_cvt_pk_bf16_f32 v137, v237, v238
	v_lshlrev_b32_e32 v237, 16, v54
	v_and_b32_e32 v238, 0xffff0000, v54
	v_mul_f32_e32 v237, v236, v237
	v_mul_f32_e32 v238, v236, v238
	v_cvt_pk_bf16_f32 v138, v237, v238
	v_lshlrev_b32_e32 v237, 16, v55
	v_and_b32_e32 v238, 0xffff0000, v55
	v_mul_f32_e32 v237, v236, v237
	v_mul_f32_e32 v238, v236, v238
	v_cvt_pk_bf16_f32 v139, v237, v238
	s_waitcnt vmcnt(8)
	s_nop 0
	v_mfma_f32_16x16x32_bf16 v[32:35], v[136:139], v[104:107], v[32:35]
	v_mfma_f32_16x16x32_bf16 v[36:39], v[136:139], v[108:111], v[36:39]
	v_mfma_f32_16x16x32_bf16 v[40:43], v[136:139], v[112:115], v[40:43]
	v_mfma_f32_16x16x32_bf16 v[44:47], v[136:139], v[116:119], v[44:47]
	v_lshlrev_b32_e32 v237, 16, v56
	v_and_b32_e32 v238, 0xffff0000, v56
	v_mul_f32_e32 v237, v236, v237
	v_mul_f32_e32 v238, v236, v238
	v_cvt_pk_bf16_f32 v136, v237, v238
	v_lshlrev_b32_e32 v237, 16, v57
	v_and_b32_e32 v238, 0xffff0000, v57
	v_mul_f32_e32 v237, v236, v237
	v_mul_f32_e32 v238, v236, v238
	v_cvt_pk_bf16_f32 v137, v237, v238
	v_lshlrev_b32_e32 v237, 16, v58
	v_and_b32_e32 v238, 0xffff0000, v58
	v_mul_f32_e32 v237, v236, v237
	v_mul_f32_e32 v238, v236, v238
	v_cvt_pk_bf16_f32 v138, v237, v238
	v_lshlrev_b32_e32 v237, 16, v59
	v_and_b32_e32 v238, 0xffff0000, v59
	v_mul_f32_e32 v237, v236, v237
	v_mul_f32_e32 v238, v236, v238
	v_cvt_pk_bf16_f32 v139, v237, v238
	s_waitcnt vmcnt(4)
	s_nop 0
	v_mfma_f32_16x16x32_bf16 v[32:35], v[136:139], v[120:123], v[32:35]
	v_mfma_f32_16x16x32_bf16 v[36:39], v[136:139], v[124:127], v[36:39]
	v_mfma_f32_16x16x32_bf16 v[40:43], v[136:139], v[128:131], v[40:43]
	v_mfma_f32_16x16x32_bf16 v[44:47], v[136:139], v[132:135], v[44:47]
	v_lshlrev_b32_e32 v237, 16, v60
	v_and_b32_e32 v238, 0xffff0000, v60
	v_mul_f32_e32 v237, v236, v237
	v_mul_f32_e32 v238, v236, v238
	v_cvt_pk_bf16_f32 v136, v237, v238
	v_lshlrev_b32_e32 v237, 16, v61
	v_and_b32_e32 v238, 0xffff0000, v61
	v_mul_f32_e32 v237, v236, v237
	v_mul_f32_e32 v238, v236, v238
	v_cvt_pk_bf16_f32 v137, v237, v238
	v_lshlrev_b32_e32 v237, 16, v62
	v_and_b32_e32 v238, 0xffff0000, v62
	v_mul_f32_e32 v237, v236, v237
	v_mul_f32_e32 v238, v236, v238
	v_cvt_pk_bf16_f32 v138, v237, v238
	v_lshlrev_b32_e32 v237, 16, v63
	v_and_b32_e32 v238, 0xffff0000, v63
	v_mul_f32_e32 v237, v236, v237
	v_mul_f32_e32 v238, v236, v238
	v_cvt_pk_bf16_f32 v139, v237, v238
	s_waitcnt vmcnt(0)
	s_nop 0
	v_mfma_f32_16x16x32_bf16 v[32:35], v[136:139], v[64:67], v[32:35]
	v_mfma_f32_16x16x32_bf16 v[36:39], v[136:139], v[68:71], v[36:39]
	v_mfma_f32_16x16x32_bf16 v[40:43], v[136:139], v[72:75], v[40:43]
	v_mfma_f32_16x16x32_bf16 v[44:47], v[136:139], v[76:79], v[44:47]
	global_load_dword v104, v234, s[50:51] offset:0
	global_load_dword v105, v234, s[50:51] offset:64
	global_load_dword v106, v234, s[50:51] offset:128
	global_load_dword v107, v234, s[50:51] offset:192
	global_load_dword v108, v234, s[50:51] offset:256
	global_load_dword v109, v234, s[50:51] offset:320
	global_load_dword v110, v234, s[50:51] offset:384
	global_load_dword v111, v234, s[50:51] offset:448
	global_load_dword v112, v234, s[50:51] offset:512
	global_load_dword v113, v234, s[50:51] offset:576
	global_load_dword v114, v234, s[50:51] offset:640
	global_load_dword v115, v234, s[50:51] offset:704
	global_load_dword v116, v234, s[50:51] offset:768
	global_load_dword v117, v234, s[50:51] offset:832
	global_load_dword v118, v234, s[50:51] offset:896
	global_load_dword v119, v234, s[50:51] offset:960
	s_nop 7
	ds_read_b64_tr_b16 v[140:141], v174 offset:256
	ds_read_b64_tr_b16 v[148:149], v227 offset:256
	ds_read_b64_tr_b16 v[142:143], v174 offset:288
	ds_read_b64_tr_b16 v[150:151], v227 offset:288
	ds_read_b64_tr_b16 v[144:145], v174 offset:320
	ds_read_b64_tr_b16 v[152:153], v227 offset:320
	ds_read_b64_tr_b16 v[146:147], v174 offset:352
	ds_read_b64_tr_b16 v[154:155], v227 offset:352
	s_waitcnt lgkmcnt(6)
	v_lshlrev_b32_e32 v236, 16, v140
	v_lshlrev_b32_e32 v237, 16, v148
	v_fma_f32 v238, s62, v236, v16
	v_mul_f32_e32 v239, 0xbfb8aa3b, v237
	v_exp_f32_e32 v239, v239
	s_nop 0
	v_add_f32_e32 v239, 1.0, v239
	v_div_scale_f32 v240, s[0:1], v239, v239, v237
	v_rcp_f32_e32 v241, v240
	s_nop 0
	v_fma_f32 v242, -v240, v241, 1.0
	v_fmac_f32_e32 v241, v242, v241
	v_div_scale_f32 v242, vcc, v237, v239, v237
	v_mul_f32_e32 v243, v242, v241
	v_fma_f32 v244, -v240, v243, v242
	v_fmac_f32_e32 v243, v244, v241
	v_fma_f32 v240, -v240, v243, v242
	v_div_fmas_f32 v240, v240, v241, v243
	v_div_fixup_f32 v240, v240, v239, v237
	v_mul_f32_e32 v246, v238, v240
	v_fmac_f32_e32 v228, v246, v246
	v_and_b32_e32 v236, 0xffff0000, v140
	v_and_b32_e32 v237, 0xffff0000, v148
	v_fma_f32 v238, s62, v236, v17
	v_mul_f32_e32 v239, 0xbfb8aa3b, v237
	v_exp_f32_e32 v239, v239
	s_nop 0
	v_add_f32_e32 v239, 1.0, v239
	v_div_scale_f32 v240, s[0:1], v239, v239, v237
	v_rcp_f32_e32 v241, v240
	s_nop 0
	v_fma_f32 v242, -v240, v241, 1.0
	v_fmac_f32_e32 v241, v242, v241
	v_div_scale_f32 v242, vcc, v237, v239, v237
	v_mul_f32_e32 v243, v242, v241
	v_fma_f32 v244, -v240, v243, v242
	v_fmac_f32_e32 v243, v244, v241
	v_fma_f32 v240, -v240, v243, v242
	v_div_fmas_f32 v240, v240, v241, v243
	v_div_fixup_f32 v240, v240, v239, v237
	v_mul_f32_e32 v247, v238, v240
	v_fmac_f32_e32 v229, v247, v247
	v_lshlrev_b32_e32 v236, 16, v141
	v_lshlrev_b32_e32 v237, 16, v149
	v_fma_f32 v238, s62, v236, v18
	v_mul_f32_e32 v239, 0xbfb8aa3b, v237
	v_exp_f32_e32 v239, v239
	s_nop 0
	v_add_f32_e32 v239, 1.0, v239
	v_div_scale_f32 v240, s[0:1], v239, v239, v237
	v_rcp_f32_e32 v241, v240
	s_nop 0
	v_fma_f32 v242, -v240, v241, 1.0
	v_fmac_f32_e32 v241, v242, v241
	v_div_scale_f32 v242, vcc, v237, v239, v237
	v_mul_f32_e32 v243, v242, v241
	v_fma_f32 v244, -v240, v243, v242
	v_fmac_f32_e32 v243, v244, v241
	v_fma_f32 v240, -v240, v243, v242
	v_div_fmas_f32 v240, v240, v241, v243
	v_div_fixup_f32 v240, v240, v239, v237
	v_mul_f32_e32 v248, v238, v240
	v_fmac_f32_e32 v230, v248, v248
	v_and_b32_e32 v236, 0xffff0000, v141
	v_and_b32_e32 v237, 0xffff0000, v149
	v_fma_f32 v238, s62, v236, v19
	v_mul_f32_e32 v239, 0xbfb8aa3b, v237
	v_exp_f32_e32 v239, v239
	s_nop 0
	v_add_f32_e32 v239, 1.0, v239
	v_div_scale_f32 v240, s[0:1], v239, v239, v237
	v_rcp_f32_e32 v241, v240
	s_nop 0
	v_fma_f32 v242, -v240, v241, 1.0
	v_fmac_f32_e32 v241, v242, v241
	v_div_scale_f32 v242, vcc, v237, v239, v237
	v_mul_f32_e32 v243, v242, v241
	v_fma_f32 v244, -v240, v243, v242
	v_fmac_f32_e32 v243, v244, v241
	v_fma_f32 v240, -v240, v243, v242
	v_div_fmas_f32 v240, v240, v241, v243
	v_div_fixup_f32 v240, v240, v239, v237
	v_mul_f32_e32 v249, v238, v240
	v_fmac_f32_e32 v231, v249, v249
	v_cvt_pk_bf16_f32 v204, v246, v247
	v_cvt_pk_bf16_f32 v205, v248, v249
	s_waitcnt lgkmcnt(4)
	v_lshlrev_b32_e32 v236, 16, v142
	v_lshlrev_b32_e32 v237, 16, v150
	v_fma_f32 v238, s62, v236, v20
	v_mul_f32_e32 v239, 0xbfb8aa3b, v237
	v_exp_f32_e32 v239, v239
	s_nop 0
	v_add_f32_e32 v239, 1.0, v239
	v_div_scale_f32 v240, s[0:1], v239, v239, v237
	v_rcp_f32_e32 v241, v240
	s_nop 0
	v_fma_f32 v242, -v240, v241, 1.0
	v_fmac_f32_e32 v241, v242, v241
	v_div_scale_f32 v242, vcc, v237, v239, v237
	v_mul_f32_e32 v243, v242, v241
	v_fma_f32 v244, -v240, v243, v242
	v_fmac_f32_e32 v243, v244, v241
	v_fma_f32 v240, -v240, v243, v242
	v_div_fmas_f32 v240, v240, v241, v243
	v_div_fixup_f32 v240, v240, v239, v237
	v_mul_f32_e32 v246, v238, v240
	v_fmac_f32_e32 v228, v246, v246
	v_and_b32_e32 v236, 0xffff0000, v142
	v_and_b32_e32 v237, 0xffff0000, v150
	v_fma_f32 v238, s62, v236, v21
	v_mul_f32_e32 v239, 0xbfb8aa3b, v237
	v_exp_f32_e32 v239, v239
	s_nop 0
	v_add_f32_e32 v239, 1.0, v239
	v_div_scale_f32 v240, s[0:1], v239, v239, v237
	v_rcp_f32_e32 v241, v240
	s_nop 0
	v_fma_f32 v242, -v240, v241, 1.0
	v_fmac_f32_e32 v241, v242, v241
	v_div_scale_f32 v242, vcc, v237, v239, v237
	v_mul_f32_e32 v243, v242, v241
	v_fma_f32 v244, -v240, v243, v242
	v_fmac_f32_e32 v243, v244, v241
	v_fma_f32 v240, -v240, v243, v242
	v_div_fmas_f32 v240, v240, v241, v243
	v_div_fixup_f32 v240, v240, v239, v237
	v_mul_f32_e32 v247, v238, v240
	v_fmac_f32_e32 v229, v247, v247
	v_lshlrev_b32_e32 v236, 16, v143
	v_lshlrev_b32_e32 v237, 16, v151
	v_fma_f32 v238, s62, v236, v22
	v_mul_f32_e32 v239, 0xbfb8aa3b, v237
	v_exp_f32_e32 v239, v239
	s_nop 0
	v_add_f32_e32 v239, 1.0, v239
	v_div_scale_f32 v240, s[0:1], v239, v239, v237
	v_rcp_f32_e32 v241, v240
	s_nop 0
	v_fma_f32 v242, -v240, v241, 1.0
	v_fmac_f32_e32 v241, v242, v241
	v_div_scale_f32 v242, vcc, v237, v239, v237
	v_mul_f32_e32 v243, v242, v241
	v_fma_f32 v244, -v240, v243, v242
	v_fmac_f32_e32 v243, v244, v241
	v_fma_f32 v240, -v240, v243, v242
	v_div_fmas_f32 v240, v240, v241, v243
	v_div_fixup_f32 v240, v240, v239, v237
	v_mul_f32_e32 v248, v238, v240
	v_fmac_f32_e32 v230, v248, v248
	v_and_b32_e32 v236, 0xffff0000, v143
	v_and_b32_e32 v237, 0xffff0000, v151
	v_fma_f32 v238, s62, v236, v23
	v_mul_f32_e32 v239, 0xbfb8aa3b, v237
	v_exp_f32_e32 v239, v239
	s_nop 0
	v_add_f32_e32 v239, 1.0, v239
	v_div_scale_f32 v240, s[0:1], v239, v239, v237
	v_rcp_f32_e32 v241, v240
	s_nop 0
	v_fma_f32 v242, -v240, v241, 1.0
	v_fmac_f32_e32 v241, v242, v241
	v_div_scale_f32 v242, vcc, v237, v239, v237
	v_mul_f32_e32 v243, v242, v241
	v_fma_f32 v244, -v240, v243, v242
	v_fmac_f32_e32 v243, v244, v241
	v_fma_f32 v240, -v240, v243, v242
	v_div_fmas_f32 v240, v240, v241, v243
	v_div_fixup_f32 v240, v240, v239, v237
	v_mul_f32_e32 v249, v238, v240
	v_fmac_f32_e32 v231, v249, v249
	v_cvt_pk_bf16_f32 v206, v246, v247
	v_cvt_pk_bf16_f32 v207, v248, v249
	s_waitcnt lgkmcnt(2)
	v_lshlrev_b32_e32 v236, 16, v144
	v_lshlrev_b32_e32 v237, 16, v152
	v_fma_f32 v238, s62, v236, v24
	v_mul_f32_e32 v239, 0xbfb8aa3b, v237
	v_exp_f32_e32 v239, v239
	s_nop 0
	v_add_f32_e32 v239, 1.0, v239
	v_div_scale_f32 v240, s[0:1], v239, v239, v237
	v_rcp_f32_e32 v241, v240
	s_nop 0
	v_fma_f32 v242, -v240, v241, 1.0
	v_fmac_f32_e32 v241, v242, v241
	v_div_scale_f32 v242, vcc, v237, v239, v237
	v_mul_f32_e32 v243, v242, v241
	v_fma_f32 v244, -v240, v243, v242
	v_fmac_f32_e32 v243, v244, v241
	v_fma_f32 v240, -v240, v243, v242
	v_div_fmas_f32 v240, v240, v241, v243
	v_div_fixup_f32 v240, v240, v239, v237
	v_mul_f32_e32 v246, v238, v240
	v_fmac_f32_e32 v228, v246, v246
	v_and_b32_e32 v236, 0xffff0000, v144
	v_and_b32_e32 v237, 0xffff0000, v152
	v_fma_f32 v238, s62, v236, v25
	v_mul_f32_e32 v239, 0xbfb8aa3b, v237
	v_exp_f32_e32 v239, v239
	s_nop 0
	v_add_f32_e32 v239, 1.0, v239
	v_div_scale_f32 v240, s[0:1], v239, v239, v237
	v_rcp_f32_e32 v241, v240
	s_nop 0
	v_fma_f32 v242, -v240, v241, 1.0
	v_fmac_f32_e32 v241, v242, v241
	v_div_scale_f32 v242, vcc, v237, v239, v237
	v_mul_f32_e32 v243, v242, v241
	v_fma_f32 v244, -v240, v243, v242
	v_fmac_f32_e32 v243, v244, v241
	v_fma_f32 v240, -v240, v243, v242
	v_div_fmas_f32 v240, v240, v241, v243
	v_div_fixup_f32 v240, v240, v239, v237
	v_mul_f32_e32 v247, v238, v240
	v_fmac_f32_e32 v229, v247, v247
	v_lshlrev_b32_e32 v236, 16, v145
	v_lshlrev_b32_e32 v237, 16, v153
	v_fma_f32 v238, s62, v236, v26
	v_mul_f32_e32 v239, 0xbfb8aa3b, v237
	v_exp_f32_e32 v239, v239
	s_nop 0
	v_add_f32_e32 v239, 1.0, v239
	v_div_scale_f32 v240, s[0:1], v239, v239, v237
	v_rcp_f32_e32 v241, v240
	s_nop 0
	v_fma_f32 v242, -v240, v241, 1.0
	v_fmac_f32_e32 v241, v242, v241
	v_div_scale_f32 v242, vcc, v237, v239, v237
	v_mul_f32_e32 v243, v242, v241
	v_fma_f32 v244, -v240, v243, v242
	v_fmac_f32_e32 v243, v244, v241
	v_fma_f32 v240, -v240, v243, v242
	v_div_fmas_f32 v240, v240, v241, v243
	v_div_fixup_f32 v240, v240, v239, v237
	v_mul_f32_e32 v248, v238, v240
	v_fmac_f32_e32 v230, v248, v248
	v_and_b32_e32 v236, 0xffff0000, v145
	v_and_b32_e32 v237, 0xffff0000, v153
	v_fma_f32 v238, s62, v236, v27
	v_mul_f32_e32 v239, 0xbfb8aa3b, v237
	v_exp_f32_e32 v239, v239
	s_nop 0
	v_add_f32_e32 v239, 1.0, v239
	v_div_scale_f32 v240, s[0:1], v239, v239, v237
	v_rcp_f32_e32 v241, v240
	s_nop 0
	v_fma_f32 v242, -v240, v241, 1.0
	v_fmac_f32_e32 v241, v242, v241
	v_div_scale_f32 v242, vcc, v237, v239, v237
	v_mul_f32_e32 v243, v242, v241
	v_fma_f32 v244, -v240, v243, v242
	v_fmac_f32_e32 v243, v244, v241
	v_fma_f32 v240, -v240, v243, v242
	v_div_fmas_f32 v240, v240, v241, v243
	v_div_fixup_f32 v240, v240, v239, v237
	v_mul_f32_e32 v249, v238, v240
	v_fmac_f32_e32 v231, v249, v249
	v_cvt_pk_bf16_f32 v208, v246, v247
	v_cvt_pk_bf16_f32 v209, v248, v249
	s_waitcnt lgkmcnt(0)
	v_lshlrev_b32_e32 v236, 16, v146
	v_lshlrev_b32_e32 v237, 16, v154
	v_fma_f32 v238, s62, v236, v28
	v_mul_f32_e32 v239, 0xbfb8aa3b, v237
	v_exp_f32_e32 v239, v239
	s_nop 0
	v_add_f32_e32 v239, 1.0, v239
	v_div_scale_f32 v240, s[0:1], v239, v239, v237
	v_rcp_f32_e32 v241, v240
	s_nop 0
	v_fma_f32 v242, -v240, v241, 1.0
	v_fmac_f32_e32 v241, v242, v241
	v_div_scale_f32 v242, vcc, v237, v239, v237
	v_mul_f32_e32 v243, v242, v241
	v_fma_f32 v244, -v240, v243, v242
	v_fmac_f32_e32 v243, v244, v241
	v_fma_f32 v240, -v240, v243, v242
	v_div_fmas_f32 v240, v240, v241, v243
	v_div_fixup_f32 v240, v240, v239, v237
	v_mul_f32_e32 v246, v238, v240
	v_fmac_f32_e32 v228, v246, v246
	v_and_b32_e32 v236, 0xffff0000, v146
	v_and_b32_e32 v237, 0xffff0000, v154
	v_fma_f32 v238, s62, v236, v29
	v_mul_f32_e32 v239, 0xbfb8aa3b, v237
	v_exp_f32_e32 v239, v239
	s_nop 0
	v_add_f32_e32 v239, 1.0, v239
	v_div_scale_f32 v240, s[0:1], v239, v239, v237
	v_rcp_f32_e32 v241, v240
	s_nop 0
	v_fma_f32 v242, -v240, v241, 1.0
	v_fmac_f32_e32 v241, v242, v241
	v_div_scale_f32 v242, vcc, v237, v239, v237
	v_mul_f32_e32 v243, v242, v241
	v_fma_f32 v244, -v240, v243, v242
	v_fmac_f32_e32 v243, v244, v241
	v_fma_f32 v240, -v240, v243, v242
	v_div_fmas_f32 v240, v240, v241, v243
	v_div_fixup_f32 v240, v240, v239, v237
	v_mul_f32_e32 v247, v238, v240
	v_fmac_f32_e32 v229, v247, v247
	v_lshlrev_b32_e32 v236, 16, v147
	v_lshlrev_b32_e32 v237, 16, v155
	v_fma_f32 v238, s62, v236, v30
	v_mul_f32_e32 v239, 0xbfb8aa3b, v237
	v_exp_f32_e32 v239, v239
	s_nop 0
	v_add_f32_e32 v239, 1.0, v239
	v_div_scale_f32 v240, s[0:1], v239, v239, v237
	v_rcp_f32_e32 v241, v240
	s_nop 0
	v_fma_f32 v242, -v240, v241, 1.0
	v_fmac_f32_e32 v241, v242, v241
	v_div_scale_f32 v242, vcc, v237, v239, v237
	v_mul_f32_e32 v243, v242, v241
	v_fma_f32 v244, -v240, v243, v242
	v_fmac_f32_e32 v243, v244, v241
	v_fma_f32 v240, -v240, v243, v242
	v_div_fmas_f32 v240, v240, v241, v243
	v_div_fixup_f32 v240, v240, v239, v237
	v_mul_f32_e32 v248, v238, v240
	v_fmac_f32_e32 v230, v248, v248
	v_and_b32_e32 v236, 0xffff0000, v147
	v_and_b32_e32 v237, 0xffff0000, v155
	v_fma_f32 v238, s62, v236, v31
	v_mul_f32_e32 v239, 0xbfb8aa3b, v237
	v_exp_f32_e32 v239, v239
	s_nop 0
	v_add_f32_e32 v239, 1.0, v239
	v_div_scale_f32 v240, s[0:1], v239, v239, v237
	v_rcp_f32_e32 v241, v240
	s_nop 0
	v_fma_f32 v242, -v240, v241, 1.0
	v_fmac_f32_e32 v241, v242, v241
	v_div_scale_f32 v242, vcc, v237, v239, v237
	v_mul_f32_e32 v243, v242, v241
	v_fma_f32 v244, -v240, v243, v242
	v_fmac_f32_e32 v243, v244, v241
	v_fma_f32 v240, -v240, v243, v242
	v_div_fmas_f32 v240, v240, v241, v243
	v_div_fixup_f32 v240, v240, v239, v237
	v_mul_f32_e32 v249, v238, v240
	v_fmac_f32_e32 v231, v249, v249
	v_cvt_pk_bf16_f32 v210, v246, v247
	v_cvt_pk_bf16_f32 v211, v248, v249
	ds_read_b64_tr_b16 v[140:141], v174 offset:384
	ds_read_b64_tr_b16 v[148:149], v227 offset:384
	ds_read_b64_tr_b16 v[142:143], v174 offset:416
	ds_read_b64_tr_b16 v[150:151], v227 offset:416
	ds_read_b64_tr_b16 v[144:145], v174 offset:448
	ds_read_b64_tr_b16 v[152:153], v227 offset:448
	ds_read_b64_tr_b16 v[146:147], v174 offset:480
	ds_read_b64_tr_b16 v[154:155], v227 offset:480
	s_waitcnt lgkmcnt(6)
	v_lshlrev_b32_e32 v236, 16, v140
	v_lshlrev_b32_e32 v237, 16, v148
	v_fma_f32 v238, s63, v236, v32
	v_mul_f32_e32 v239, 0xbfb8aa3b, v237
	v_exp_f32_e32 v239, v239
	s_nop 0
	v_add_f32_e32 v239, 1.0, v239
	v_div_scale_f32 v240, s[0:1], v239, v239, v237
	v_rcp_f32_e32 v241, v240
	s_nop 0
	v_fma_f32 v242, -v240, v241, 1.0
	v_fmac_f32_e32 v241, v242, v241
	v_div_scale_f32 v242, vcc, v237, v239, v237
	v_mul_f32_e32 v243, v242, v241
	v_fma_f32 v244, -v240, v243, v242
	v_fmac_f32_e32 v243, v244, v241
	v_fma_f32 v240, -v240, v243, v242
	v_div_fmas_f32 v240, v240, v241, v243
	v_div_fixup_f32 v240, v240, v239, v237
	v_mul_f32_e32 v246, v238, v240
	v_fmac_f32_e32 v228, v246, v246
	v_and_b32_e32 v236, 0xffff0000, v140
	v_and_b32_e32 v237, 0xffff0000, v148
	v_fma_f32 v238, s63, v236, v33
	v_mul_f32_e32 v239, 0xbfb8aa3b, v237
	v_exp_f32_e32 v239, v239
	s_nop 0
	v_add_f32_e32 v239, 1.0, v239
	v_div_scale_f32 v240, s[0:1], v239, v239, v237
	v_rcp_f32_e32 v241, v240
	s_nop 0
	v_fma_f32 v242, -v240, v241, 1.0
	v_fmac_f32_e32 v241, v242, v241
	v_div_scale_f32 v242, vcc, v237, v239, v237
	v_mul_f32_e32 v243, v242, v241
	v_fma_f32 v244, -v240, v243, v242
	v_fmac_f32_e32 v243, v244, v241
	v_fma_f32 v240, -v240, v243, v242
	v_div_fmas_f32 v240, v240, v241, v243
	v_div_fixup_f32 v240, v240, v239, v237
	v_mul_f32_e32 v247, v238, v240
	v_fmac_f32_e32 v229, v247, v247
	v_lshlrev_b32_e32 v236, 16, v141
	v_lshlrev_b32_e32 v237, 16, v149
	v_fma_f32 v238, s63, v236, v34
	v_mul_f32_e32 v239, 0xbfb8aa3b, v237
	v_exp_f32_e32 v239, v239
	s_nop 0
	v_add_f32_e32 v239, 1.0, v239
	v_div_scale_f32 v240, s[0:1], v239, v239, v237
	v_rcp_f32_e32 v241, v240
	s_nop 0
	v_fma_f32 v242, -v240, v241, 1.0
	v_fmac_f32_e32 v241, v242, v241
	v_div_scale_f32 v242, vcc, v237, v239, v237
	v_mul_f32_e32 v243, v242, v241
	v_fma_f32 v244, -v240, v243, v242
	v_fmac_f32_e32 v243, v244, v241
	v_fma_f32 v240, -v240, v243, v242
	v_div_fmas_f32 v240, v240, v241, v243
	v_div_fixup_f32 v240, v240, v239, v237
	v_mul_f32_e32 v248, v238, v240
	v_fmac_f32_e32 v230, v248, v248
	v_and_b32_e32 v236, 0xffff0000, v141
	v_and_b32_e32 v237, 0xffff0000, v149
	v_fma_f32 v238, s63, v236, v35
	v_mul_f32_e32 v239, 0xbfb8aa3b, v237
	v_exp_f32_e32 v239, v239
	s_nop 0
	v_add_f32_e32 v239, 1.0, v239
	v_div_scale_f32 v240, s[0:1], v239, v239, v237
	v_rcp_f32_e32 v241, v240
	s_nop 0
	v_fma_f32 v242, -v240, v241, 1.0
	v_fmac_f32_e32 v241, v242, v241
	v_div_scale_f32 v242, vcc, v237, v239, v237
	v_mul_f32_e32 v243, v242, v241
	v_fma_f32 v244, -v240, v243, v242
	v_fmac_f32_e32 v243, v244, v241
	v_fma_f32 v240, -v240, v243, v242
	v_div_fmas_f32 v240, v240, v241, v243
	v_div_fixup_f32 v240, v240, v239, v237
	v_mul_f32_e32 v249, v238, v240
	v_fmac_f32_e32 v231, v249, v249
	v_cvt_pk_bf16_f32 v212, v246, v247
	v_cvt_pk_bf16_f32 v213, v248, v249
	s_waitcnt lgkmcnt(4)
	v_lshlrev_b32_e32 v236, 16, v142
	v_lshlrev_b32_e32 v237, 16, v150
	v_fma_f32 v238, s63, v236, v36
	v_mul_f32_e32 v239, 0xbfb8aa3b, v237
	v_exp_f32_e32 v239, v239
	s_nop 0
	v_add_f32_e32 v239, 1.0, v239
	v_div_scale_f32 v240, s[0:1], v239, v239, v237
	v_rcp_f32_e32 v241, v240
	s_nop 0
	v_fma_f32 v242, -v240, v241, 1.0
	v_fmac_f32_e32 v241, v242, v241
	v_div_scale_f32 v242, vcc, v237, v239, v237
	v_mul_f32_e32 v243, v242, v241
	v_fma_f32 v244, -v240, v243, v242
	v_fmac_f32_e32 v243, v244, v241
	v_fma_f32 v240, -v240, v243, v242
	v_div_fmas_f32 v240, v240, v241, v243
	v_div_fixup_f32 v240, v240, v239, v237
	v_mul_f32_e32 v246, v238, v240
	v_fmac_f32_e32 v228, v246, v246
	v_and_b32_e32 v236, 0xffff0000, v142
	v_and_b32_e32 v237, 0xffff0000, v150
	v_fma_f32 v238, s63, v236, v37
	v_mul_f32_e32 v239, 0xbfb8aa3b, v237
	v_exp_f32_e32 v239, v239
	s_nop 0
	v_add_f32_e32 v239, 1.0, v239
	v_div_scale_f32 v240, s[0:1], v239, v239, v237
	v_rcp_f32_e32 v241, v240
	s_nop 0
	v_fma_f32 v242, -v240, v241, 1.0
	v_fmac_f32_e32 v241, v242, v241
	v_div_scale_f32 v242, vcc, v237, v239, v237
	v_mul_f32_e32 v243, v242, v241
	v_fma_f32 v244, -v240, v243, v242
	v_fmac_f32_e32 v243, v244, v241
	v_fma_f32 v240, -v240, v243, v242
	v_div_fmas_f32 v240, v240, v241, v243
	v_div_fixup_f32 v240, v240, v239, v237
	v_mul_f32_e32 v247, v238, v240
	v_fmac_f32_e32 v229, v247, v247
	v_lshlrev_b32_e32 v236, 16, v143
	v_lshlrev_b32_e32 v237, 16, v151
	v_fma_f32 v238, s63, v236, v38
	v_mul_f32_e32 v239, 0xbfb8aa3b, v237
	v_exp_f32_e32 v239, v239
	s_nop 0
	v_add_f32_e32 v239, 1.0, v239
	v_div_scale_f32 v240, s[0:1], v239, v239, v237
	v_rcp_f32_e32 v241, v240
	s_nop 0
	v_fma_f32 v242, -v240, v241, 1.0
	v_fmac_f32_e32 v241, v242, v241
	v_div_scale_f32 v242, vcc, v237, v239, v237
	v_mul_f32_e32 v243, v242, v241
	v_fma_f32 v244, -v240, v243, v242
	v_fmac_f32_e32 v243, v244, v241
	v_fma_f32 v240, -v240, v243, v242
	v_div_fmas_f32 v240, v240, v241, v243
	v_div_fixup_f32 v240, v240, v239, v237
	v_mul_f32_e32 v248, v238, v240
	v_fmac_f32_e32 v230, v248, v248
	v_and_b32_e32 v236, 0xffff0000, v143
	v_and_b32_e32 v237, 0xffff0000, v151
	v_fma_f32 v238, s63, v236, v39
	v_mul_f32_e32 v239, 0xbfb8aa3b, v237
	v_exp_f32_e32 v239, v239
	s_nop 0
	v_add_f32_e32 v239, 1.0, v239
	v_div_scale_f32 v240, s[0:1], v239, v239, v237
	v_rcp_f32_e32 v241, v240
	s_nop 0
	v_fma_f32 v242, -v240, v241, 1.0
	v_fmac_f32_e32 v241, v242, v241
	v_div_scale_f32 v242, vcc, v237, v239, v237
	v_mul_f32_e32 v243, v242, v241
	v_fma_f32 v244, -v240, v243, v242
	v_fmac_f32_e32 v243, v244, v241
	v_fma_f32 v240, -v240, v243, v242
	v_div_fmas_f32 v240, v240, v241, v243
	v_div_fixup_f32 v240, v240, v239, v237
	v_mul_f32_e32 v249, v238, v240
	v_fmac_f32_e32 v231, v249, v249
	v_cvt_pk_bf16_f32 v214, v246, v247
	v_cvt_pk_bf16_f32 v215, v248, v249
	s_waitcnt lgkmcnt(2)
	v_lshlrev_b32_e32 v236, 16, v144
	v_lshlrev_b32_e32 v237, 16, v152
	v_fma_f32 v238, s63, v236, v40
	v_mul_f32_e32 v239, 0xbfb8aa3b, v237
	v_exp_f32_e32 v239, v239
	s_nop 0
	v_add_f32_e32 v239, 1.0, v239
	v_div_scale_f32 v240, s[0:1], v239, v239, v237
	v_rcp_f32_e32 v241, v240
	s_nop 0
	v_fma_f32 v242, -v240, v241, 1.0
	v_fmac_f32_e32 v241, v242, v241
	v_div_scale_f32 v242, vcc, v237, v239, v237
	v_mul_f32_e32 v243, v242, v241
	v_fma_f32 v244, -v240, v243, v242
	v_fmac_f32_e32 v243, v244, v241
	v_fma_f32 v240, -v240, v243, v242
	v_div_fmas_f32 v240, v240, v241, v243
	v_div_fixup_f32 v240, v240, v239, v237
	v_mul_f32_e32 v246, v238, v240
	v_fmac_f32_e32 v228, v246, v246
	v_and_b32_e32 v236, 0xffff0000, v144
	v_and_b32_e32 v237, 0xffff0000, v152
	v_fma_f32 v238, s63, v236, v41
	v_mul_f32_e32 v239, 0xbfb8aa3b, v237
	v_exp_f32_e32 v239, v239
	s_nop 0
	v_add_f32_e32 v239, 1.0, v239
	v_div_scale_f32 v240, s[0:1], v239, v239, v237
	v_rcp_f32_e32 v241, v240
	s_nop 0
	v_fma_f32 v242, -v240, v241, 1.0
	v_fmac_f32_e32 v241, v242, v241
	v_div_scale_f32 v242, vcc, v237, v239, v237
	v_mul_f32_e32 v243, v242, v241
	v_fma_f32 v244, -v240, v243, v242
	v_fmac_f32_e32 v243, v244, v241
	v_fma_f32 v240, -v240, v243, v242
	v_div_fmas_f32 v240, v240, v241, v243
	v_div_fixup_f32 v240, v240, v239, v237
	v_mul_f32_e32 v247, v238, v240
	v_fmac_f32_e32 v229, v247, v247
	v_lshlrev_b32_e32 v236, 16, v145
	v_lshlrev_b32_e32 v237, 16, v153
	v_fma_f32 v238, s63, v236, v42
	v_mul_f32_e32 v239, 0xbfb8aa3b, v237
	v_exp_f32_e32 v239, v239
	s_nop 0
	v_add_f32_e32 v239, 1.0, v239
	v_div_scale_f32 v240, s[0:1], v239, v239, v237
	v_rcp_f32_e32 v241, v240
	s_nop 0
	v_fma_f32 v242, -v240, v241, 1.0
	v_fmac_f32_e32 v241, v242, v241
	v_div_scale_f32 v242, vcc, v237, v239, v237
	v_mul_f32_e32 v243, v242, v241
	v_fma_f32 v244, -v240, v243, v242
	v_fmac_f32_e32 v243, v244, v241
	v_fma_f32 v240, -v240, v243, v242
	v_div_fmas_f32 v240, v240, v241, v243
	v_div_fixup_f32 v240, v240, v239, v237
	v_mul_f32_e32 v248, v238, v240
	v_fmac_f32_e32 v230, v248, v248
	v_and_b32_e32 v236, 0xffff0000, v145
	v_and_b32_e32 v237, 0xffff0000, v153
	v_fma_f32 v238, s63, v236, v43
	v_mul_f32_e32 v239, 0xbfb8aa3b, v237
	v_exp_f32_e32 v239, v239
	s_nop 0
	v_add_f32_e32 v239, 1.0, v239
	v_div_scale_f32 v240, s[0:1], v239, v239, v237
	v_rcp_f32_e32 v241, v240
	s_nop 0
	v_fma_f32 v242, -v240, v241, 1.0
	v_fmac_f32_e32 v241, v242, v241
	v_div_scale_f32 v242, vcc, v237, v239, v237
	v_mul_f32_e32 v243, v242, v241
	v_fma_f32 v244, -v240, v243, v242
	v_fmac_f32_e32 v243, v244, v241
	v_fma_f32 v240, -v240, v243, v242
	v_div_fmas_f32 v240, v240, v241, v243
	v_div_fixup_f32 v240, v240, v239, v237
	v_mul_f32_e32 v249, v238, v240
	v_fmac_f32_e32 v231, v249, v249
	v_cvt_pk_bf16_f32 v216, v246, v247
	v_cvt_pk_bf16_f32 v217, v248, v249
	s_waitcnt lgkmcnt(0)
	v_lshlrev_b32_e32 v236, 16, v146
	v_lshlrev_b32_e32 v237, 16, v154
	v_fma_f32 v238, s63, v236, v44
	v_mul_f32_e32 v239, 0xbfb8aa3b, v237
	v_exp_f32_e32 v239, v239
	s_nop 0
	v_add_f32_e32 v239, 1.0, v239
	v_div_scale_f32 v240, s[0:1], v239, v239, v237
	v_rcp_f32_e32 v241, v240
	s_nop 0
	v_fma_f32 v242, -v240, v241, 1.0
	v_fmac_f32_e32 v241, v242, v241
	v_div_scale_f32 v242, vcc, v237, v239, v237
	v_mul_f32_e32 v243, v242, v241
	v_fma_f32 v244, -v240, v243, v242
	v_fmac_f32_e32 v243, v244, v241
	v_fma_f32 v240, -v240, v243, v242
	v_div_fmas_f32 v240, v240, v241, v243
	v_div_fixup_f32 v240, v240, v239, v237
	v_mul_f32_e32 v246, v238, v240
	v_fmac_f32_e32 v228, v246, v246
	v_and_b32_e32 v236, 0xffff0000, v146
	v_and_b32_e32 v237, 0xffff0000, v154
	v_fma_f32 v238, s63, v236, v45
	v_mul_f32_e32 v239, 0xbfb8aa3b, v237
	v_exp_f32_e32 v239, v239
	s_nop 0
	v_add_f32_e32 v239, 1.0, v239
	v_div_scale_f32 v240, s[0:1], v239, v239, v237
	v_rcp_f32_e32 v241, v240
	s_nop 0
	v_fma_f32 v242, -v240, v241, 1.0
	v_fmac_f32_e32 v241, v242, v241
	v_div_scale_f32 v242, vcc, v237, v239, v237
	v_mul_f32_e32 v243, v242, v241
	v_fma_f32 v244, -v240, v243, v242
	v_fmac_f32_e32 v243, v244, v241
	v_fma_f32 v240, -v240, v243, v242
	v_div_fmas_f32 v240, v240, v241, v243
	v_div_fixup_f32 v240, v240, v239, v237
	v_mul_f32_e32 v247, v238, v240
	v_fmac_f32_e32 v229, v247, v247
	v_lshlrev_b32_e32 v236, 16, v147
	v_lshlrev_b32_e32 v237, 16, v155
	v_fma_f32 v238, s63, v236, v46
	v_mul_f32_e32 v239, 0xbfb8aa3b, v237
	v_exp_f32_e32 v239, v239
	s_nop 0
	v_add_f32_e32 v239, 1.0, v239
	v_div_scale_f32 v240, s[0:1], v239, v239, v237
	v_rcp_f32_e32 v241, v240
	s_nop 0
	v_fma_f32 v242, -v240, v241, 1.0
	v_fmac_f32_e32 v241, v242, v241
	v_div_scale_f32 v242, vcc, v237, v239, v237
	v_mul_f32_e32 v243, v242, v241
	v_fma_f32 v244, -v240, v243, v242
	v_fmac_f32_e32 v243, v244, v241
	v_fma_f32 v240, -v240, v243, v242
	v_div_fmas_f32 v240, v240, v241, v243
	v_div_fixup_f32 v240, v240, v239, v237
	v_mul_f32_e32 v248, v238, v240
	v_fmac_f32_e32 v230, v248, v248
	v_and_b32_e32 v236, 0xffff0000, v147
	v_and_b32_e32 v237, 0xffff0000, v155
	v_fma_f32 v238, s63, v236, v47
	v_mul_f32_e32 v239, 0xbfb8aa3b, v237
	v_exp_f32_e32 v239, v239
	s_nop 0
	v_add_f32_e32 v239, 1.0, v239
	v_div_scale_f32 v240, s[0:1], v239, v239, v237
	v_rcp_f32_e32 v241, v240
	s_nop 0
	v_fma_f32 v242, -v240, v241, 1.0
	v_fmac_f32_e32 v241, v242, v241
	v_div_scale_f32 v242, vcc, v237, v239, v237
	v_mul_f32_e32 v243, v242, v241
	v_fma_f32 v244, -v240, v243, v242
	v_fmac_f32_e32 v243, v244, v241
	v_fma_f32 v240, -v240, v243, v242
	v_div_fmas_f32 v240, v240, v241, v243
	v_div_fixup_f32 v240, v240, v239, v237
	v_mul_f32_e32 v249, v238, v240
	v_fmac_f32_e32 v231, v249, v249
	v_cvt_pk_bf16_f32 v224, v246, v247
	v_cvt_pk_bf16_f32 v225, v248, v249
	s_nop 1
	v_add_f32_dpp v228, v228, v228 quad_perm:[1,0,3,2] row_mask:0xf bank_mask:0xf
	v_add_f32_dpp v229, v229, v229 quad_perm:[1,0,3,2] row_mask:0xf bank_mask:0xf
	v_add_f32_dpp v230, v230, v230 quad_perm:[1,0,3,2] row_mask:0xf bank_mask:0xf
	v_add_f32_dpp v231, v231, v231 quad_perm:[1,0,3,2] row_mask:0xf bank_mask:0xf
	s_nop 1
	v_add_f32_dpp v228, v228, v228 quad_perm:[2,3,0,1] row_mask:0xf bank_mask:0xf
	v_add_f32_dpp v229, v229, v229 quad_perm:[2,3,0,1] row_mask:0xf bank_mask:0xf
	v_add_f32_dpp v230, v230, v230 quad_perm:[2,3,0,1] row_mask:0xf bank_mask:0xf
	v_add_f32_dpp v231, v231, v231 quad_perm:[2,3,0,1] row_mask:0xf bank_mask:0xf
	s_nop 1
	v_add_f32_dpp v228, v228, v228 row_half_mirror row_mask:0xf bank_mask:0xf
	v_add_f32_dpp v229, v229, v229 row_half_mirror row_mask:0xf bank_mask:0xf
	v_add_f32_dpp v230, v230, v230 row_half_mirror row_mask:0xf bank_mask:0xf
	v_add_f32_dpp v231, v231, v231 row_half_mirror row_mask:0xf bank_mask:0xf
	s_nop 1
	v_add_f32_dpp v228, v228, v228 row_mirror row_mask:0xf bank_mask:0xf
	v_add_f32_dpp v229, v229, v229 row_mirror row_mask:0xf bank_mask:0xf
	v_add_f32_dpp v230, v230, v230 row_mirror row_mask:0xf bank_mask:0xf
	v_add_f32_dpp v231, v231, v231 row_mirror row_mask:0xf bank_mask:0xf
	v_fma_f32 v228, v228, s25, v218
	v_fma_f32 v229, v229, s25, v218
	v_fma_f32 v230, v230, s25, v218
	v_fma_f32 v231, v231, s25, v218
	v_rsq_f32_e32 v228, v228
	v_rsq_f32_e32 v229, v229
	v_rsq_f32_e32 v230, v230
	v_rsq_f32_e32 v231, v231
	s_waitcnt vmcnt(0)
	v_lshlrev_b32_e32 v236, 16, v178
	v_mul_f32_e32 v236, v228, v236
	v_mul_f32_e32 v236, v104, v236
	v_cvt_pk_bf16_f32 v237, v236, v236
	global_store_short v232, v237, s[46:47] offset:0
	v_and_b32_e32 v236, 0xffff0000, v178
	v_mul_f32_e32 v236, v229, v236
	v_mul_f32_e32 v236, v104, v236
	v_cvt_pk_bf16_f32 v238, v236, v236
	global_store_short v232, v238, s[46:47] offset:2048
	v_lshlrev_b32_e32 v236, 16, v179
	v_mul_f32_e32 v236, v230, v236
	v_mul_f32_e32 v236, v104, v236
	v_cvt_pk_bf16_f32 v239, v236, v236
	global_store_short v233, v239, s[46:47] offset:0
	v_and_b32_e32 v236, 0xffff0000, v179
	v_mul_f32_e32 v236, v231, v236
	v_mul_f32_e32 v236, v104, v236
	v_cvt_pk_bf16_f32 v240, v236, v236
	global_store_short v233, v240, s[46:47] offset:2048
	v_lshlrev_b32_e32 v236, 16, v180
	v_mul_f32_e32 v236, v228, v236
	v_mul_f32_e32 v236, v105, v236
	v_cvt_pk_bf16_f32 v237, v236, v236
	global_store_short v232, v237, s[46:47] offset:32
	v_and_b32_e32 v236, 0xffff0000, v180
	v_mul_f32_e32 v236, v229, v236
	v_mul_f32_e32 v236, v105, v236
	v_cvt_pk_bf16_f32 v238, v236, v236
	global_store_short v232, v238, s[46:47] offset:2080
	v_lshlrev_b32_e32 v236, 16, v181
	v_mul_f32_e32 v236, v230, v236
	v_mul_f32_e32 v236, v105, v236
	v_cvt_pk_bf16_f32 v239, v236, v236
	global_store_short v233, v239, s[46:47] offset:32
	v_and_b32_e32 v236, 0xffff0000, v181
	v_mul_f32_e32 v236, v231, v236
	v_mul_f32_e32 v236, v105, v236
	v_cvt_pk_bf16_f32 v240, v236, v236
	global_store_short v233, v240, s[46:47] offset:2080
	v_lshlrev_b32_e32 v236, 16, v182
	v_mul_f32_e32 v236, v228, v236
	v_mul_f32_e32 v236, v106, v236
	v_cvt_pk_bf16_f32 v237, v236, v236
	global_store_short v232, v237, s[46:47] offset:64
	v_and_b32_e32 v236, 0xffff0000, v182
	v_mul_f32_e32 v236, v229, v236
	v_mul_f32_e32 v236, v106, v236
	v_cvt_pk_bf16_f32 v238, v236, v236
	global_store_short v232, v238, s[46:47] offset:2112
	v_lshlrev_b32_e32 v236, 16, v183
	v_mul_f32_e32 v236, v230, v236
	v_mul_f32_e32 v236, v106, v236
	v_cvt_pk_bf16_f32 v239, v236, v236
	global_store_short v233, v239, s[46:47] offset:64
	v_and_b32_e32 v236, 0xffff0000, v183
	v_mul_f32_e32 v236, v231, v236
	v_mul_f32_e32 v236, v106, v236
	v_cvt_pk_bf16_f32 v240, v236, v236
	global_store_short v233, v240, s[46:47] offset:2112
	v_lshlrev_b32_e32 v236, 16, v184
	v_mul_f32_e32 v236, v228, v236
	v_mul_f32_e32 v236, v107, v236
	v_cvt_pk_bf16_f32 v237, v236, v236
	global_store_short v232, v237, s[46:47] offset:96
	v_and_b32_e32 v236, 0xffff0000, v184
	v_mul_f32_e32 v236, v229, v236
	v_mul_f32_e32 v236, v107, v236
	v_cvt_pk_bf16_f32 v238, v236, v236
	global_store_short v232, v238, s[46:47] offset:2144
	v_lshlrev_b32_e32 v236, 16, v185
	v_mul_f32_e32 v236, v230, v236
	v_mul_f32_e32 v236, v107, v236
	v_cvt_pk_bf16_f32 v239, v236, v236
	global_store_short v233, v239, s[46:47] offset:96
	v_and_b32_e32 v236, 0xffff0000, v185
	v_mul_f32_e32 v236, v231, v236
	v_mul_f32_e32 v236, v107, v236
	v_cvt_pk_bf16_f32 v240, v236, v236
	global_store_short v233, v240, s[46:47] offset:2144
	v_lshlrev_b32_e32 v236, 16, v186
	v_mul_f32_e32 v236, v228, v236
	v_mul_f32_e32 v236, v108, v236
	v_cvt_pk_bf16_f32 v237, v236, v236
	global_store_short v232, v237, s[46:47] offset:128
	v_and_b32_e32 v236, 0xffff0000, v186
	v_mul_f32_e32 v236, v229, v236
	v_mul_f32_e32 v236, v108, v236
	v_cvt_pk_bf16_f32 v238, v236, v236
	global_store_short v232, v238, s[46:47] offset:2176
	v_lshlrev_b32_e32 v236, 16, v187
	v_mul_f32_e32 v236, v230, v236
	v_mul_f32_e32 v236, v108, v236
	v_cvt_pk_bf16_f32 v239, v236, v236
	global_store_short v233, v239, s[46:47] offset:128
	v_and_b32_e32 v236, 0xffff0000, v187
	v_mul_f32_e32 v236, v231, v236
	v_mul_f32_e32 v236, v108, v236
	v_cvt_pk_bf16_f32 v240, v236, v236
	global_store_short v233, v240, s[46:47] offset:2176
	v_lshlrev_b32_e32 v236, 16, v188
	v_mul_f32_e32 v236, v228, v236
	v_mul_f32_e32 v236, v109, v236
	v_cvt_pk_bf16_f32 v237, v236, v236
	global_store_short v232, v237, s[46:47] offset:160
	v_and_b32_e32 v236, 0xffff0000, v188
	v_mul_f32_e32 v236, v229, v236
	v_mul_f32_e32 v236, v109, v236
	v_cvt_pk_bf16_f32 v238, v236, v236
	global_store_short v232, v238, s[46:47] offset:2208
	v_lshlrev_b32_e32 v236, 16, v189
	v_mul_f32_e32 v236, v230, v236
	v_mul_f32_e32 v236, v109, v236
	v_cvt_pk_bf16_f32 v239, v236, v236
	global_store_short v233, v239, s[46:47] offset:160
	v_and_b32_e32 v236, 0xffff0000, v189
	v_mul_f32_e32 v236, v231, v236
	v_mul_f32_e32 v236, v109, v236
	v_cvt_pk_bf16_f32 v240, v236, v236
	global_store_short v233, v240, s[46:47] offset:2208
	v_lshlrev_b32_e32 v236, 16, v190
	v_mul_f32_e32 v236, v228, v236
	v_mul_f32_e32 v236, v110, v236
	v_cvt_pk_bf16_f32 v237, v236, v236
	global_store_short v232, v237, s[46:47] offset:192
	v_and_b32_e32 v236, 0xffff0000, v190
	v_mul_f32_e32 v236, v229, v236
	v_mul_f32_e32 v236, v110, v236
	v_cvt_pk_bf16_f32 v238, v236, v236
	global_store_short v232, v238, s[46:47] offset:2240
	v_lshlrev_b32_e32 v236, 16, v191
	v_mul_f32_e32 v236, v230, v236
	v_mul_f32_e32 v236, v110, v236
	v_cvt_pk_bf16_f32 v239, v236, v236
	global_store_short v233, v239, s[46:47] offset:192
	v_and_b32_e32 v236, 0xffff0000, v191
	v_mul_f32_e32 v236, v231, v236
	v_mul_f32_e32 v236, v110, v236
	v_cvt_pk_bf16_f32 v240, v236, v236
	global_store_short v233, v240, s[46:47] offset:2240
	v_lshlrev_b32_e32 v236, 16, v192
	v_mul_f32_e32 v236, v228, v236
	v_mul_f32_e32 v236, v111, v236
	v_cvt_pk_bf16_f32 v237, v236, v236
	global_store_short v232, v237, s[46:47] offset:224
	v_and_b32_e32 v236, 0xffff0000, v192
	v_mul_f32_e32 v236, v229, v236
	v_mul_f32_e32 v236, v111, v236
	v_cvt_pk_bf16_f32 v238, v236, v236
	global_store_short v232, v238, s[46:47] offset:2272
	v_lshlrev_b32_e32 v236, 16, v193
	v_mul_f32_e32 v236, v230, v236
	v_mul_f32_e32 v236, v111, v236
	v_cvt_pk_bf16_f32 v239, v236, v236
	global_store_short v233, v239, s[46:47] offset:224
	v_and_b32_e32 v236, 0xffff0000, v193
	v_mul_f32_e32 v236, v231, v236
	v_mul_f32_e32 v236, v111, v236
	v_cvt_pk_bf16_f32 v240, v236, v236
	global_store_short v233, v240, s[46:47] offset:2272
	v_lshlrev_b32_e32 v236, 16, v204
	v_mul_f32_e32 v236, v228, v236
	v_mul_f32_e32 v236, v112, v236
	v_cvt_pk_bf16_f32 v237, v236, v236
	global_store_short v232, v237, s[46:47] offset:256
	v_and_b32_e32 v236, 0xffff0000, v204
	v_mul_f32_e32 v236, v229, v236
	v_mul_f32_e32 v236, v112, v236
	v_cvt_pk_bf16_f32 v238, v236, v236
	global_store_short v232, v238, s[46:47] offset:2304
	v_lshlrev_b32_e32 v236, 16, v205
	v_mul_f32_e32 v236, v230, v236
	v_mul_f32_e32 v236, v112, v236
	v_cvt_pk_bf16_f32 v239, v236, v236
	global_store_short v233, v239, s[46:47] offset:256
	v_and_b32_e32 v236, 0xffff0000, v205
	v_mul_f32_e32 v236, v231, v236
	v_mul_f32_e32 v236, v112, v236
	v_cvt_pk_bf16_f32 v240, v236, v236
	global_store_short v233, v240, s[46:47] offset:2304
	v_lshlrev_b32_e32 v236, 16, v206
	v_mul_f32_e32 v236, v228, v236
	v_mul_f32_e32 v236, v113, v236
	v_cvt_pk_bf16_f32 v237, v236, v236
	global_store_short v232, v237, s[46:47] offset:288
	v_and_b32_e32 v236, 0xffff0000, v206
	v_mul_f32_e32 v236, v229, v236
	v_mul_f32_e32 v236, v113, v236
	v_cvt_pk_bf16_f32 v238, v236, v236
	global_store_short v232, v238, s[46:47] offset:2336
	v_lshlrev_b32_e32 v236, 16, v207
	v_mul_f32_e32 v236, v230, v236
	v_mul_f32_e32 v236, v113, v236
	v_cvt_pk_bf16_f32 v239, v236, v236
	global_store_short v233, v239, s[46:47] offset:288
	v_and_b32_e32 v236, 0xffff0000, v207
	v_mul_f32_e32 v236, v231, v236
	v_mul_f32_e32 v236, v113, v236
	v_cvt_pk_bf16_f32 v240, v236, v236
	global_store_short v233, v240, s[46:47] offset:2336
	v_lshlrev_b32_e32 v236, 16, v208
	v_mul_f32_e32 v236, v228, v236
	v_mul_f32_e32 v236, v114, v236
	v_cvt_pk_bf16_f32 v237, v236, v236
	global_store_short v232, v237, s[46:47] offset:320
	v_and_b32_e32 v236, 0xffff0000, v208
	v_mul_f32_e32 v236, v229, v236
	v_mul_f32_e32 v236, v114, v236
	v_cvt_pk_bf16_f32 v238, v236, v236
	global_store_short v232, v238, s[46:47] offset:2368
	v_lshlrev_b32_e32 v236, 16, v209
	v_mul_f32_e32 v236, v230, v236
	v_mul_f32_e32 v236, v114, v236
	v_cvt_pk_bf16_f32 v239, v236, v236
	global_store_short v233, v239, s[46:47] offset:320
	v_and_b32_e32 v236, 0xffff0000, v209
	v_mul_f32_e32 v236, v231, v236
	v_mul_f32_e32 v236, v114, v236
	v_cvt_pk_bf16_f32 v240, v236, v236
	global_store_short v233, v240, s[46:47] offset:2368
	v_lshlrev_b32_e32 v236, 16, v210
	v_mul_f32_e32 v236, v228, v236
	v_mul_f32_e32 v236, v115, v236
	v_cvt_pk_bf16_f32 v237, v236, v236
	global_store_short v232, v237, s[46:47] offset:352
	v_and_b32_e32 v236, 0xffff0000, v210
	v_mul_f32_e32 v236, v229, v236
	v_mul_f32_e32 v236, v115, v236
	v_cvt_pk_bf16_f32 v238, v236, v236
	global_store_short v232, v238, s[46:47] offset:2400
	v_lshlrev_b32_e32 v236, 16, v211
	v_mul_f32_e32 v236, v230, v236
	v_mul_f32_e32 v236, v115, v236
	v_cvt_pk_bf16_f32 v239, v236, v236
	global_store_short v233, v239, s[46:47] offset:352
	v_and_b32_e32 v236, 0xffff0000, v211
	v_mul_f32_e32 v236, v231, v236
	v_mul_f32_e32 v236, v115, v236
	v_cvt_pk_bf16_f32 v240, v236, v236
	global_store_short v233, v240, s[46:47] offset:2400
	v_lshlrev_b32_e32 v236, 16, v212
	v_mul_f32_e32 v236, v228, v236
	v_mul_f32_e32 v236, v116, v236
	v_cvt_pk_bf16_f32 v237, v236, v236
	global_store_short v232, v237, s[46:47] offset:384
	v_and_b32_e32 v236, 0xffff0000, v212
	v_mul_f32_e32 v236, v229, v236
	v_mul_f32_e32 v236, v116, v236
	v_cvt_pk_bf16_f32 v238, v236, v236
	global_store_short v232, v238, s[46:47] offset:2432
	v_lshlrev_b32_e32 v236, 16, v213
	v_mul_f32_e32 v236, v230, v236
	v_mul_f32_e32 v236, v116, v236
	v_cvt_pk_bf16_f32 v239, v236, v236
	global_store_short v233, v239, s[46:47] offset:384
	v_and_b32_e32 v236, 0xffff0000, v213
	v_mul_f32_e32 v236, v231, v236
	v_mul_f32_e32 v236, v116, v236
	v_cvt_pk_bf16_f32 v240, v236, v236
	global_store_short v233, v240, s[46:47] offset:2432
	v_lshlrev_b32_e32 v236, 16, v214
	v_mul_f32_e32 v236, v228, v236
	v_mul_f32_e32 v236, v117, v236
	v_cvt_pk_bf16_f32 v237, v236, v236
	global_store_short v232, v237, s[46:47] offset:416
	v_and_b32_e32 v236, 0xffff0000, v214
	v_mul_f32_e32 v236, v229, v236
	v_mul_f32_e32 v236, v117, v236
	v_cvt_pk_bf16_f32 v238, v236, v236
	global_store_short v232, v238, s[46:47] offset:2464
	v_lshlrev_b32_e32 v236, 16, v215
	v_mul_f32_e32 v236, v230, v236
	v_mul_f32_e32 v236, v117, v236
	v_cvt_pk_bf16_f32 v239, v236, v236
	global_store_short v233, v239, s[46:47] offset:416
	v_and_b32_e32 v236, 0xffff0000, v215
	v_mul_f32_e32 v236, v231, v236
	v_mul_f32_e32 v236, v117, v236
	v_cvt_pk_bf16_f32 v240, v236, v236
	global_store_short v233, v240, s[46:47] offset:2464
	v_lshlrev_b32_e32 v236, 16, v216
	v_mul_f32_e32 v236, v228, v236
	v_mul_f32_e32 v236, v118, v236
	v_cvt_pk_bf16_f32 v237, v236, v236
	global_store_short v232, v237, s[46:47] offset:448
	v_and_b32_e32 v236, 0xffff0000, v216
	v_mul_f32_e32 v236, v229, v236
	v_mul_f32_e32 v236, v118, v236
	v_cvt_pk_bf16_f32 v238, v236, v236
	global_store_short v232, v238, s[46:47] offset:2496
	v_lshlrev_b32_e32 v236, 16, v217
	v_mul_f32_e32 v236, v230, v236
	v_mul_f32_e32 v236, v118, v236
	v_cvt_pk_bf16_f32 v239, v236, v236
	global_store_short v233, v239, s[46:47] offset:448
	v_and_b32_e32 v236, 0xffff0000, v217
	v_mul_f32_e32 v236, v231, v236
	v_mul_f32_e32 v236, v118, v236
	v_cvt_pk_bf16_f32 v240, v236, v236
	global_store_short v233, v240, s[46:47] offset:2496
	v_lshlrev_b32_e32 v236, 16, v224
	v_mul_f32_e32 v236, v228, v236
	v_mul_f32_e32 v236, v119, v236
	v_cvt_pk_bf16_f32 v237, v236, v236
	global_store_short v232, v237, s[46:47] offset:480
	v_and_b32_e32 v236, 0xffff0000, v224
	v_mul_f32_e32 v236, v229, v236
	v_mul_f32_e32 v236, v119, v236
	v_cvt_pk_bf16_f32 v238, v236, v236
	global_store_short v232, v238, s[46:47] offset:2528
	v_lshlrev_b32_e32 v236, 16, v225
	v_mul_f32_e32 v236, v230, v236
	v_mul_f32_e32 v236, v119, v236
	v_cvt_pk_bf16_f32 v239, v236, v236
	global_store_short v233, v239, s[46:47] offset:480
	v_and_b32_e32 v236, 0xffff0000, v225
	v_mul_f32_e32 v236, v231, v236
	v_mul_f32_e32 v236, v119, v236
	v_cvt_pk_bf16_f32 v240, v236, v236
	global_store_short v233, v240, s[46:47] offset:2528
.Ls3_end:
	s_waitcnt vmcnt(0) lgkmcnt(0)
	s_barrier
	s_branch .LBB0_106
